# v42 = v37 + prep_rwkv token-shift loop: the two mu_prev/mu_next parameter load groups of each half issued together with the P-row loads (one wait instead of three)
# speedup vs baseline: 1.0141x; 1.0141x over previous
.LBB0_423:
	v_add_u32_e32 v4, s25, v135
	v_mul_hi_i32 v2, v4, s64
	v_lshrrev_b32_e32 v3, 31, v2
	v_ashrrev_i32_e32 v2, 3, v2
	v_add_u32_e32 v5, v2, v3
	v_mad_u64_u32 v[20:21], s[0:1], v5, s66, v[0:1]
	v_add_u32_e32 v6, s18, v5
	v_mov_b64_e32 v[2:3], s[52:53]
	v_add_u32_e32 v8, s27, v5
	v_mad_i64_i32 v[6:7], s[0:1], v6, s34, v[2:3]
	v_ashrrev_i32_e32 v21, 31, v20
	v_mad_u64_u32 v[18:19], s[0:1], v5, s65, v[4:5]
	v_lshl_add_u64 v[6:7], v[20:21], 1, v[6:7]
	v_cmp_lt_i32_e32 vcc, s12, v8
	v_lshl_add_u64 v[14:15], v[6:7], 0, s[22:23]
	v_add_co_u32_e64 v6, s[0:1], s67, v6
	v_cndmask_b32_e64 v11, 0, -1, vcc
	v_cndmask_b32_e32 v10, 0, v132, vcc
	v_cmp_gt_i32_e64 s[6:7], s24, v8
	v_addc_co_u32_e64 v7, s[0:1], 0, v7, s[0:1]
	v_lshl_add_u64 v[10:11], v[14:15], 0, v[10:11]
	global_load_dwordx4 v[6:9], v[6:7], off offset:1792
	v_cndmask_b32_e64 v64, 0, v133, s[6:7]
	global_load_dwordx4 v[10:13], v[10:11], off
	v_lshl_add_u64 v[14:15], v[14:15], 0, v[64:65]
	global_load_dwordx4 v[14:17], v[14:15], off
	v_lshlrev_b64 v[208:209], 2, v[20:21]
	v_lshl_add_u64 v[210:211], s[10:11], 0, v[208:209]
	v_lshl_add_u64 v[212:213], s[8:9], 0, v[208:209]
	global_load_dwordx4 v[216:219], v[210:211], off offset:3072
	global_load_dwordx4 v[220:223], v[212:213], off offset:3072
	global_load_dwordx4 v[224:227], v[210:211], off offset:3088
	global_load_dwordx4 v[228:231], v[212:213], off offset:3088
	v_cmp_gt_i32_e64 s[4:5], 32, v18
	v_cmp_gt_i32_e64 s[0:1], 16, v18
	v_lshl_add_u32 v5, v5, 4, v1
	v_add_u32_e32 v4, 0x100, v4
	s_addk_i32 s25, 0x200
	s_cmpk_eq_i32 s25, 0x600
	s_waitcnt vmcnt(0) lgkmcnt(0)
	v_lshlrev_b32_e32 v31, 16, v7
	v_and_b32_e32 v7, 0xffff0000, v7
	v_lshlrev_b32_e32 v26, 16, v12
	v_and_b32_e32 v27, 0xffff0000, v12
	v_lshlrev_b32_e32 v29, 16, v13
	v_and_b32_e32 v30, 0xffff0000, v13
	v_lshlrev_b64 v[12:13], 2, v[20:21]
	v_and_b32_e32 v19, 0xffff0000, v10
	v_lshlrev_b32_e32 v25, 16, v11
	v_and_b32_e32 v11, 0xffff0000, v11
	v_lshl_add_u64 v[20:21], s[10:11], 0, v[12:13]
	v_lshlrev_b32_e32 v10, 16, v10
	v_lshlrev_b32_e32 v32, 16, v14
	v_lshlrev_b32_e32 v33, 16, v15
	v_and_b32_e32 v36, 0xffff0000, v15
	v_and_b32_e32 v37, 0xffff0000, v14
	v_lshlrev_b32_e32 v38, 16, v16
	v_lshlrev_b32_e32 v39, 16, v17
	v_and_b32_e32 v40, 0xffff0000, v17
	v_and_b32_e32 v41, 0xffff0000, v16
	v_lshl_add_u64 v[22:23], s[8:9], 0, v[12:13]
	v_cndmask_b32_e32 v18, 0, v10, vcc
	v_cndmask_b32_e32 v24, 0, v19, vcc
	v_cndmask_b32_e32 v19, 0, v25, vcc
	v_cndmask_b32_e32 v25, 0, v11, vcc
	v_cndmask_b32_e32 v28, 0, v27, vcc
	v_cndmask_b32_e32 v27, 0, v29, vcc
	v_cndmask_b32_e32 v29, 0, v30, vcc
	v_lshlrev_b32_e32 v30, 16, v6
	v_cndmask_b32_e64 v33, 0, v33, s[6:7]
	v_cndmask_b32_e64 v32, 0, v32, s[6:7]
	v_pk_add_f32 v[18:19], v[18:19], v[30:31] neg_lo:[0,1] neg_hi:[0,1]
	v_and_b32_e32 v6, 0xffff0000, v6
	v_pk_add_f32 v[24:25], v[24:25], v[6:7] neg_lo:[0,1] neg_hi:[0,1]
	v_cndmask_b32_e32 v26, 0, v26, vcc
	s_waitcnt vmcnt(0) lgkmcnt(0)
	v_mov_b64_e32 v[10:11], v[216:217]
	v_mov_b64_e32 v[12:13], v[218:219]
	v_mov_b64_e32 v[14:15], v[220:221]
	v_mov_b64_e32 v[16:17], v[222:223]
	v_mov_b32_e32 v34, v10
	v_mov_b32_e32 v35, v12
	v_pk_fma_f32 v[18:19], v[34:35], v[18:19], v[30:31]
	v_pk_add_f32 v[30:31], v[32:33], v[30:31] neg_lo:[0,1] neg_hi:[0,1]
	v_mov_b32_e32 v32, v14
	v_mov_b32_e32 v33, v16
	v_pk_fma_f32 v[18:19], v[30:31], v[32:33], v[18:19]
	v_cndmask_b32_e64 v31, 0, v36, s[6:7]
	v_cndmask_b32_e64 v30, 0, v37, s[6:7]
	v_mov_b32_e32 v12, v11
	v_pk_fma_f32 v[12:13], v[12:13], v[24:25], v[6:7]
	v_pk_add_f32 v[6:7], v[30:31], v[6:7] neg_lo:[0,1] neg_hi:[0,1]
	v_mov_b32_e32 v16, v15
	v_pk_fma_f32 v[6:7], v[6:7], v[16:17], v[12:13]
	v_add_f32_e32 v10, v18, v18
	v_add_f32_e32 v11, v6, v6
	v_cndmask_b32_e64 v11, v11, v6, s[0:1]
	v_mul_f32_e32 v11, 0xbfb8aa3b, v11
	v_exp_f32_e32 v12, v11
	v_add_f32_e32 v11, v19, v19
	v_cndmask_b32_e64 v10, v10, v18, s[0:1]
	v_cndmask_b32_e64 v11, v11, v19, s[0:1]
	v_mul_f32_e32 v10, 0xbfb8aa3b, v10
	v_mul_f32_e32 v11, 0xbfb8aa3b, v11
	v_exp_f32_e32 v10, v10
	v_exp_f32_e32 v11, v11
	s_nop 0
	v_pk_add_f32 v[10:11], v[10:11], 1.0 op_sel_hi:[1,0]
	s_nop 0
	v_div_scale_f32 v13, s[78:79], v11, v11, 1.0
	v_rcp_f32_e32 v14, v13
	s_nop 0
	v_fma_f32 v15, -v13, v14, 1.0
	v_fmac_f32_e32 v14, v15, v14
	v_div_scale_f32 v15, vcc, 1.0, v11, 1.0
	v_mul_f32_e32 v16, v15, v14
	v_fma_f32 v17, -v13, v16, v15
	v_fmac_f32_e32 v16, v17, v14
	v_fma_f32 v13, -v13, v16, v15
	v_div_fmas_f32 v13, v13, v14, v16
	v_div_fixup_f32 v11, v13, v11, 1.0
	v_div_scale_f32 v13, s[78:79], v10, v10, 1.0
	v_rcp_f32_e32 v14, v13
	s_nop 0
	v_fma_f32 v15, -v13, v14, 1.0
	v_fmac_f32_e32 v14, v15, v14
	v_div_scale_f32 v15, vcc, 1.0, v10, 1.0
	v_mul_f32_e32 v16, v15, v14
	v_fma_f32 v17, -v13, v16, v15
	v_fmac_f32_e32 v16, v17, v14
	v_fma_f32 v13, -v13, v16, v15
	v_div_fmas_f32 v13, v13, v14, v16
	v_div_fixup_f32 v10, v13, v10, 1.0
	v_pk_fma_f32 v[14:15], v[10:11], 2.0, -1.0 op_sel_hi:[1,0,0]
	v_and_b32_e32 v17, 0xffff0000, v9
	v_cndmask_b32_e64 v13, v18, v14, s[4:5]
	v_cndmask_b32_e64 v25, v13, v10, s[0:1]
	v_add_f32_e32 v10, v7, v7
	v_cndmask_b32_e64 v10, v10, v7, s[0:1]
	v_mul_f32_e32 v10, 0xbfb8aa3b, v10
	v_exp_f32_e32 v13, v10
	v_cndmask_b32_e64 v14, v19, v15, s[4:5]
	v_cndmask_b32_e64 v24, v14, v11, s[0:1]
	v_cndmask_b32_e64 v19, 0, v39, s[6:7]
	v_pk_add_f32 v[10:11], v[12:13], 1.0 op_sel_hi:[1,0]
	v_cndmask_b32_e64 v18, 0, v38, s[6:7]
	v_div_scale_f32 v12, s[78:79], v11, v11, 1.0
	v_rcp_f32_e32 v13, v12
	s_nop 0
	v_fma_f32 v14, -v12, v13, 1.0
	v_fmac_f32_e32 v13, v14, v13
	v_div_scale_f32 v14, vcc, 1.0, v11, 1.0
	v_mul_f32_e32 v15, v14, v13
	v_fma_f32 v16, -v12, v15, v14
	v_fmac_f32_e32 v15, v16, v13
	v_fma_f32 v12, -v12, v15, v14
	v_div_fmas_f32 v12, v12, v13, v15
	v_div_fixup_f32 v11, v12, v11, 1.0
	v_div_scale_f32 v12, s[78:79], v10, v10, 1.0
	v_rcp_f32_e32 v13, v12
	s_nop 0
	v_fma_f32 v14, -v12, v13, 1.0
	v_fmac_f32_e32 v13, v14, v13
	v_div_scale_f32 v14, vcc, 1.0, v10, 1.0
	v_mul_f32_e32 v15, v14, v13
	v_fma_f32 v16, -v12, v15, v14
	v_fmac_f32_e32 v15, v16, v13
	v_fma_f32 v12, -v12, v15, v14
	v_div_fmas_f32 v12, v12, v13, v15
	v_div_fixup_f32 v10, v12, v10, 1.0
	v_pk_fma_f32 v[12:13], v[10:11], 2.0, -1.0 op_sel_hi:[1,0,0]
	v_lshlrev_b32_e32 v15, 16, v9
	v_cndmask_b32_e64 v7, v7, v13, s[4:5]
	v_cndmask_b32_e64 v6, v6, v12, s[4:5]
	v_cndmask_b32_e64 v30, v6, v10, s[0:1]
	v_cndmask_b32_e64 v31, v7, v11, s[0:1]
	v_lshlrev_b32_e32 v14, 16, v8
	v_and_b32_e32 v16, 0xffff0000, v8
	v_pk_add_f32 v[20:21], v[26:27], v[14:15] neg_lo:[0,1] neg_hi:[0,1]
	s_waitcnt vmcnt(0) lgkmcnt(0)
	v_mov_b64_e32 v[6:7], v[224:225]
	v_mov_b64_e32 v[8:9], v[226:227]
	v_mov_b64_e32 v[10:11], v[228:229]
	v_mov_b64_e32 v[12:13], v[230:231]
	v_mov_b32_e32 v22, v6
	v_mov_b32_e32 v23, v8
	v_pk_fma_f32 v[20:21], v[20:21], v[22:23], v[14:15]
	v_pk_add_f32 v[14:15], v[18:19], v[14:15] neg_lo:[0,1] neg_hi:[0,1]
	v_mov_b32_e32 v18, v10
	v_mov_b32_e32 v19, v12
	v_pk_fma_f32 v[14:15], v[14:15], v[18:19], v[20:21]
	v_cndmask_b32_e64 v19, 0, v40, s[6:7]
	v_cndmask_b32_e64 v18, 0, v41, s[6:7]
	v_pk_add_f32 v[20:21], v[28:29], v[16:17] neg_lo:[0,1] neg_hi:[0,1]
	v_mov_b32_e32 v8, v7
	v_pk_fma_f32 v[8:9], v[20:21], v[8:9], v[16:17]
	v_pk_add_f32 v[16:17], v[18:19], v[16:17] neg_lo:[0,1] neg_hi:[0,1]
	v_mov_b32_e32 v12, v11
	v_pk_fma_f32 v[8:9], v[16:17], v[12:13], v[8:9]
	v_add_f32_e32 v6, v14, v14
	v_add_f32_e32 v7, v8, v8
	v_cndmask_b32_e64 v7, v7, v8, s[0:1]
	v_mul_f32_e32 v7, 0xbfb8aa3b, v7
	v_exp_f32_e32 v10, v7
	v_add_f32_e32 v7, v15, v15
	v_cndmask_b32_e64 v6, v6, v14, s[0:1]
	v_cndmask_b32_e64 v7, v7, v15, s[0:1]
	v_mul_f32_e32 v6, 0xbfb8aa3b, v6
	v_mul_f32_e32 v7, 0xbfb8aa3b, v7
	v_exp_f32_e32 v6, v6
	v_exp_f32_e32 v7, v7
	s_nop 0
	v_pk_add_f32 v[6:7], v[6:7], 1.0 op_sel_hi:[1,0]
	s_nop 0
	v_div_scale_f32 v11, s[6:7], v7, v7, 1.0
	v_rcp_f32_e32 v12, v11
	s_nop 0
	v_fma_f32 v13, -v11, v12, 1.0
	v_fmac_f32_e32 v12, v13, v12
	v_div_scale_f32 v13, vcc, 1.0, v7, 1.0
	v_mul_f32_e32 v16, v13, v12
	v_fma_f32 v17, -v11, v16, v13
	v_fmac_f32_e32 v16, v17, v12
	v_fma_f32 v11, -v11, v16, v13
	v_div_fmas_f32 v11, v11, v12, v16
	v_div_fixup_f32 v7, v11, v7, 1.0
	v_div_scale_f32 v11, s[6:7], v6, v6, 1.0
	v_rcp_f32_e32 v12, v11
	s_nop 0
	v_fma_f32 v13, -v11, v12, 1.0
	v_fmac_f32_e32 v12, v13, v12
	v_div_scale_f32 v13, vcc, 1.0, v6, 1.0
	v_mul_f32_e32 v16, v13, v12
	v_fma_f32 v17, -v11, v16, v13
	v_fmac_f32_e32 v16, v17, v12
	v_fma_f32 v11, -v11, v16, v13
	v_div_fmas_f32 v11, v11, v12, v16
	v_div_fixup_f32 v6, v11, v6, 1.0
	v_pk_fma_f32 v[12:13], v[6:7], 2.0, -1.0 op_sel_hi:[1,0,0]
	s_nop 0
	v_cndmask_b32_e64 v11, v14, v12, s[4:5]
	v_cndmask_b32_e64 v12, v15, v13, s[4:5]
	v_cndmask_b32_e64 v13, v11, v6, s[0:1]
	v_add_f32_e32 v6, v9, v9
	v_cndmask_b32_e64 v6, v6, v9, s[0:1]
	v_mul_f32_e32 v6, 0xbfb8aa3b, v6
	v_exp_f32_e32 v11, v6
	v_cndmask_b32_e64 v12, v12, v7, s[0:1]
	v_pk_add_f32 v[6:7], v[10:11], 1.0 op_sel_hi:[1,0]
	s_nop 0
	v_div_scale_f32 v10, s[6:7], v7, v7, 1.0
	v_rcp_f32_e32 v11, v10
	s_nop 0
	v_fma_f32 v14, -v10, v11, 1.0
	v_fmac_f32_e32 v11, v14, v11
	v_div_scale_f32 v14, vcc, 1.0, v7, 1.0
	v_mul_f32_e32 v15, v14, v11
	v_fma_f32 v16, -v10, v15, v14
	v_fmac_f32_e32 v15, v16, v11
	v_fma_f32 v10, -v10, v15, v14
	v_div_fmas_f32 v10, v10, v11, v15
	v_div_fixup_f32 v7, v10, v7, 1.0
	v_div_scale_f32 v10, s[6:7], v6, v6, 1.0
	v_rcp_f32_e32 v11, v10
	s_nop 0
	v_fma_f32 v14, -v10, v11, 1.0
	v_fmac_f32_e32 v11, v14, v11
	v_div_scale_f32 v14, vcc, 1.0, v6, 1.0
	v_mul_f32_e32 v15, v14, v11
	v_fma_f32 v16, -v10, v15, v14
	v_fmac_f32_e32 v15, v16, v11
	v_fma_f32 v10, -v10, v15, v14
	v_div_fmas_f32 v10, v10, v11, v15
	v_div_fixup_f32 v6, v10, v6, 1.0
	v_pk_fma_f32 v[10:11], v[6:7], 2.0, -1.0 op_sel_hi:[1,0,0]
	v_bfe_u32 v14, v13, 16, 1
	v_cndmask_b32_e64 v9, v9, v11, s[4:5]
	v_cndmask_b32_e64 v8, v8, v10, s[4:5]
	v_cndmask_b32_e64 v6, v8, v6, s[0:1]
	v_cndmask_b32_e64 v7, v9, v7, s[0:1]
	v_bfe_u32 v8, v7, 16, 1
	v_bfe_u32 v9, v6, 16, 1
	v_add3_u32 v6, v6, v9, s58
	v_add3_u32 v7, v7, v8, s58
	v_bfe_u32 v8, v25, 16, 1
	v_bfe_u32 v9, v24, 16, 1
	v_bfe_u32 v15, v12, 16, 1
	v_bfe_u32 v10, v31, 16, 1
	v_bfe_u32 v11, v30, 16, 1
	v_add3_u32 v12, v12, v15, s58
	v_add3_u32 v13, v13, v14, s58
	v_add3_u32 v9, v24, v9, s58
	v_add3_u32 v8, v25, v8, s58
	v_add3_u32 v11, v30, v11, s58
	v_add3_u32 v10, v31, v10, s58
	v_lshrrev_b32_e32 v14, 16, v8
	v_lshrrev_b32_e32 v15, 16, v9
	v_lshrrev_b32_e32 v8, 16, v13
	v_lshrrev_b32_e32 v9, 16, v12
	v_and_or_b32 v9, v7, s54, v9
	v_and_or_b32 v8, v6, s54, v8
	v_and_or_b32 v7, v10, s54, v15
	v_and_or_b32 v6, v11, s54, v14
	ds_write_b128 v5, v[6:9]
	v_mul_hi_i32 v5, v4, s64
	v_lshrrev_b32_e32 v6, 31, v5
	v_ashrrev_i32_e32 v5, 3, v5
	v_add_u32_e32 v6, v5, v6
	v_mad_u64_u32 v[4:5], s[0:1], v6, s65, v[4:5]
	v_mul_lo_u32 v5, v6, s66
	s_movk_i32 s0, 0x800
	v_add3_u32 v20, v0, v5, s0
	v_add_u32_e32 v7, s18, v6
	v_mad_i64_i32 v[2:3], s[0:1], v7, s34, v[2:3]
	v_ashrrev_i32_e32 v21, 31, v20
	v_lshl_add_u64 v[2:3], v[20:21], 1, v[2:3]
	v_add_u32_e32 v5, s27, v6
	v_lshl_add_u64 v[16:17], v[2:3], 0, s[22:23]
	v_add_co_u32_e64 v2, s[0:1], s67, v2
	v_cmp_lt_i32_e32 vcc, s12, v5
	s_nop 0
	v_addc_co_u32_e64 v3, s[0:1], 0, v3, s[0:1]
	v_cmp_gt_i32_e64 s[6:7], s24, v5
	global_load_dwordx4 v[8:11], v[2:3], off offset:1792
	v_cndmask_b32_e64 v3, 0, -1, vcc
	v_cndmask_b32_e32 v2, 0, v132, vcc
	v_lshl_add_u64 v[2:3], v[16:17], 0, v[2:3]
	v_cndmask_b32_e64 v64, 0, v133, s[6:7]
	global_load_dwordx4 v[12:15], v[2:3], off
	v_lshl_add_u64 v[2:3], v[16:17], 0, v[64:65]
	global_load_dwordx4 v[16:19], v[2:3], off
	v_lshlrev_b64 v[208:209], 2, v[20:21]
	v_lshl_add_u64 v[210:211], s[10:11], 0, v[208:209]
	v_lshl_add_u64 v[212:213], s[8:9], 0, v[208:209]
	global_load_dwordx4 v[216:219], v[210:211], off offset:3072
	global_load_dwordx4 v[220:223], v[212:213], off offset:3072
	global_load_dwordx4 v[224:227], v[210:211], off offset:3088
	global_load_dwordx4 v[228:231], v[212:213], off offset:3088
	v_lshlrev_b64 v[2:3], 2, v[20:21]
	v_cmp_gt_i32_e64 s[4:5], 32, v4
	v_cmp_gt_i32_e64 s[0:1], 16, v4
	v_lshl_add_u32 v6, v6, 4, v1
	v_add_u32_e32 v1, 0x2000, v1
	v_add_u32_e32 v0, 0x1000, v0
	s_waitcnt vmcnt(0) lgkmcnt(0)
	v_lshlrev_b32_e32 v29, 16, v9
	v_lshlrev_b32_e32 v28, 16, v8
	v_and_b32_e32 v9, 0xffff0000, v9
	v_and_b32_e32 v8, 0xffff0000, v8
	v_and_b32_e32 v5, 0xffff0000, v12
	v_lshlrev_b32_e32 v7, 16, v13
	v_and_b32_e32 v13, 0xffff0000, v13
	v_lshlrev_b32_e32 v24, 16, v14
	v_and_b32_e32 v14, 0xffff0000, v14
	v_lshlrev_b32_e32 v25, 16, v15
	v_and_b32_e32 v15, 0xffff0000, v15
	v_lshlrev_b32_e32 v30, 16, v16
	v_lshlrev_b32_e32 v31, 16, v17
	v_and_b32_e32 v34, 0xffff0000, v17
	v_and_b32_e32 v35, 0xffff0000, v16
	v_lshlrev_b32_e32 v36, 16, v18
	v_lshlrev_b32_e32 v37, 16, v19
	v_and_b32_e32 v38, 0xffff0000, v19
	v_and_b32_e32 v39, 0xffff0000, v18
	v_lshl_add_u64 v[16:17], s[10:11], 0, v[2:3]
	v_lshl_add_u64 v[18:19], s[8:9], 0, v[2:3]
	v_lshlrev_b32_e32 v2, 16, v12
	v_cndmask_b32_e32 v20, 0, v2, vcc
	v_cndmask_b32_e32 v22, 0, v5, vcc
	v_cndmask_b32_e32 v23, 0, v13, vcc
	v_cndmask_b32_e32 v26, 0, v14, vcc
	v_cndmask_b32_e32 v27, 0, v15, vcc
	v_cndmask_b32_e32 v21, 0, v7, vcc
	v_cndmask_b32_e64 v31, 0, v31, s[6:7]
	v_cndmask_b32_e64 v30, 0, v30, s[6:7]
	v_pk_add_f32 v[20:21], v[20:21], v[28:29] neg_lo:[0,1] neg_hi:[0,1]
	v_pk_add_f32 v[22:23], v[22:23], v[8:9] neg_lo:[0,1] neg_hi:[0,1]
	v_cndmask_b32_e32 v24, 0, v24, vcc
	v_cndmask_b32_e32 v25, 0, v25, vcc
	s_waitcnt vmcnt(0) lgkmcnt(0)
	v_mov_b64_e32 v[2:3], v[216:217]
	v_mov_b64_e32 v[4:5], v[218:219]
	v_mov_b64_e32 v[12:13], v[220:221]
	v_mov_b64_e32 v[14:15], v[222:223]
	v_mov_b32_e32 v32, v2
	v_mov_b32_e32 v33, v4
	v_pk_fma_f32 v[20:21], v[32:33], v[20:21], v[28:29]
	v_pk_add_f32 v[28:29], v[30:31], v[28:29] neg_lo:[0,1] neg_hi:[0,1]
	v_mov_b32_e32 v30, v12
	v_mov_b32_e32 v31, v14
	v_pk_fma_f32 v[20:21], v[28:29], v[30:31], v[20:21]
	v_cndmask_b32_e64 v29, 0, v34, s[6:7]
	v_cndmask_b32_e64 v28, 0, v35, s[6:7]
	v_mov_b32_e32 v4, v3
	v_pk_fma_f32 v[4:5], v[4:5], v[22:23], v[8:9]
	v_pk_add_f32 v[8:9], v[28:29], v[8:9] neg_lo:[0,1] neg_hi:[0,1]
	v_mov_b32_e32 v14, v13
	v_pk_fma_f32 v[4:5], v[8:9], v[14:15], v[4:5]
	v_add_f32_e32 v2, v20, v20
	v_add_f32_e32 v3, v4, v4
	v_cndmask_b32_e64 v3, v3, v4, s[0:1]
	v_mul_f32_e32 v3, 0xbfb8aa3b, v3
	v_exp_f32_e32 v8, v3
	v_add_f32_e32 v3, v21, v21
	v_cndmask_b32_e64 v2, v2, v20, s[0:1]
	v_cndmask_b32_e64 v3, v3, v21, s[0:1]
	v_mul_f32_e32 v2, 0xbfb8aa3b, v2
	v_mul_f32_e32 v3, 0xbfb8aa3b, v3
	v_exp_f32_e32 v2, v2
	v_exp_f32_e32 v3, v3
	v_and_b32_e32 v15, 0xffff0000, v11
	v_pk_add_f32 v[2:3], v[2:3], 1.0 op_sel_hi:[1,0]
	s_nop 0
	v_div_scale_f32 v7, s[78:79], v3, v3, 1.0
	v_rcp_f32_e32 v9, v7
	s_nop 0
	v_fma_f32 v12, -v7, v9, 1.0
	v_fmac_f32_e32 v9, v12, v9
	v_div_scale_f32 v12, vcc, 1.0, v3, 1.0
	v_mul_f32_e32 v13, v12, v9
	v_fma_f32 v14, -v7, v13, v12
	v_fmac_f32_e32 v13, v14, v9
	v_fma_f32 v7, -v7, v13, v12
	v_div_fmas_f32 v7, v7, v9, v13
	v_div_fixup_f32 v3, v7, v3, 1.0
	v_div_scale_f32 v7, s[78:79], v2, v2, 1.0
	v_rcp_f32_e32 v9, v7
	s_nop 0
	v_fma_f32 v12, -v7, v9, 1.0
	v_fmac_f32_e32 v9, v12, v9
	v_div_scale_f32 v12, vcc, 1.0, v2, 1.0
	v_mul_f32_e32 v13, v12, v9
	v_fma_f32 v14, -v7, v13, v12
	v_fmac_f32_e32 v13, v14, v9
	v_fma_f32 v7, -v7, v13, v12
	v_div_fmas_f32 v7, v7, v9, v13
	v_div_fixup_f32 v2, v7, v2, 1.0
	v_pk_fma_f32 v[12:13], v[2:3], 2.0, -1.0 op_sel_hi:[1,0,0]
	s_nop 0
	v_cndmask_b32_e64 v7, v20, v12, s[4:5]
	v_cndmask_b32_e64 v7, v7, v2, s[0:1]
	v_add_f32_e32 v2, v5, v5
	v_cndmask_b32_e64 v2, v2, v5, s[0:1]
	v_cndmask_b32_e64 v9, v21, v13, s[4:5]
	v_mul_f32_e32 v2, 0xbfb8aa3b, v2
	v_cndmask_b32_e64 v22, v9, v3, s[0:1]
	v_exp_f32_e32 v9, v2
	s_nop 0
	v_pk_add_f32 v[2:3], v[8:9], 1.0 op_sel_hi:[1,0]
	s_nop 0
	v_div_scale_f32 v8, s[78:79], v3, v3, 1.0
	v_rcp_f32_e32 v9, v8
	s_nop 0
	v_fma_f32 v12, -v8, v9, 1.0
	v_fmac_f32_e32 v9, v12, v9
	v_div_scale_f32 v12, vcc, 1.0, v3, 1.0
	v_mul_f32_e32 v13, v12, v9
	v_fma_f32 v14, -v8, v13, v12
	v_fmac_f32_e32 v13, v14, v9
	v_fma_f32 v8, -v8, v13, v12
	v_div_fmas_f32 v8, v8, v9, v13
	v_div_fixup_f32 v3, v8, v3, 1.0
	v_div_scale_f32 v8, s[78:79], v2, v2, 1.0
	v_rcp_f32_e32 v9, v8
	s_nop 0
	v_fma_f32 v12, -v8, v9, 1.0
	v_fmac_f32_e32 v9, v12, v9
	v_div_scale_f32 v12, vcc, 1.0, v2, 1.0
	v_mul_f32_e32 v13, v12, v9
	v_fma_f32 v14, -v8, v13, v12
	v_fmac_f32_e32 v13, v14, v9
	v_fma_f32 v8, -v8, v13, v12
	v_div_fmas_f32 v8, v8, v9, v13
	v_div_fixup_f32 v2, v8, v2, 1.0
	v_pk_fma_f32 v[8:9], v[2:3], 2.0, -1.0 op_sel_hi:[1,0,0]
	v_lshlrev_b32_e32 v13, 16, v11
	v_cndmask_b32_e64 v5, v5, v9, s[4:5]
	v_cndmask_b32_e64 v4, v4, v8, s[4:5]
	v_cndmask_b32_e64 v23, v4, v2, s[0:1]
	v_cndmask_b32_e64 v28, v5, v3, s[0:1]
	v_lshlrev_b32_e32 v12, 16, v10
	v_and_b32_e32 v14, 0xffff0000, v10
	v_cndmask_b32_e64 v17, 0, v37, s[6:7]
	v_cndmask_b32_e64 v16, 0, v36, s[6:7]
	v_pk_add_f32 v[18:19], v[24:25], v[12:13] neg_lo:[0,1] neg_hi:[0,1]
	s_waitcnt vmcnt(0) lgkmcnt(0)
	v_mov_b64_e32 v[2:3], v[224:225]
	v_mov_b64_e32 v[4:5], v[226:227]
	v_mov_b64_e32 v[8:9], v[228:229]
	v_mov_b64_e32 v[10:11], v[230:231]
	v_mov_b32_e32 v20, v2
	v_mov_b32_e32 v21, v4
	v_pk_fma_f32 v[18:19], v[18:19], v[20:21], v[12:13]
	v_pk_add_f32 v[12:13], v[16:17], v[12:13] neg_lo:[0,1] neg_hi:[0,1]
	v_mov_b32_e32 v16, v8
	v_mov_b32_e32 v17, v10
	v_pk_fma_f32 v[12:13], v[12:13], v[16:17], v[18:19]
	v_cndmask_b32_e64 v17, 0, v38, s[6:7]
	v_cndmask_b32_e64 v16, 0, v39, s[6:7]
	v_pk_add_f32 v[18:19], v[26:27], v[14:15] neg_lo:[0,1] neg_hi:[0,1]
	v_mov_b32_e32 v4, v3
	v_pk_fma_f32 v[4:5], v[18:19], v[4:5], v[14:15]
	v_pk_add_f32 v[14:15], v[16:17], v[14:15] neg_lo:[0,1] neg_hi:[0,1]
	v_mov_b32_e32 v10, v9
	v_pk_fma_f32 v[4:5], v[14:15], v[10:11], v[4:5]
	v_add_f32_e32 v2, v12, v12
	v_add_f32_e32 v3, v4, v4
	v_cndmask_b32_e64 v3, v3, v4, s[0:1]
	v_mul_f32_e32 v3, 0xbfb8aa3b, v3
	v_exp_f32_e32 v8, v3
	v_add_f32_e32 v3, v13, v13
	v_cndmask_b32_e64 v2, v2, v12, s[0:1]
	v_cndmask_b32_e64 v3, v3, v13, s[0:1]
	v_mul_f32_e32 v2, 0xbfb8aa3b, v2
	v_mul_f32_e32 v3, 0xbfb8aa3b, v3
	v_exp_f32_e32 v2, v2
	v_exp_f32_e32 v3, v3
	s_nop 0
	v_pk_add_f32 v[2:3], v[2:3], 1.0 op_sel_hi:[1,0]
	s_nop 0
	v_div_scale_f32 v9, s[6:7], v3, v3, 1.0
	v_rcp_f32_e32 v10, v9
	s_nop 0
	v_fma_f32 v11, -v9, v10, 1.0
	v_fmac_f32_e32 v10, v11, v10
	v_div_scale_f32 v11, vcc, 1.0, v3, 1.0
	v_mul_f32_e32 v14, v11, v10
	v_fma_f32 v15, -v9, v14, v11
	v_fmac_f32_e32 v14, v15, v10
	v_fma_f32 v9, -v9, v14, v11
	v_div_fmas_f32 v9, v9, v10, v14
	v_div_fixup_f32 v3, v9, v3, 1.0
	v_div_scale_f32 v9, s[6:7], v2, v2, 1.0
	v_rcp_f32_e32 v10, v9
	s_nop 0
	v_fma_f32 v11, -v9, v10, 1.0
	v_fmac_f32_e32 v10, v11, v10
	v_div_scale_f32 v11, vcc, 1.0, v2, 1.0
	v_mul_f32_e32 v14, v11, v10
	v_fma_f32 v15, -v9, v14, v11
	v_fmac_f32_e32 v14, v15, v10
	v_fma_f32 v9, -v9, v14, v11
	v_div_fmas_f32 v9, v9, v10, v14
	v_div_fixup_f32 v2, v9, v2, 1.0
	v_pk_fma_f32 v[10:11], v[2:3], 2.0, -1.0 op_sel_hi:[1,0,0]
	s_nop 0
	v_cndmask_b32_e64 v9, v12, v10, s[4:5]
	v_cndmask_b32_e64 v10, v13, v11, s[4:5]
	v_cndmask_b32_e64 v11, v9, v2, s[0:1]
	v_add_f32_e32 v2, v5, v5
	v_cndmask_b32_e64 v2, v2, v5, s[0:1]
	v_mul_f32_e32 v2, 0xbfb8aa3b, v2
	v_exp_f32_e32 v9, v2
	v_cndmask_b32_e64 v10, v10, v3, s[0:1]
	v_pk_add_f32 v[2:3], v[8:9], 1.0 op_sel_hi:[1,0]
	s_nop 0
	v_div_scale_f32 v8, s[6:7], v3, v3, 1.0
	v_rcp_f32_e32 v9, v8
	s_nop 0
	v_fma_f32 v12, -v8, v9, 1.0
	v_fmac_f32_e32 v9, v12, v9
	v_div_scale_f32 v12, vcc, 1.0, v3, 1.0
	v_mul_f32_e32 v13, v12, v9
	v_fma_f32 v14, -v8, v13, v12
	v_fmac_f32_e32 v13, v14, v9
	v_fma_f32 v8, -v8, v13, v12
	v_div_fmas_f32 v8, v8, v9, v13
	v_div_fixup_f32 v3, v8, v3, 1.0
	v_div_scale_f32 v8, s[6:7], v2, v2, 1.0
	v_rcp_f32_e32 v9, v8
	s_nop 0
	v_fma_f32 v12, -v8, v9, 1.0
	v_fmac_f32_e32 v9, v12, v9
	v_div_scale_f32 v12, vcc, 1.0, v2, 1.0
	v_mul_f32_e32 v13, v12, v9
	v_fma_f32 v14, -v8, v13, v12
	v_fmac_f32_e32 v13, v14, v9
	v_fma_f32 v8, -v8, v13, v12
	v_div_fmas_f32 v8, v8, v9, v13
	v_div_fixup_f32 v2, v8, v2, 1.0
	v_pk_fma_f32 v[8:9], v[2:3], 2.0, -1.0 op_sel_hi:[1,0,0]
	v_bfe_u32 v12, v11, 16, 1
	v_cndmask_b32_e64 v5, v5, v9, s[4:5]
	v_cndmask_b32_e64 v4, v4, v8, s[4:5]
	v_cndmask_b32_e64 v2, v4, v2, s[0:1]
	v_cndmask_b32_e64 v3, v5, v3, s[0:1]
	v_bfe_u32 v4, v3, 16, 1
	v_bfe_u32 v5, v2, 16, 1
	v_add3_u32 v2, v2, v5, s58
	v_add3_u32 v3, v3, v4, s58
	v_bfe_u32 v4, v7, 16, 1
	v_bfe_u32 v5, v22, 16, 1
	v_bfe_u32 v13, v10, 16, 1
	v_bfe_u32 v8, v28, 16, 1
	v_bfe_u32 v9, v23, 16, 1
	v_add3_u32 v10, v10, v13, s58
	v_add3_u32 v11, v11, v12, s58
	v_add3_u32 v5, v22, v5, s58
	v_add3_u32 v4, v7, v4, s58
	v_add3_u32 v9, v23, v9, s58
	v_add3_u32 v8, v28, v8, s58
	v_lshrrev_b32_e32 v7, 16, v4
	v_lshrrev_b32_e32 v12, 16, v5
	v_lshrrev_b32_e32 v4, 16, v11
	v_lshrrev_b32_e32 v5, 16, v10
	v_and_or_b32 v5, v3, s54, v5
	v_and_or_b32 v4, v2, s54, v4
	v_and_or_b32 v3, v8, s54, v12
	v_and_or_b32 v2, v9, s54, v7
	ds_write_b128 v6, v[2:5] offset:4096
	s_cbranch_scc0 .LBB0_423
	v_ashrrev_i32_e32 v137, 3, v135
	v_and_b32_e32 v138, -4, v137
	v_add_u32_e32 v16, s27, v138
	v_add_u32_e32 v0, -1, v16
	v_or_b32_e32 v44, 1, v16
	v_and_b32_e32 v126, 31, v135
	v_max_i32_e32 v0, s12, v0
	v_max_i32_e32 v2, s12, v16
	v_max_i32_e32 v10, s12, v44
	v_lshlrev_b32_e32 v34, 4, v126
	v_mov_b32_e32 v35, v65
	s_mulk_i32 s26, 0x900
	v_min_i32_e32 v0, s24, v0
	v_min_i32_e32 v2, s24, v2
	v_min_i32_e32 v10, s24, v10
	v_lshl_add_u64 v[88:89], s[52:53], 0, v[34:35]
	s_mov_b64 s[0:1], 0x7158100
	v_add_u32_e32 v0, s26, v0
	v_add_u32_e32 v2, s26, v2
	v_add_u32_e32 v10, s26, v10
	v_lshl_add_u64 v[8:9], v[88:89], 0, s[0:1]
	v_mul_hi_i32_i24_e32 v29, 0x1240, v0
	v_mul_i32_i24_e32 v28, 0x1240, v0
	v_mul_hi_i32_i24_e32 v47, 0x1240, v2
	v_mul_i32_i24_e32 v46, 0x1240, v2
	v_mul_hi_i32_i24_e32 v49, 0x1240, v10
	v_mul_i32_i24_e32 v48, 0x1240, v10
	v_lshl_add_u64 v[0:1], v[8:9], 0, v[28:29]
	v_lshl_add_u64 v[4:5], v[8:9], 0, v[46:47]
	v_lshl_add_u64 v[10:11], v[8:9], 0, v[48:49]
	v_or_b32_e32 v45, 2, v16
	global_load_dwordx4 v[0:3], v[0:1], off
	s_nop 0
	global_load_dwordx4 v[4:7], v[4:5], off
	v_or_b32_e32 v66, 3, v16
	global_load_dwordx4 v[36:39], v[10:11], off
	v_max_i32_e32 v10, s12, v45
	v_min_i32_e32 v10, s24, v10
	v_add_u32_e32 v10, s26, v10
	v_mul_hi_i32_i24_e32 v51, 0x1240, v10
	v_mul_i32_i24_e32 v50, 0x1240, v10
	v_lshl_add_u64 v[10:11], v[8:9], 0, v[50:51]
	global_load_dwordx4 v[40:43], v[10:11], off
	v_max_i32_e32 v10, s12, v66
	v_min_i32_e32 v10, s24, v10
	v_add_u32_e32 v10, s26, v10
	v_mul_hi_i32_i24_e32 v53, 0x1240, v10
	v_mul_i32_i24_e32 v52, 0x1240, v10
	v_lshl_add_u64 v[10:11], v[8:9], 0, v[52:53]
	v_add_u32_e32 v67, 4, v16
	global_load_dwordx4 v[56:59], v[10:11], off
	v_max_i32_e32 v10, s12, v67
	v_min_i32_e32 v10, s24, v10
	v_add_u32_e32 v10, s26, v10
	v_mul_hi_i32_i24_e32 v55, 0x1240, v10
	v_mul_i32_i24_e32 v54, 0x1240, v10
	v_lshl_add_u64 v[8:9], v[8:9], 0, v[54:55]
	global_load_dwordx4 v[60:63], v[8:9], off
	v_mov_b32_e32 v8, s52
	v_lshlrev_b32_e32 v64, 5, v126
	v_mov_b32_e32 v9, s53
	v_add_co_u32_e32 v32, vcc, s55, v8
	v_lshl_add_u64 v[24:25], s[10:11], 0, v[64:65]
	s_nop 0
	v_addc_co_u32_e32 v33, vcc, 0, v9, vcc
	global_load_dwordx4 v[8:11], v[24:25], off
	v_lshl_add_u64 v[26:27], s[8:9], 0, v[64:65]
	global_load_dwordx2 v[30:31], v[32:33], off offset:464
	global_load_dwordx4 v[12:15], v[26:27], off
	v_cmp_lt_i32_e32 vcc, s12, v16
	v_cmp_ge_i32_e64 s[0:1], s13, v16
	v_cmp_le_i32_e64 s[4:5], s12, v16
	v_cmp_gt_i32_e64 s[6:7], s13, v16
	global_load_dwordx4 v[16:19], v[24:25], off offset:16
	global_load_dwordx4 v[20:23], v[26:27], off offset:16
	v_cmp_le_i32_e64 s[8:9], s12, v44
	v_cmp_gt_i32_e64 s[10:11], s13, v44
	s_and_b64 vcc, vcc, s[0:1]
	s_and_b64 s[4:5], s[4:5], s[6:7]
	s_and_b64 s[6:7], s[8:9], s[10:11]
	v_cmp_le_i32_e64 s[0:1], s12, v45
	v_cmp_gt_i32_e64 s[8:9], s13, v45
	s_and_b64 s[8:9], s[0:1], s[8:9]
	v_cmp_le_i32_e64 s[0:1], s12, v66
	v_cmp_gt_i32_e64 s[10:11], s13, v66
	s_and_b64 s[10:11], s[0:1], s[10:11]
	v_cmp_le_i32_e64 s[0:1], s12, v67
	v_cmp_gt_i32_e64 s[12:13], s13, v67
	s_and_b64 s[12:13], s[0:1], s[12:13]
	v_add_u32_e32 v90, s18, v138
	v_ashrrev_i32_e32 v91, 31, v90
	v_or_b32_e32 v92, 1, v90
	v_ashrrev_i32_e32 v93, 31, v92
	s_mov_b32 s24, 0
	v_lshlrev_b32_e32 v126, 3, v126
	s_waitcnt vmcnt(0) lgkmcnt(0)
	v_cndmask_b32_e32 v44, 0, v1, vcc
	v_cndmask_b32_e32 v68, 0, v0, vcc
	v_cndmask_b32_e64 v69, 0, v5, s[4:5]
	v_cndmask_b32_e64 v73, 0, v4, s[4:5]
	v_cndmask_b32_e64 v76, 0, v39, s[6:7]
	v_cndmask_b32_e64 v78, 0, v38, s[6:7]
	v_cndmask_b32_e64 v38, 0, v37, s[6:7]
	v_cndmask_b32_e64 v39, 0, v36, s[6:7]
	v_and_b32_e32 v37, 0xffff0000, v44
	v_and_b32_e32 v36, 0xffff0000, v68
	v_cndmask_b32_e32 v70, 0, v3, vcc
	v_cndmask_b32_e32 v71, 0, v2, vcc
	v_cndmask_b32_e64 v72, 0, v7, s[4:5]
	v_cndmask_b32_e64 v74, 0, v6, s[4:5]
	v_lshlrev_b32_e32 v45, 16, v69
	v_lshlrev_b32_e32 v75, 16, v76
	v_and_b32_e32 v77, 0xffff0000, v76
	v_and_b32_e32 v76, 0xffff0000, v78
	v_cndmask_b32_e64 v86, 0, v59, s[10:11]
	v_cndmask_b32_e64 v87, 0, v58, s[10:11]
	v_and_b32_e32 v59, 0xffff0000, v69
	v_and_b32_e32 v58, 0xffff0000, v73
	v_pk_add_f32 v[36:37], v[36:37], v[58:59] neg_lo:[0,1] neg_hi:[0,1]
	v_cndmask_b32_e64 v94, 0, v57, s[10:11]
	v_cndmask_b32_e64 v95, 0, v56, s[10:11]
	v_cndmask_b32_e64 v96, 0, v63, s[12:13]
	v_cndmask_b32_e64 v97, 0, v62, s[12:13]
	v_and_b32_e32 v63, 0xffff0000, v38
	v_and_b32_e32 v62, 0xffff0000, v39
	v_cndmask_b32_e64 v118, 0, v61, s[12:13]
	v_cndmask_b32_e64 v119, 0, v60, s[12:13]
	v_lshlrev_b32_e32 v61, 16, v38
	v_lshlrev_b32_e32 v60, 16, v39
	v_lshl_add_u64 v[56:57], v[88:89], 0, s[36:37]
	v_mov_b32_e32 v67, v10
	v_mov_b32_e32 v10, v9
	v_readfirstlane_b32 s1, v31
	v_readfirstlane_b32 s0, v30
	v_lshlrev_b32_e32 v31, 16, v44
	v_lshlrev_b32_e32 v30, 16, v68
	v_lshlrev_b32_e32 v44, 16, v73
	v_mov_b32_e32 v66, v8
	v_mov_b32_e32 v69, v14
	v_pk_fma_f32 v[8:9], v[10:11], v[36:37], v[58:59]
	v_pk_add_f32 v[36:37], v[62:63], v[58:59] neg_lo:[0,1] neg_hi:[0,1]
	v_mov_b32_e32 v14, v13
	v_pk_add_f32 v[30:31], v[30:31], v[44:45] neg_lo:[0,1] neg_hi:[0,1]
	v_mov_b32_e32 v68, v12
	v_pk_fma_f32 v[36:37], v[14:15], v[36:37], v[8:9]
	v_lshlrev_b32_e32 v9, 16, v70
	v_lshlrev_b32_e32 v8, 16, v71
	v_and_b32_e32 v13, 0xffff0000, v70
	v_and_b32_e32 v12, 0xffff0000, v71
	v_lshlrev_b32_e32 v71, 16, v72
	v_lshlrev_b32_e32 v70, 16, v74
	v_pk_fma_f32 v[30:31], v[66:67], v[30:31], v[44:45]
	v_pk_add_f32 v[38:39], v[60:61], v[44:45] neg_lo:[0,1] neg_hi:[0,1]
	v_and_b32_e32 v73, 0xffff0000, v72
	v_and_b32_e32 v72, 0xffff0000, v74
	v_lshlrev_b32_e32 v74, 16, v78
	v_pk_add_f32 v[8:9], v[8:9], v[70:71] neg_lo:[0,1] neg_hi:[0,1]
	v_mov_b32_e32 v78, v16
	v_mov_b32_e32 v79, v18
	v_pk_fma_f32 v[30:31], v[68:69], v[38:39], v[30:31]
	v_pk_fma_f32 v[8:9], v[78:79], v[8:9], v[70:71]
	v_pk_add_f32 v[38:39], v[74:75], v[70:71] neg_lo:[0,1] neg_hi:[0,1]
	v_mov_b32_e32 v80, v20
	v_mov_b32_e32 v81, v22
	v_pk_fma_f32 v[98:99], v[80:81], v[38:39], v[8:9]
	v_pk_add_f32 v[8:9], v[12:13], v[72:73] neg_lo:[0,1] neg_hi:[0,1]
	v_mov_b32_e32 v18, v17
	v_pk_fma_f32 v[8:9], v[18:19], v[8:9], v[72:73]
	v_pk_add_f32 v[12:13], v[76:77], v[72:73] neg_lo:[0,1] neg_hi:[0,1]
	v_mov_b32_e32 v22, v21
	v_pk_fma_f32 v[100:101], v[22:23], v[12:13], v[8:9]
	v_bfe_u32 v8, v30, 16, 1
	v_bfe_u32 v9, v31, 16, 1
	v_bfe_u32 v12, v98, 16, 1
	v_bfe_u32 v13, v99, 16, 1
	v_add3_u32 v13, v99, v13, s58
	v_add3_u32 v12, v98, v12, s58
	v_add3_u32 v9, v31, v9, s58
	v_add3_u32 v8, v30, v8, s58
	v_lshrrev_b32_e32 v8, 16, v8
	v_lshrrev_b32_e32 v9, 16, v9
	v_lshrrev_b32_e32 v12, 16, v12
	v_lshrrev_b32_e32 v13, 16, v13
	v_lshlrev_b64 v[38:39], 9, v[90:91]
	v_cndmask_b32_e64 v82, 0, v43, s[8:9]
	v_cndmask_b32_e64 v83, 0, v42, s[8:9]
	v_cndmask_b32_e64 v84, 0, v41, s[8:9]
	v_cndmask_b32_e64 v85, 0, v40, s[8:9]
	v_lshl_add_u64 v[0:1], s[0:1], 0, v[64:65]
	v_and_or_b32 v43, v101, s54, v13
	v_and_or_b32 v42, v100, s54, v12
	v_and_or_b32 v41, v37, s54, v9
	v_and_or_b32 v40, v36, s54, v8
	v_lshl_add_u64 v[8:9], v[56:57], 0, v[38:39]
	global_load_dwordx4 v[4:7], v[0:1], off
	s_nop 0
	global_load_dwordx4 v[0:3], v[0:1], off offset:16
	v_pk_add_f32 v[16:17], v[44:45], v[60:61] neg_lo:[0,1] neg_hi:[0,1]
	global_store_dwordx4 v[8:9], v[40:43], off
	v_lshlrev_b32_e32 v9, 16, v84
	v_lshlrev_b32_e32 v8, 16, v85
	v_pk_fma_f32 v[16:17], v[66:67], v[16:17], v[60:61]
	v_pk_add_f32 v[20:21], v[8:9], v[60:61] neg_lo:[0,1] neg_hi:[0,1]
	v_and_b32_e32 v13, 0xffff0000, v84
	v_and_b32_e32 v12, 0xffff0000, v85
	v_pk_fma_f32 v[102:103], v[68:69], v[20:21], v[16:17]
	v_pk_add_f32 v[16:17], v[58:59], v[62:63] neg_lo:[0,1] neg_hi:[0,1]
	v_pk_add_f32 v[20:21], v[12:13], v[62:63] neg_lo:[0,1] neg_hi:[0,1]
	v_pk_fma_f32 v[16:17], v[10:11], v[16:17], v[62:63]
	v_pk_add_f32 v[40:41], v[70:71], v[74:75] neg_lo:[0,1] neg_hi:[0,1]
	v_pk_fma_f32 v[104:105], v[14:15], v[20:21], v[16:17]
	v_lshlrev_b32_e32 v17, 16, v82
	v_lshlrev_b32_e32 v16, 16, v83
	v_pk_fma_f32 v[40:41], v[78:79], v[40:41], v[74:75]
	v_pk_add_f32 v[42:43], v[16:17], v[74:75] neg_lo:[0,1] neg_hi:[0,1]
	v_and_b32_e32 v21, 0xffff0000, v82
	v_and_b32_e32 v20, 0xffff0000, v83
	v_pk_fma_f32 v[106:107], v[80:81], v[42:43], v[40:41]
	v_pk_add_f32 v[40:41], v[72:73], v[76:77] neg_lo:[0,1] neg_hi:[0,1]
	v_pk_add_f32 v[42:43], v[20:21], v[76:77] neg_lo:[0,1] neg_hi:[0,1]
	v_pk_fma_f32 v[40:41], v[18:19], v[40:41], v[76:77]
	v_pk_add_f32 v[60:61], v[60:61], v[8:9] neg_lo:[0,1] neg_hi:[0,1]
	v_pk_fma_f32 v[108:109], v[22:23], v[42:43], v[40:41]
	v_bfe_u32 v40, v102, 16, 1
	v_bfe_u32 v41, v103, 16, 1
	v_bfe_u32 v42, v106, 16, 1
	v_bfe_u32 v43, v107, 16, 1
	v_add3_u32 v43, v107, v43, s58
	v_add3_u32 v42, v106, v42, s58
	v_add3_u32 v41, v103, v41, s58
	v_add3_u32 v40, v102, v40, s58
	v_lshrrev_b32_e32 v40, 16, v40
	v_lshrrev_b32_e32 v41, 16, v41
	v_lshrrev_b32_e32 v42, 16, v42
	v_lshrrev_b32_e32 v43, 16, v43
	v_and_or_b32 v45, v109, s54, v43
	v_and_or_b32 v44, v108, s54, v42
	v_and_or_b32 v43, v105, s54, v41
	v_and_or_b32 v42, v104, s54, v40
	v_lshlrev_b64 v[40:41], 9, v[92:93]
	v_lshl_add_u64 v[58:59], v[56:57], 0, v[40:41]
	global_store_dwordx4 v[58:59], v[42:45], off
	v_pk_fma_f32 v[60:61], v[66:67], v[60:61], v[8:9]
	v_and_b32_e32 v71, 0xffff0000, v94
	v_lshlrev_b32_e32 v45, 16, v94
	v_lshlrev_b32_e32 v44, 16, v95
	v_pk_add_f32 v[42:43], v[44:45], v[8:9] neg_lo:[0,1] neg_hi:[0,1]
	v_and_b32_e32 v70, 0xffff0000, v95
	v_pk_fma_f32 v[110:111], v[68:69], v[42:43], v[60:61]
	v_pk_add_f32 v[42:43], v[62:63], v[12:13] neg_lo:[0,1] neg_hi:[0,1]
	v_pk_add_f32 v[58:59], v[70:71], v[12:13] neg_lo:[0,1] neg_hi:[0,1]
	v_pk_fma_f32 v[42:43], v[10:11], v[42:43], v[12:13]
	v_lshlrev_b32_e32 v63, 16, v86
	v_lshlrev_b32_e32 v62, 16, v87
	v_pk_add_f32 v[60:61], v[74:75], v[16:17] neg_lo:[0,1] neg_hi:[0,1]
	v_pk_fma_f32 v[112:113], v[14:15], v[58:59], v[42:43]
	v_pk_add_f32 v[42:43], v[62:63], v[16:17] neg_lo:[0,1] neg_hi:[0,1]
	v_pk_fma_f32 v[60:61], v[78:79], v[60:61], v[16:17]
	v_and_b32_e32 v73, 0xffff0000, v86
	v_and_b32_e32 v72, 0xffff0000, v87
	v_pk_fma_f32 v[114:115], v[80:81], v[42:43], v[60:61]
	v_pk_add_f32 v[42:43], v[76:77], v[20:21] neg_lo:[0,1] neg_hi:[0,1]
	v_pk_add_f32 v[58:59], v[72:73], v[20:21] neg_lo:[0,1] neg_hi:[0,1]
	v_pk_fma_f32 v[42:43], v[18:19], v[42:43], v[20:21]
	v_or_b32_e32 v94, 2, v90
	v_pk_fma_f32 v[116:117], v[22:23], v[58:59], v[42:43]
	v_bfe_u32 v42, v110, 16, 1
	v_bfe_u32 v43, v111, 16, 1
	v_bfe_u32 v58, v114, 16, 1
	v_bfe_u32 v59, v115, 16, 1
	v_add3_u32 v59, v115, v59, s58
	v_add3_u32 v58, v114, v58, s58
	v_add3_u32 v43, v111, v43, s58
	v_add3_u32 v42, v110, v42, s58
	v_lshrrev_b32_e32 v42, 16, v42
	v_lshrrev_b32_e32 v43, 16, v43
	v_lshrrev_b32_e32 v58, 16, v58
	v_lshrrev_b32_e32 v59, 16, v59
	v_ashrrev_i32_e32 v95, 31, v94
	v_and_or_b32 v61, v117, s54, v59
	v_and_or_b32 v60, v116, s54, v58
	v_and_or_b32 v59, v113, s54, v43
	v_and_or_b32 v58, v112, s54, v42
	v_lshlrev_b64 v[42:43], 9, v[94:95]
	v_lshl_add_u64 v[74:75], v[56:57], 0, v[42:43]
	global_store_dwordx4 v[74:75], v[58:61], off
	v_pk_add_f32 v[8:9], v[8:9], v[44:45] neg_lo:[0,1] neg_hi:[0,1]
	v_pk_add_f32 v[12:13], v[12:13], v[70:71] neg_lo:[0,1] neg_hi:[0,1]
	v_lshlrev_b32_e32 v59, 16, v118
	v_lshlrev_b32_e32 v58, 16, v119
	v_and_b32_e32 v61, 0xffff0000, v118
	v_and_b32_e32 v60, 0xffff0000, v119
	v_pk_add_f32 v[58:59], v[58:59], v[44:45] neg_lo:[0,1] neg_hi:[0,1]
	v_pk_fma_f32 v[8:9], v[66:67], v[8:9], v[44:45]
	v_pk_add_f32 v[60:61], v[60:61], v[70:71] neg_lo:[0,1] neg_hi:[0,1]
	v_pk_fma_f32 v[118:119], v[68:69], v[58:59], v[8:9]
	v_pk_fma_f32 v[8:9], v[10:11], v[12:13], v[70:71]
	v_pk_add_f32 v[12:13], v[16:17], v[62:63] neg_lo:[0,1] neg_hi:[0,1]
	v_pk_fma_f32 v[120:121], v[14:15], v[60:61], v[8:9]
	v_lshlrev_b32_e32 v9, 16, v96
	v_lshlrev_b32_e32 v8, 16, v97
	v_and_b32_e32 v11, 0xffff0000, v96
	v_and_b32_e32 v10, 0xffff0000, v97
	v_pk_add_f32 v[8:9], v[8:9], v[62:63] neg_lo:[0,1] neg_hi:[0,1]
	v_pk_add_f32 v[14:15], v[20:21], v[72:73] neg_lo:[0,1] neg_hi:[0,1]
	v_pk_fma_f32 v[12:13], v[78:79], v[12:13], v[62:63]
	v_pk_add_f32 v[10:11], v[10:11], v[72:73] neg_lo:[0,1] neg_hi:[0,1]
	v_pk_fma_f32 v[122:123], v[80:81], v[8:9], v[12:13]
	v_pk_fma_f32 v[8:9], v[18:19], v[14:15], v[72:73]
	v_or_b32_e32 v96, 3, v90
	v_pk_fma_f32 v[124:125], v[22:23], v[10:11], v[8:9]
	v_bfe_u32 v8, v118, 16, 1
	v_bfe_u32 v9, v119, 16, 1
	v_bfe_u32 v10, v122, 16, 1
	v_bfe_u32 v11, v123, 16, 1
	v_add3_u32 v11, v123, v11, s58
	v_add3_u32 v10, v122, v10, s58
	v_add3_u32 v9, v119, v9, s58
	v_add3_u32 v8, v118, v8, s58
	v_ashrrev_i32_e32 v97, 31, v96
	v_lshrrev_b32_e32 v8, 16, v8
	v_lshrrev_b32_e32 v9, 16, v9
	v_lshrrev_b32_e32 v10, 16, v10
	v_lshrrev_b32_e32 v11, 16, v11
	v_lshlrev_b64 v[44:45], 9, v[96:97]
	v_and_or_b32 v11, v125, s54, v11
	v_and_or_b32 v10, v124, s54, v10
	v_and_or_b32 v9, v121, s54, v9
	v_and_or_b32 v8, v120, s54, v8
	v_lshl_add_u64 v[12:13], v[56:57], 0, v[44:45]
	global_store_dwordx4 v[12:13], v[8:11], off
	s_waitcnt vmcnt(0) lgkmcnt(0)
	v_mul_f32_e32 v159, v98, v0
	v_mul_f32_e32 v160, v100, v1
	v_lshl_add_u64 v[8:9], v[88:89], 0, s[38:39]
	v_lshl_add_u64 v[10:11], v[8:9], 0, v[28:29]
	global_load_dwordx4 v[56:59], v[10:11], off
	v_lshl_add_u64 v[10:11], v[8:9], 0, v[46:47]
	global_load_dwordx4 v[60:63], v[10:11], off
	v_lshl_add_u64 v[10:11], v[8:9], 0, v[48:49]
	global_load_dwordx4 v[66:69], v[10:11], off
	v_lshl_add_u64 v[10:11], v[8:9], 0, v[50:51]
	global_load_dwordx4 v[70:73], v[10:11], off
	v_lshl_add_u64 v[10:11], v[8:9], 0, v[52:53]
	global_load_dwordx4 v[74:77], v[10:11], off
	v_lshl_add_u64 v[8:9], v[8:9], 0, v[54:55]
	global_load_dwordx4 v[78:81], v[8:9], off
	s_nop 0
	global_load_dwordx4 v[8:11], v[24:25], off offset:2048
	global_load_dwordx4 v[12:15], v[26:27], off offset:2048
	global_load_dwordx4 v[16:19], v[24:25], off offset:2064
	global_load_dwordx4 v[20:23], v[26:27], off offset:2064
	v_mul_f32_e32 v161, v99, v2
	v_mul_f32_e32 v162, v101, v3
	v_mul_f32_e32 v163, v4, v102
	v_mul_f32_e32 v168, v5, v104
	v_mul_f32_e32 v169, v103, v6
	v_mul_f32_e32 v170, v105, v7
	v_mul_f32_e32 v171, v106, v0
	v_mul_f32_e32 v175, v114, v0
	v_mul_f32_e32 v187, v122, v0
	v_mul_f32_e32 v172, v108, v1
	v_mul_f32_e32 v176, v116, v1
	v_mul_f32_e32 v177, v115, v2
	v_mul_f32_e32 v188, v124, v1
	v_bitop3_b32 v1, v135, 31, v130 bitop3:0xe0
	v_mul_f32_e32 v173, v107, v2
	v_mul_f32_e32 v174, v109, v3
	v_mul_f32_e32 v110, v4, v110
	v_mul_f32_e32 v112, v5, v112
	v_mul_f32_e32 v111, v6, v111
	v_mul_f32_e32 v113, v113, v7
	v_mul_f32_e32 v178, v117, v3
	v_mul_f32_e32 v179, v4, v118
	v_mul_f32_e32 v184, v5, v120
	v_mul_f32_e32 v185, v6, v119
	v_mul_f32_e32 v186, v7, v121
	v_mul_f32_e32 v189, v123, v2
	v_mul_f32_e32 v190, v125, v3
	s_waitcnt vmcnt(0) lgkmcnt(0)
	v_cndmask_b32_e32 v84, 0, v57, vcc
	v_cndmask_b32_e32 v85, 0, v56, vcc
	v_cndmask_b32_e64 v136, 0, v61, s[4:5]
	v_cndmask_b32_e64 v139, 0, v60, s[4:5]
	v_cndmask_b32_e64 v142, 0, v67, s[6:7]
	v_cndmask_b32_e64 v143, 0, v66, s[6:7]
	v_and_b32_e32 v61, 0xffff0000, v84
	v_and_b32_e32 v60, 0xffff0000, v85
	v_and_b32_e32 v67, 0xffff0000, v136
	v_and_b32_e32 v66, 0xffff0000, v139
	v_cndmask_b32_e32 v82, 0, v59, vcc
	v_cndmask_b32_e32 v83, 0, v58, vcc
	v_cndmask_b32_e64 v86, 0, v63, s[4:5]
	v_cndmask_b32_e64 v87, 0, v62, s[4:5]
	v_cndmask_b32_e64 v144, 0, v73, s[8:9]
	v_cndmask_b32_e64 v146, 0, v71, s[8:9]
	v_cndmask_b32_e64 v147, 0, v70, s[8:9]
	v_lshlrev_b32_e32 v59, 16, v84
	v_lshlrev_b32_e32 v58, 16, v85
	v_lshlrev_b32_e32 v63, 16, v136
	v_lshlrev_b32_e32 v62, 16, v139
	v_and_b32_e32 v71, 0xffff0000, v142
	v_and_b32_e32 v70, 0xffff0000, v143
	v_mov_b32_e32 v73, v10
	v_pk_add_f32 v[60:61], v[60:61], v[66:67] neg_lo:[0,1] neg_hi:[0,1]
	v_mov_b32_e32 v10, v9
	v_cndmask_b32_e64 v140, 0, v69, s[6:7]
	v_cndmask_b32_e64 v141, 0, v68, s[6:7]
	v_cndmask_b32_e64 v145, 0, v72, s[8:9]
	v_cndmask_b32_e64 v148, 0, v77, s[10:11]
	v_lshlrev_b32_e32 v69, 16, v142
	v_lshlrev_b32_e32 v68, 16, v143
	v_pk_add_f32 v[58:59], v[58:59], v[62:63] neg_lo:[0,1] neg_hi:[0,1]
	v_mov_b32_e32 v72, v8
	v_mov_b32_e32 v77, v14
	v_pk_fma_f32 v[8:9], v[10:11], v[60:61], v[66:67]
	v_pk_add_f32 v[60:61], v[70:71], v[66:67] neg_lo:[0,1] neg_hi:[0,1]
	v_mov_b32_e32 v14, v13
	v_cndmask_b32_e64 v149, 0, v76, s[10:11]
	v_cndmask_b32_e64 v150, 0, v75, s[10:11]
	v_cndmask_b32_e64 v151, 0, v74, s[10:11]
	v_cndmask_b32_e64 v154, 0, v79, s[12:13]
	v_cndmask_b32_e64 v155, 0, v78, s[12:13]
	v_pk_fma_f32 v[58:59], v[72:73], v[58:59], v[62:63]
	v_pk_add_f32 v[74:75], v[68:69], v[62:63] neg_lo:[0,1] neg_hi:[0,1]
	v_mov_b32_e32 v76, v12
	v_pk_fma_f32 v[8:9], v[14:15], v[60:61], v[8:9]
	v_and_b32_e32 v61, 0xffff0000, v82
	v_and_b32_e32 v60, 0xffff0000, v83
	v_and_b32_e32 v79, 0xffff0000, v86
	v_and_b32_e32 v78, 0xffff0000, v87
	v_pk_fma_f32 v[58:59], v[76:77], v[74:75], v[58:59]
	v_lshlrev_b32_e32 v13, 16, v82
	v_lshlrev_b32_e32 v12, 16, v83
	v_lshlrev_b32_e32 v75, 16, v86
	v_lshlrev_b32_e32 v74, 16, v87
	v_and_b32_e32 v83, 0xffff0000, v140
	v_and_b32_e32 v82, 0xffff0000, v141
	v_mov_b32_e32 v85, v18
	v_pk_add_f32 v[60:61], v[60:61], v[78:79] neg_lo:[0,1] neg_hi:[0,1]
	v_mov_b32_e32 v18, v17
	v_cndmask_b32_e64 v152, 0, v81, s[12:13]
	v_cndmask_b32_e64 v153, 0, v80, s[12:13]
	v_lshlrev_b32_e32 v81, 16, v140
	v_lshlrev_b32_e32 v80, 16, v141
	v_pk_add_f32 v[12:13], v[12:13], v[74:75] neg_lo:[0,1] neg_hi:[0,1]
	v_mov_b32_e32 v84, v16
	v_mov_b32_e32 v141, v22
	v_pk_fma_f32 v[16:17], v[18:19], v[60:61], v[78:79]
	v_pk_add_f32 v[60:61], v[82:83], v[78:79] neg_lo:[0,1] neg_hi:[0,1]
	v_mov_b32_e32 v22, v21
	v_pk_fma_f32 v[12:13], v[84:85], v[12:13], v[74:75]
	v_pk_add_f32 v[86:87], v[80:81], v[74:75] neg_lo:[0,1] neg_hi:[0,1]
	v_mov_b32_e32 v140, v20
	v_pk_fma_f32 v[16:17], v[22:23], v[60:61], v[16:17]
	v_pk_fma_f32 v[12:13], v[140:141], v[86:87], v[12:13]
	v_bfe_u32 v20, v17, 16, 1
	v_bfe_u32 v21, v16, 16, 1
	v_bfe_u32 v60, v9, 16, 1
	v_bfe_u32 v61, v8, 16, 1
	v_add3_u32 v8, v8, v61, s58
	v_add3_u32 v9, v9, v60, s58
	v_add3_u32 v16, v16, v21, s58
	v_add3_u32 v17, v17, v20, s58
	v_bfe_u32 v20, v58, 16, 1
	v_bfe_u32 v21, v59, 16, 1
	v_bfe_u32 v60, v12, 16, 1
	v_bfe_u32 v61, v13, 16, 1
	v_add3_u32 v13, v13, v61, s58
	v_add3_u32 v12, v12, v60, s58
	v_add3_u32 v21, v59, v21, s58
	v_add3_u32 v20, v58, v20, s58
	v_lshl_add_u64 v[56:57], v[88:89], 0, s[40:41]
	v_lshrrev_b32_e32 v20, 16, v20
	v_lshrrev_b32_e32 v21, 16, v21
	v_lshrrev_b32_e32 v12, 16, v12
	v_lshrrev_b32_e32 v13, 16, v13
	v_and_or_b32 v61, v17, s54, v13
	v_and_or_b32 v60, v16, s54, v12
	v_and_or_b32 v59, v9, s54, v21
	v_and_or_b32 v58, v8, s54, v20
	v_lshl_add_u64 v[8:9], v[56:57], 0, v[38:39]
	global_store_dwordx4 v[8:9], v[58:61], off
	v_lshlrev_b32_e32 v9, 16, v146
	v_lshlrev_b32_e32 v8, 16, v147
	v_pk_add_f32 v[16:17], v[62:63], v[68:69] neg_lo:[0,1] neg_hi:[0,1]
	v_pk_add_f32 v[20:21], v[8:9], v[68:69] neg_lo:[0,1] neg_hi:[0,1]
	v_pk_fma_f32 v[16:17], v[72:73], v[16:17], v[68:69]
	v_and_b32_e32 v13, 0xffff0000, v146
	v_and_b32_e32 v12, 0xffff0000, v147
	v_pk_fma_f32 v[16:17], v[76:77], v[20:21], v[16:17]
	v_pk_add_f32 v[20:21], v[66:67], v[70:71] neg_lo:[0,1] neg_hi:[0,1]
	v_pk_add_f32 v[58:59], v[12:13], v[70:71] neg_lo:[0,1] neg_hi:[0,1]
	v_pk_fma_f32 v[20:21], v[10:11], v[20:21], v[70:71]
	v_lshlrev_b32_e32 v63, 16, v144
	v_pk_fma_f32 v[20:21], v[14:15], v[58:59], v[20:21]
	v_lshlrev_b32_e32 v62, 16, v145
	v_pk_add_f32 v[58:59], v[74:75], v[80:81] neg_lo:[0,1] neg_hi:[0,1]
	v_pk_add_f32 v[60:61], v[62:63], v[80:81] neg_lo:[0,1] neg_hi:[0,1]
	v_pk_fma_f32 v[58:59], v[84:85], v[58:59], v[80:81]
	v_and_b32_e32 v67, 0xffff0000, v144
	v_and_b32_e32 v66, 0xffff0000, v145
	v_pk_fma_f32 v[58:59], v[140:141], v[60:61], v[58:59]
	v_pk_add_f32 v[60:61], v[78:79], v[82:83] neg_lo:[0,1] neg_hi:[0,1]
	v_pk_add_f32 v[74:75], v[66:67], v[82:83] neg_lo:[0,1] neg_hi:[0,1]
	v_pk_fma_f32 v[60:61], v[18:19], v[60:61], v[82:83]
	v_bfe_u32 v78, v21, 16, 1
	v_pk_fma_f32 v[60:61], v[22:23], v[74:75], v[60:61]
	v_bfe_u32 v79, v20, 16, 1
	v_bfe_u32 v74, v61, 16, 1
	v_bfe_u32 v75, v60, 16, 1
	v_add3_u32 v20, v20, v79, s58
	v_add3_u32 v21, v21, v78, s58
	v_add3_u32 v60, v60, v75, s58
	v_add3_u32 v61, v61, v74, s58
	v_bfe_u32 v74, v16, 16, 1
	v_bfe_u32 v75, v17, 16, 1
	v_bfe_u32 v78, v58, 16, 1
	v_bfe_u32 v79, v59, 16, 1
	v_add3_u32 v59, v59, v79, s58
	v_add3_u32 v58, v58, v78, s58
	v_add3_u32 v17, v17, v75, s58
	v_add3_u32 v16, v16, v74, s58
	v_lshrrev_b32_e32 v16, 16, v16
	v_lshrrev_b32_e32 v17, 16, v17
	v_lshrrev_b32_e32 v58, 16, v58
	v_lshrrev_b32_e32 v59, 16, v59
	v_and_or_b32 v61, v61, s54, v59
	v_and_or_b32 v60, v60, s54, v58
	v_and_or_b32 v59, v21, s54, v17
	v_and_or_b32 v58, v20, s54, v16
	v_lshl_add_u64 v[16:17], v[56:57], 0, v[40:41]
	global_store_dwordx4 v[16:17], v[58:61], off
	v_lshlrev_b32_e32 v17, 16, v150
	v_lshlrev_b32_e32 v16, 16, v151
	v_pk_add_f32 v[68:69], v[68:69], v[8:9] neg_lo:[0,1] neg_hi:[0,1]
	v_pk_add_f32 v[58:59], v[16:17], v[8:9] neg_lo:[0,1] neg_hi:[0,1]
	v_pk_fma_f32 v[68:69], v[72:73], v[68:69], v[8:9]
	v_and_b32_e32 v21, 0xffff0000, v150
	v_and_b32_e32 v20, 0xffff0000, v151
	v_pk_fma_f32 v[58:59], v[76:77], v[58:59], v[68:69]
	v_pk_add_f32 v[68:69], v[70:71], v[12:13] neg_lo:[0,1] neg_hi:[0,1]
	v_pk_add_f32 v[60:61], v[20:21], v[12:13] neg_lo:[0,1] neg_hi:[0,1]
	v_pk_fma_f32 v[68:69], v[10:11], v[68:69], v[12:13]
	v_pk_add_f32 v[80:81], v[80:81], v[62:63] neg_lo:[0,1] neg_hi:[0,1]
	v_pk_fma_f32 v[60:61], v[14:15], v[60:61], v[68:69]
	v_lshlrev_b32_e32 v69, 16, v148
	v_lshlrev_b32_e32 v68, 16, v149
	v_pk_add_f32 v[74:75], v[68:69], v[62:63] neg_lo:[0,1] neg_hi:[0,1]
	v_pk_fma_f32 v[80:81], v[84:85], v[80:81], v[62:63]
	v_and_b32_e32 v71, 0xffff0000, v148
	v_and_b32_e32 v70, 0xffff0000, v149
	v_pk_fma_f32 v[74:75], v[140:141], v[74:75], v[80:81]
	v_pk_add_f32 v[80:81], v[82:83], v[66:67] neg_lo:[0,1] neg_hi:[0,1]
	v_pk_add_f32 v[78:79], v[70:71], v[66:67] neg_lo:[0,1] neg_hi:[0,1]
	v_pk_fma_f32 v[80:81], v[18:19], v[80:81], v[66:67]
	v_bfe_u32 v82, v61, 16, 1
	v_pk_fma_f32 v[78:79], v[22:23], v[78:79], v[80:81]
	v_bfe_u32 v83, v60, 16, 1
	v_bfe_u32 v80, v79, 16, 1
	v_bfe_u32 v81, v78, 16, 1
	v_add3_u32 v83, v60, v83, s58
	v_add3_u32 v82, v61, v82, s58
	v_add3_u32 v60, v78, v81, s58
	v_add3_u32 v61, v79, v80, s58
	v_bfe_u32 v78, v58, 16, 1
	v_bfe_u32 v79, v59, 16, 1
	v_bfe_u32 v80, v74, 16, 1
	v_bfe_u32 v81, v75, 16, 1
	v_add3_u32 v75, v75, v81, s58
	v_add3_u32 v74, v74, v80, s58
	v_add3_u32 v59, v59, v79, s58
	v_add3_u32 v58, v58, v78, s58
	v_lshrrev_b32_e32 v58, 16, v58
	v_lshrrev_b32_e32 v59, 16, v59
	v_lshrrev_b32_e32 v74, 16, v74
	v_lshrrev_b32_e32 v75, 16, v75
	v_and_or_b32 v61, v61, s54, v75
	v_and_or_b32 v60, v60, s54, v74
	v_and_or_b32 v59, v82, s54, v59
	v_and_or_b32 v58, v83, s54, v58
	v_lshl_add_u64 v[74:75], v[56:57], 0, v[42:43]
	global_store_dwordx4 v[74:75], v[58:61], off
	v_pk_add_f32 v[8:9], v[8:9], v[16:17] neg_lo:[0,1] neg_hi:[0,1]
	v_pk_add_f32 v[12:13], v[12:13], v[20:21] neg_lo:[0,1] neg_hi:[0,1]
	v_lshlrev_b32_e32 v59, 16, v154
	v_lshlrev_b32_e32 v58, 16, v155
	v_and_b32_e32 v61, 0xffff0000, v154
	v_and_b32_e32 v60, 0xffff0000, v155
	v_pk_add_f32 v[58:59], v[58:59], v[16:17] neg_lo:[0,1] neg_hi:[0,1]
	v_pk_add_f32 v[60:61], v[60:61], v[20:21] neg_lo:[0,1] neg_hi:[0,1]
	v_pk_fma_f32 v[8:9], v[72:73], v[8:9], v[16:17]
	v_pk_fma_f32 v[10:11], v[10:11], v[12:13], v[20:21]
	v_lshlrev_b32_e32 v13, 16, v152
	v_lshlrev_b32_e32 v12, 16, v153
	v_pk_add_f32 v[16:17], v[62:63], v[68:69] neg_lo:[0,1] neg_hi:[0,1]
	v_pk_fma_f32 v[10:11], v[14:15], v[60:61], v[10:11]
	v_and_b32_e32 v15, 0xffff0000, v152
	v_and_b32_e32 v14, 0xffff0000, v153
	v_pk_add_f32 v[12:13], v[12:13], v[68:69] neg_lo:[0,1] neg_hi:[0,1]
	v_pk_add_f32 v[20:21], v[66:67], v[70:71] neg_lo:[0,1] neg_hi:[0,1]
	v_pk_fma_f32 v[16:17], v[84:85], v[16:17], v[68:69]
	v_pk_add_f32 v[14:15], v[14:15], v[70:71] neg_lo:[0,1] neg_hi:[0,1]
	v_pk_fma_f32 v[12:13], v[140:141], v[12:13], v[16:17]
	v_pk_fma_f32 v[16:17], v[18:19], v[20:21], v[70:71]
	v_pk_fma_f32 v[8:9], v[76:77], v[58:59], v[8:9]
	v_pk_fma_f32 v[14:15], v[22:23], v[14:15], v[16:17]
	v_bfe_u32 v18, v11, 16, 1
	v_bfe_u32 v16, v15, 16, 1
	v_bfe_u32 v17, v14, 16, 1
	v_bfe_u32 v19, v10, 16, 1
	v_add3_u32 v19, v10, v19, s58
	v_add3_u32 v18, v11, v18, s58
	v_add3_u32 v10, v14, v17, s58
	v_add3_u32 v11, v15, v16, s58
	v_bfe_u32 v14, v8, 16, 1
	v_bfe_u32 v15, v9, 16, 1
	v_bfe_u32 v16, v12, 16, 1
	v_bfe_u32 v17, v13, 16, 1
	v_add3_u32 v13, v13, v17, s58
	v_add3_u32 v12, v12, v16, s58
	v_add3_u32 v9, v9, v15, s58
	v_add3_u32 v8, v8, v14, s58
	v_lshrrev_b32_e32 v8, 16, v8
	v_lshrrev_b32_e32 v9, 16, v9
	v_lshrrev_b32_e32 v12, 16, v12
	v_lshrrev_b32_e32 v13, 16, v13
	v_and_or_b32 v11, v11, s54, v13
	v_and_or_b32 v10, v10, s54, v12
	v_and_or_b32 v9, v18, s54, v9
	v_and_or_b32 v8, v19, s54, v8
	v_lshl_add_u64 v[12:13], v[56:57], 0, v[44:45]
	global_store_dwordx4 v[12:13], v[8:11], off
	v_lshl_add_u64 v[12:13], v[88:89], 0, s[42:43]
	v_lshl_add_u64 v[14:15], v[12:13], 0, v[46:47]
	v_lshl_add_u64 v[8:9], v[12:13], 0, v[28:29]
	global_load_dwordx4 v[8:11], v[8:9], off
	v_and_b32_e32 v136, 0xffffffc0, v135
	global_load_dwordx4 v[56:59], v[14:15], off
	v_lshl_add_u64 v[14:15], v[12:13], 0, v[48:49]
	global_load_dwordx4 v[46:49], v[14:15], off
	v_lshl_add_u64 v[14:15], v[12:13], 0, v[50:51]
	global_load_dwordx4 v[60:63], v[14:15], off
	v_lshl_add_u64 v[14:15], v[12:13], 0, v[52:53]
	v_lshl_add_u64 v[12:13], v[12:13], 0, v[54:55]
	global_load_dwordx4 v[50:53], v[14:15], off
	global_load_dwordx4 v[66:69], v[12:13], off
	s_nop 0
	global_load_dwordx2 v[12:13], v[32:33], off offset:448
	global_load_dwordx4 v[18:21], v[24:25], off offset:1024
	global_load_dwordx4 v[14:17], v[26:27], off offset:1024
	s_waitcnt vmcnt(0) lgkmcnt(0)
	v_cndmask_b32_e32 v82, 0, v9, vcc
	global_load_dwordx4 v[22:25], v[24:25], off offset:1040
	v_cndmask_b32_e32 v83, 0, v8, vcc
	global_load_dwordx4 v[26:29], v[26:27], off offset:1040
	v_cndmask_b32_e64 v54, 0, v57, s[4:5]
	v_cndmask_b32_e64 v56, 0, v56, s[4:5]
	v_cndmask_b32_e64 v55, 0, v47, s[6:7]
	v_cndmask_b32_e64 v57, 0, v46, s[6:7]
	v_cndmask_b32_e32 v139, 0, v11, vcc
	v_cndmask_b32_e32 v146, 0, v10, vcc
	v_cndmask_b32_e64 v151, 0, v63, s[8:9]
	v_cndmask_b32_e64 v152, 0, v62, s[8:9]
	v_cndmask_b32_e64 v157, 0, v67, s[12:13]
	v_cndmask_b32_e64 v158, 0, v66, s[12:13]
	v_lshlrev_b32_e32 v8, 16, v83
	v_lshlrev_b32_e32 v9, 16, v82
	v_lshlrev_b32_e32 v10, 16, v56
	v_lshlrev_b32_e32 v11, 16, v54
	v_lshlrev_b32_e32 v62, 16, v57
	v_lshlrev_b32_e32 v63, 16, v55
	v_readfirstlane_b32 s1, v13
	v_readfirstlane_b32 s0, v12
	v_and_b32_e32 v67, 0xffff0000, v55
	v_and_b32_e32 v66, 0xffff0000, v57
	v_and_b32_e32 v55, 0xffff0000, v54
	v_and_b32_e32 v54, 0xffff0000, v56
	v_and_b32_e32 v57, 0xffff0000, v82
	v_and_b32_e32 v56, 0xffff0000, v83
	v_cndmask_b32_e64 v147, 0, v59, s[4:5]
	v_cndmask_b32_e64 v148, 0, v58, s[4:5]
	v_cndmask_b32_e64 v58, 0, v61, s[8:9]
	v_cndmask_b32_e64 v59, 0, v60, s[8:9]
	v_lshl_add_u64 v[12:13], s[0:1], 0, v[64:65]
	v_pk_add_f32 v[8:9], v[8:9], v[10:11] neg_lo:[0,1] neg_hi:[0,1]
	v_pk_add_f32 v[56:57], v[56:57], v[54:55] neg_lo:[0,1] neg_hi:[0,1]
	v_mov_b32_e32 v82, v18
	v_mov_b32_e32 v83, v20
	v_mov_b32_e32 v20, v19
	v_cndmask_b32_e64 v155, 0, v69, s[12:13]
	v_cndmask_b32_e64 v156, 0, v68, s[12:13]
	v_lshlrev_b32_e32 v68, 16, v59
	v_lshlrev_b32_e32 v69, 16, v58
	v_and_b32_e32 v77, 0xffff0000, v58
	v_and_b32_e32 v76, 0xffff0000, v59
	v_pk_add_f32 v[58:59], v[10:11], v[62:63] neg_lo:[0,1] neg_hi:[0,1]
	v_pk_fma_f32 v[140:141], v[82:83], v[8:9], v[10:11]
	v_pk_fma_f32 v[18:19], v[20:21], v[56:57], v[54:55]
	v_pk_add_f32 v[56:57], v[62:63], v[10:11] neg_lo:[0,1] neg_hi:[0,1]
	global_load_dwordx4 v[8:11], v[12:13], off
	v_mov_b32_e32 v144, v14
	v_mov_b32_e32 v145, v16
	v_mov_b32_e32 v16, v15
	global_load_dwordx4 v[12:15], v[12:13], off offset:16
	v_cndmask_b32_e64 v60, 0, v51, s[10:11]
	v_cndmask_b32_e64 v61, 0, v50, s[10:11]
	v_pk_add_f32 v[142:143], v[66:67], v[54:55] neg_lo:[0,1] neg_hi:[0,1]
	v_lshlrev_b32_e32 v70, 16, v61
	v_lshlrev_b32_e32 v71, 16, v60
	v_and_b32_e32 v79, 0xffff0000, v60
	v_and_b32_e32 v78, 0xffff0000, v61
	v_pk_add_f32 v[60:61], v[54:55], v[66:67] neg_lo:[0,1] neg_hi:[0,1]
	v_pk_fma_f32 v[54:55], v[144:145], v[56:57], v[140:141]
	v_pk_fma_f32 v[56:57], v[16:17], v[142:143], v[18:19]
	v_pk_fma_f32 v[18:19], v[82:83], v[58:59], v[62:63]
	v_pk_add_f32 v[58:59], v[68:69], v[62:63] neg_lo:[0,1] neg_hi:[0,1]
	v_and_b32_e32 v141, 0xffff0000, v157
	v_pk_fma_f32 v[58:59], v[144:145], v[58:59], v[18:19]
	v_pk_fma_f32 v[18:19], v[20:21], v[60:61], v[66:67]
	v_pk_add_f32 v[60:61], v[76:77], v[66:67] neg_lo:[0,1] neg_hi:[0,1]
	v_and_b32_e32 v140, 0xffff0000, v158
	v_pk_fma_f32 v[60:61], v[16:17], v[60:61], v[18:19]
	v_pk_add_f32 v[18:19], v[62:63], v[68:69] neg_lo:[0,1] neg_hi:[0,1]
	v_pk_add_f32 v[62:63], v[70:71], v[68:69] neg_lo:[0,1] neg_hi:[0,1]
	v_pk_fma_f32 v[18:19], v[82:83], v[18:19], v[68:69]
	v_pk_add_f32 v[68:69], v[68:69], v[70:71] neg_lo:[0,1] neg_hi:[0,1]
	v_pk_fma_f32 v[62:63], v[144:145], v[62:63], v[18:19]
	v_pk_add_f32 v[18:19], v[66:67], v[76:77] neg_lo:[0,1] neg_hi:[0,1]
	v_pk_add_f32 v[66:67], v[78:79], v[76:77] neg_lo:[0,1] neg_hi:[0,1]
	v_pk_fma_f32 v[18:19], v[20:21], v[18:19], v[76:77]
	v_pk_fma_f32 v[68:69], v[82:83], v[68:69], v[70:71]
	v_pk_fma_f32 v[66:67], v[16:17], v[66:67], v[18:19]
	v_lshlrev_b32_e32 v19, 16, v157
	v_lshlrev_b32_e32 v18, 16, v158
	v_pk_add_f32 v[18:19], v[18:19], v[70:71] neg_lo:[0,1] neg_hi:[0,1]
	v_cndmask_b32_e64 v149, 0, v49, s[6:7]
	v_pk_fma_f32 v[68:69], v[144:145], v[18:19], v[68:69]
	v_pk_add_f32 v[18:19], v[76:77], v[78:79] neg_lo:[0,1] neg_hi:[0,1]
	v_cndmask_b32_e64 v150, 0, v48, s[6:7]
	v_lshlrev_b32_e32 v74, 16, v146
	v_lshlrev_b32_e32 v75, 16, v139
	v_lshlrev_b32_e32 v72, 16, v148
	v_lshlrev_b32_e32 v73, 16, v147
	v_pk_fma_f32 v[18:19], v[20:21], v[18:19], v[78:79]
	v_pk_add_f32 v[20:21], v[140:141], v[78:79] neg_lo:[0,1] neg_hi:[0,1]
	v_and_b32_e32 v77, 0xffff0000, v147
	v_and_b32_e32 v76, 0xffff0000, v148
	v_and_b32_e32 v141, 0xffff0000, v139
	v_and_b32_e32 v140, 0xffff0000, v146
	v_lshlrev_b32_e32 v80, 16, v150
	v_lshlrev_b32_e32 v81, 16, v149
	v_pk_fma_f32 v[70:71], v[16:17], v[20:21], v[18:19]
	v_and_b32_e32 v17, 0xffff0000, v149
	v_and_b32_e32 v16, 0xffff0000, v150
	v_pk_add_f32 v[74:75], v[74:75], v[72:73] neg_lo:[0,1] neg_hi:[0,1]
	v_pk_add_f32 v[140:141], v[140:141], v[76:77] neg_lo:[0,1] neg_hi:[0,1]
	s_waitcnt vmcnt(0) lgkmcnt(0)
	v_mov_b32_e32 v142, v22
	v_mov_b32_e32 v143, v24
	v_mov_b32_e32 v24, v23
	v_lshlrev_b32_e32 v86, 16, v152
	v_lshlrev_b32_e32 v87, 16, v151
	v_pk_add_f32 v[78:79], v[72:73], v[80:81] neg_lo:[0,1] neg_hi:[0,1]
	v_pk_add_f32 v[82:83], v[76:77], v[16:17] neg_lo:[0,1] neg_hi:[0,1]
	v_pk_fma_f32 v[74:75], v[142:143], v[74:75], v[72:73]
	v_pk_fma_f32 v[22:23], v[24:25], v[140:141], v[76:77]
	v_pk_add_f32 v[72:73], v[80:81], v[72:73] neg_lo:[0,1] neg_hi:[0,1]
	v_pk_add_f32 v[76:77], v[16:17], v[76:77] neg_lo:[0,1] neg_hi:[0,1]
	v_mov_b32_e32 v140, v26
	v_mov_b32_e32 v141, v28
	v_mov_b32_e32 v28, v27
	v_and_b32_e32 v19, 0xffff0000, v151
	v_and_b32_e32 v18, 0xffff0000, v152
	v_pk_fma_f32 v[72:73], v[140:141], v[72:73], v[74:75]
	v_pk_fma_f32 v[74:75], v[28:29], v[76:77], v[22:23]
	v_pk_fma_f32 v[22:23], v[142:143], v[78:79], v[80:81]
	v_pk_add_f32 v[26:27], v[86:87], v[80:81] neg_lo:[0,1] neg_hi:[0,1]
	v_cndmask_b32_e64 v153, 0, v53, s[10:11]
	v_cndmask_b32_e64 v154, 0, v52, s[10:11]
	v_pk_fma_f32 v[76:77], v[140:141], v[26:27], v[22:23]
	v_pk_fma_f32 v[22:23], v[24:25], v[82:83], v[16:17]
	v_pk_add_f32 v[26:27], v[18:19], v[16:17] neg_lo:[0,1] neg_hi:[0,1]
	v_lshlrev_b32_e32 v84, 16, v154
	v_lshlrev_b32_e32 v85, 16, v153
	v_pk_fma_f32 v[78:79], v[28:29], v[26:27], v[22:23]
	v_pk_add_f32 v[22:23], v[80:81], v[86:87] neg_lo:[0,1] neg_hi:[0,1]
	v_and_b32_e32 v21, 0xffff0000, v153
	v_and_b32_e32 v20, 0xffff0000, v154
	v_pk_fma_f32 v[22:23], v[142:143], v[22:23], v[86:87]
	v_pk_add_f32 v[26:27], v[84:85], v[86:87] neg_lo:[0,1] neg_hi:[0,1]
	v_pk_add_f32 v[16:17], v[16:17], v[18:19] neg_lo:[0,1] neg_hi:[0,1]
	v_pk_fma_f32 v[80:81], v[140:141], v[26:27], v[22:23]
	v_pk_fma_f32 v[16:17], v[24:25], v[16:17], v[18:19]
	v_pk_add_f32 v[22:23], v[20:21], v[18:19] neg_lo:[0,1] neg_hi:[0,1]
	v_and_b32_e32 v27, 0xffff0000, v155
	v_pk_fma_f32 v[82:83], v[28:29], v[22:23], v[16:17]
	v_pk_add_f32 v[16:17], v[86:87], v[84:85] neg_lo:[0,1] neg_hi:[0,1]
	v_lshlrev_b32_e32 v23, 16, v155
	v_pk_fma_f32 v[86:87], v[142:143], v[16:17], v[84:85]
	v_mov_b32_e32 v16, v8
	v_mov_b32_e32 v17, v10
	v_mov_b32_e32 v10, v9
	v_pk_mul_f32 v[142:143], v[16:17], v[54:55]
	v_pk_mul_f32 v[144:145], v[56:57], v[10:11]
	v_mov_b32_e32 v8, v143
	v_mov_b32_e32 v9, v145
	v_pk_mul_f32 v[146:147], v[8:9], v[8:9]
	v_mov_b32_e32 v8, v12
	v_mov_b32_e32 v9, v14
	v_mov_b32_e32 v14, v13
	v_mul_f32_e32 v139, v142, v142
	v_pk_mul_f32 v[148:149], v[72:73], v[8:9]
	v_pk_mul_f32 v[12:13], v[74:75], v[14:15]
	v_fmac_f32_e32 v139, v144, v144
	v_mov_b32_e32 v150, v148
	v_mov_b32_e32 v151, v12
	v_add_f32_e32 v139, v139, v146
	v_pk_mul_f32 v[150:151], v[150:151], v[150:151]
	v_add_f32_e32 v139, v139, v147
	v_mov_b32_e32 v152, v149
	v_mov_b32_e32 v153, v13
	v_add_f32_e32 v139, v139, v150
	v_pk_mul_f32 v[152:153], v[152:153], v[152:153]
	v_add_f32_e32 v139, v139, v151
	v_add_f32_e32 v139, v139, v152
	v_add_f32_e32 v139, v139, v153
	v_lshlrev_b32_e32 v22, 16, v156
	v_pk_add_f32 v[22:23], v[22:23], v[84:85] neg_lo:[0,1] neg_hi:[0,1]
	v_add_f32_dpp v139, v139, v139 quad_perm:[1,0,3,2] row_mask:0xf bank_mask:0xf bound_ctrl:1
	v_pk_fma_f32 v[84:85], v[140:141], v[22:23], v[86:87]
	v_and_b32_e32 v26, 0xffff0000, v156
	v_add_f32_dpp v139, v139, v139 quad_perm:[2,3,0,1] row_mask:0xf bank_mask:0xf bound_ctrl:1
	v_pk_add_f32 v[18:19], v[18:19], v[20:21] neg_lo:[0,1] neg_hi:[0,1]
	v_pk_mul_f32 v[140:141], v[78:79], v[14:15]
	v_add_f32_dpp v139, v139, v139 row_half_mirror row_mask:0xf bank_mask:0xf bound_ctrl:1
	v_mul_f32_e32 v146, 0x4f800000, v139
	v_cmp_gt_f32_e32 vcc, s69, v139
	v_pk_fma_f32 v[18:19], v[24:25], v[18:19], v[20:21]
	v_pk_add_f32 v[20:21], v[26:27], v[20:21] neg_lo:[0,1] neg_hi:[0,1]
	v_cndmask_b32_e32 v139, v139, v146, vcc
	v_sqrt_f32_e32 v146, v139
	v_lshl_add_u64 v[52:53], v[88:89], 0, s[44:45]
	v_lshl_add_u64 v[46:47], v[52:53], 0, v[38:39]
	v_lshl_add_u64 v[48:49], v[52:53], 0, v[40:41]
	v_add_u32_e32 v22, -1, v146
	v_fma_f32 v23, -v22, v146, v139
	v_cmp_ge_f32_e64 s[0:1], 0, v23
	v_add_u32_e32 v23, 1, v146
	v_fma_f32 v86, -v23, v146, v139
	v_cndmask_b32_e64 v22, v146, v22, s[0:1]
	v_cmp_lt_f32_e64 s[0:1], 0, v86
	v_pk_fma_f32 v[86:87], v[28:29], v[20:21], v[18:19]
	v_pk_mul_f32 v[28:29], v[76:77], v[8:9]
	v_cndmask_b32_e64 v22, v22, v23, s[0:1]
	v_mul_f32_e32 v23, 0x37800000, v22
	v_cndmask_b32_e32 v22, v22, v23, vcc
	v_cmp_class_f32_e32 vcc, v139, v128
	v_lshl_add_u64 v[50:51], v[52:53], 0, v[42:43]
	v_lshl_add_u64 v[52:53], v[52:53], 0, v[44:45]
	v_cndmask_b32_e32 v22, v22, v139, vcc
	v_max_f32_e32 v22, 0x2b8cbccc, v22
	v_div_scale_f32 v23, s[0:1], v22, v22, 1.0
	v_rcp_f32_e32 v139, v23
	v_mul_f32_e32 v156, v36, v5
	v_mul_f32_e32 v157, v31, v6
	v_mul_f32_e32 v158, v37, v7
	v_fma_f32 v18, -v23, v139, 1.0
	v_fmac_f32_e32 v139, v18, v139
	v_div_scale_f32 v18, vcc, 1.0, v22, 1.0
	v_mul_f32_e32 v19, v18, v139
	v_fma_f32 v20, -v23, v19, v18
	v_fmac_f32_e32 v19, v20, v139
	v_fma_f32 v18, -v23, v19, v18
	v_div_fmas_f32 v18, v18, v139, v19
	v_div_fixup_f32 v18, v18, v22, 1.0
	v_pk_mul_f32 v[20:21], v[142:143], v[18:19] op_sel_hi:[1,0]
	v_pk_mul_f32 v[22:23], v[148:149], v[18:19] op_sel_hi:[1,0]
	v_bfe_u32 v19, v20, 16, 1
	v_bfe_u32 v24, v21, 16, 1
	v_bfe_u32 v25, v22, 16, 1
	v_bfe_u32 v26, v23, 16, 1
	v_add3_u32 v23, v23, v26, s58
	v_add3_u32 v22, v22, v25, s58
	v_add3_u32 v21, v21, v24, s58
	v_add3_u32 v19, v20, v19, s58
	v_pk_mul_f32 v[24:25], v[58:59], v[16:17]
	v_pk_mul_f32 v[26:27], v[60:61], v[10:11]
	v_lshrrev_b32_e32 v139, 16, v19
	v_lshrrev_b32_e32 v19, 16, v21
	v_mov_b32_e32 v20, v27
	v_mov_b32_e32 v21, v25
	v_mul_f32_e32 v148, v24, v24
	v_pk_mul_f32 v[20:21], v[20:21], v[20:21]
	v_fmac_f32_e32 v148, v26, v26
	v_mov_b32_e32 v142, v140
	v_mov_b32_e32 v143, v28
	v_add_f32_e32 v21, v21, v148
	v_pk_mul_f32 v[142:143], v[142:143], v[142:143]
	v_add_f32_e32 v20, v20, v21
	v_lshrrev_b32_e32 v146, 16, v22
	v_lshrrev_b32_e32 v147, 16, v23
	v_pk_mul_f32 v[22:23], v[144:145], v[18:19] op_sel_hi:[1,0]
	v_mov_b32_e32 v144, v141
	v_mov_b32_e32 v145, v29
	v_add_f32_e32 v20, v143, v20
	v_pk_mul_f32 v[144:145], v[144:145], v[144:145]
	v_add_f32_e32 v20, v142, v20
	v_add_f32_e32 v20, v145, v20
	v_add_f32_e32 v20, v144, v20
	v_pk_mul_f32 v[12:13], v[12:13], v[18:19] op_sel_hi:[1,0]
	v_and_or_b32 v19, v23, s54, v19
	v_add_f32_dpp v20, v20, v20 quad_perm:[1,0,3,2] row_mask:0xf bank_mask:0xf bound_ctrl:1
	v_lshlrev_b64 v[36:37], 11, v[94:95]
	v_lshl_add_u64 v[36:37], s[52:53], 0, v[36:37]
	v_add_f32_dpp v20, v20, v20 quad_perm:[2,3,0,1] row_mask:0xf bank_mask:0xf bound_ctrl:1
	v_lshl_add_u64 v[180:181], v[36:37], 0, v[34:35]
	v_or_b32_e32 v36, 3, v137
	v_add_f32_dpp v20, v20, v20 row_half_mirror row_mask:0xf bank_mask:0xf bound_ctrl:1
	v_mul_f32_e32 v21, 0x4f800000, v20
	v_cmp_gt_f32_e32 vcc, s69, v20
	v_mul_lo_u32 v36, v36, s68
	v_add_u32_e32 v119, v64, v36
	v_cndmask_b32_e32 v142, v20, v21, vcc
	v_sqrt_f32_e32 v143, v142
	v_and_or_b32 v20, v12, s54, v146
	v_and_or_b32 v21, v13, s54, v147
	v_lshlrev_b64 v[36:37], 11, v[96:97]
	v_add_u32_e32 v12, -1, v143
	v_fma_f32 v13, -v12, v143, v142
	v_cmp_ge_f32_e64 s[0:1], 0, v13
	v_add_u32_e32 v13, 1, v143
	v_fma_f32 v18, -v13, v143, v142
	v_cndmask_b32_e64 v12, v143, v12, s[0:1]
	v_cmp_lt_f32_e64 s[0:1], 0, v18
	v_and_or_b32 v18, v22, s54, v139
	global_store_dwordx4 v[46:47], v[18:21], off
	v_cndmask_b32_e64 v12, v12, v13, s[0:1]
	v_mul_f32_e32 v13, 0x37800000, v12
	v_cndmask_b32_e32 v12, v12, v13, vcc
	v_cmp_class_f32_e32 vcc, v142, v128
	v_lshl_add_u64 v[36:37], s[52:53], 0, v[36:37]
	v_lshl_add_u64 v[182:183], v[36:37], 0, v[34:35]
	v_cndmask_b32_e32 v12, v12, v142, vcc
	v_max_f32_e32 v12, 0x2b8cbccc, v12
	v_div_scale_f32 v13, s[0:1], v12, v12, 1.0
	v_rcp_f32_e32 v142, v13
	v_mul_f32_e32 v121, v156, v56
	v_mul_f32_e32 v122, v157, v55
	v_mul_f32_e32 v123, v158, v57
	v_fma_f32 v18, -v13, v142, 1.0
	v_fmac_f32_e32 v142, v18, v142
	v_div_scale_f32 v18, vcc, 1.0, v12, 1.0
	v_mul_f32_e32 v19, v18, v142
	v_fma_f32 v20, -v13, v19, v18
	v_fmac_f32_e32 v19, v20, v142
	v_fma_f32 v13, -v13, v19, v18
	v_div_fmas_f32 v13, v13, v142, v19
	v_div_fixup_f32 v12, v13, v12, 1.0
	v_pk_mul_f32 v[18:19], v[24:25], v[12:13] op_sel_hi:[1,0]
	v_pk_mul_f32 v[20:21], v[28:29], v[12:13] op_sel_hi:[1,0]
	v_bfe_u32 v13, v18, 16, 1
	v_bfe_u32 v22, v19, 16, 1
	v_bfe_u32 v23, v20, 16, 1
	v_bfe_u32 v24, v21, 16, 1
	v_add3_u32 v21, v21, v24, s58
	v_add3_u32 v20, v20, v23, s58
	v_add3_u32 v19, v19, v22, s58
	v_add3_u32 v13, v18, v13, s58
	v_pk_mul_f32 v[22:23], v[16:17], v[62:63]
	v_pk_mul_f32 v[24:25], v[66:67], v[10:11]
	v_lshrrev_b32_e32 v139, 16, v13
	v_lshrrev_b32_e32 v146, 16, v19
	v_lshrrev_b32_e32 v147, 16, v20
	v_lshrrev_b32_e32 v148, 16, v21
	v_pk_mul_f32 v[18:19], v[26:27], v[12:13] op_sel_hi:[1,0]
	v_mov_b32_e32 v20, v25
	v_mov_b32_e32 v21, v23
	v_mul_f32_e32 v13, v22, v22
	v_pk_mul_f32 v[20:21], v[20:21], v[20:21]
	v_pk_mul_f32 v[26:27], v[80:81], v[8:9]
	v_pk_mul_f32 v[28:29], v[82:83], v[14:15]
	v_fmac_f32_e32 v13, v24, v24
	v_mov_b32_e32 v142, v28
	v_mov_b32_e32 v143, v26
	v_add_f32_e32 v13, v21, v13
	v_pk_mul_f32 v[142:143], v[142:143], v[142:143]
	v_add_f32_e32 v13, v20, v13
	v_mov_b32_e32 v144, v29
	v_mov_b32_e32 v145, v27
	v_add_f32_e32 v13, v143, v13
	v_pk_mul_f32 v[144:145], v[144:145], v[144:145]
	v_add_f32_e32 v13, v142, v13
	v_add_f32_e32 v13, v145, v13
	v_add_f32_e32 v13, v144, v13
	v_and_or_b32 v19, v19, s54, v146
	v_and_or_b32 v18, v18, s54, v139
	v_add_f32_dpp v13, v13, v13 quad_perm:[1,0,3,2] row_mask:0xf bank_mask:0xf bound_ctrl:1
	v_pk_mul_f32 v[16:17], v[16:17], v[68:69]
	v_pk_mul_f32 v[14:15], v[86:87], v[14:15]
	v_add_f32_dpp v13, v13, v13 quad_perm:[2,3,0,1] row_mask:0xf bank_mask:0xf bound_ctrl:1
	v_mul_f32_e32 v124, v163, v58
	v_mul_f32_e32 v125, v168, v60
	v_add_f32_dpp v13, v13, v13 row_half_mirror row_mask:0xf bank_mask:0xf bound_ctrl:1
	v_mul_f32_e32 v20, 0x4f800000, v13
	v_cmp_gt_f32_e32 vcc, s69, v13
	v_mul_f32_e32 v137, v169, v59
	v_mul_f32_e32 v156, v176, v82
	v_cndmask_b32_e32 v142, v13, v20, vcc
	v_sqrt_f32_e32 v143, v142
	v_pk_mul_f32 v[12:13], v[140:141], v[12:13] op_sel_hi:[1,0]
	v_mul_f32_e32 v157, v177, v81
	v_and_or_b32 v20, v12, s54, v147
	v_add_u32_e32 v12, -1, v143
	v_and_or_b32 v21, v13, s54, v148
	v_fma_f32 v13, -v12, v143, v142
	v_cmp_ge_f32_e64 s[0:1], 0, v13
	v_add_u32_e32 v13, 1, v143
	v_fma_f32 v140, -v13, v143, v142
	v_cndmask_b32_e64 v12, v143, v12, s[0:1]
	v_cmp_lt_f32_e64 s[0:1], 0, v140
	global_store_dwordx4 v[48:49], v[18:21], off
	v_mul_f32_e32 v158, v178, v83
	v_cndmask_b32_e64 v12, v12, v13, s[0:1]
	v_mul_f32_e32 v13, 0x37800000, v12
	v_cndmask_b32_e32 v12, v12, v13, vcc
	v_cmp_class_f32_e32 vcc, v142, v128
	s_nop 1
	v_cndmask_b32_e32 v12, v12, v142, vcc
	v_max_f32_e32 v12, 0x2b8cbccc, v12
	v_div_scale_f32 v13, s[0:1], v12, v12, 1.0
	v_rcp_f32_e32 v140, v13
	s_nop 0
	v_fma_f32 v18, -v13, v140, 1.0
	v_fmac_f32_e32 v140, v18, v140
	v_div_scale_f32 v18, vcc, 1.0, v12, 1.0
	v_mul_f32_e32 v19, v18, v140
	v_fma_f32 v20, -v13, v19, v18
	v_fmac_f32_e32 v19, v20, v140
	v_fma_f32 v13, -v13, v19, v18
	v_div_fmas_f32 v13, v13, v140, v19
	v_div_fixup_f32 v12, v13, v12, 1.0
	v_pk_mul_f32 v[20:21], v[26:27], v[12:13] op_sel_hi:[1,0]
	v_pk_mul_f32 v[18:19], v[22:23], v[12:13] op_sel_hi:[1,0]
	v_bfe_u32 v23, v20, 16, 1
	v_bfe_u32 v26, v21, 16, 1
	v_add3_u32 v21, v21, v26, s58
	v_add3_u32 v20, v20, v23, s58
	v_lshrrev_b32_e32 v27, 16, v20
	v_lshrrev_b32_e32 v139, 16, v21
	v_pk_mul_f32 v[20:21], v[10:11], v[70:71]
	v_bfe_u32 v22, v19, 16, 1
	v_mov_b32_e32 v10, v21
	v_mov_b32_e32 v11, v17
	v_mul_f32_e32 v140, v16, v16
	v_bfe_u32 v13, v18, 16, 1
	v_add3_u32 v19, v19, v22, s58
	v_pk_mul_f32 v[10:11], v[10:11], v[10:11]
	v_pk_mul_f32 v[22:23], v[84:85], v[8:9]
	v_fmac_f32_e32 v140, v20, v20
	v_add3_u32 v13, v18, v13, s58
	v_mov_b32_e32 v8, v14
	v_mov_b32_e32 v9, v22
	v_add_f32_e32 v11, v11, v140
	v_lshrrev_b32_e32 v13, 16, v13
	v_pk_mul_f32 v[8:9], v[8:9], v[8:9]
	v_add_f32_e32 v10, v10, v11
	v_lshrrev_b32_e32 v26, 16, v19
	v_pk_mul_f32 v[18:19], v[24:25], v[12:13] op_sel_hi:[1,0]
	v_mov_b32_e32 v24, v15
	v_mov_b32_e32 v25, v23
	v_add_f32_e32 v9, v9, v10
	v_pk_mul_f32 v[24:25], v[24:25], v[24:25]
	v_add_f32_e32 v8, v8, v9
	v_add_f32_e32 v8, v25, v8
	v_add_f32_e32 v8, v24, v8
	s_nop 1
	v_add_f32_dpp v8, v8, v8 quad_perm:[1,0,3,2] row_mask:0xf bank_mask:0xf bound_ctrl:1
	s_nop 1
	v_add_f32_dpp v8, v8, v8 quad_perm:[2,3,0,1] row_mask:0xf bank_mask:0xf bound_ctrl:1
	s_nop 1
	v_add_f32_dpp v8, v8, v8 row_half_mirror row_mask:0xf bank_mask:0xf bound_ctrl:1
	v_mul_f32_e32 v9, 0x4f800000, v8
	v_cmp_gt_f32_e32 vcc, s69, v8
	s_nop 1
	v_cndmask_b32_e32 v24, v8, v9, vcc
	v_sqrt_f32_e32 v25, v24
	v_pk_mul_f32 v[8:9], v[28:29], v[12:13] op_sel_hi:[1,0]
	s_nop 0
	v_and_or_b32 v10, v8, s54, v27
	v_add_u32_e32 v8, -1, v25
	v_and_or_b32 v11, v9, s54, v139
	v_fma_f32 v9, -v8, v25, v24
	v_cmp_ge_f32_e64 s[0:1], 0, v9
	v_add_u32_e32 v9, 1, v25
	v_fma_f32 v12, -v9, v25, v24
	v_cndmask_b32_e64 v8, v25, v8, s[0:1]
	v_cmp_lt_f32_e64 s[0:1], 0, v12
	v_mul_f32_e32 v139, v4, v30
	v_mul_f32_e32 v120, v139, v54
	v_cndmask_b32_e64 v8, v8, v9, s[0:1]
	v_mul_f32_e32 v9, 0x37800000, v8
	v_cndmask_b32_e32 v8, v8, v9, vcc
	v_cmp_class_f32_e32 vcc, v24, v128
	v_and_or_b32 v9, v19, s54, v26
	v_mul_f32_e32 v139, v110, v62
	v_cndmask_b32_e32 v8, v8, v24, vcc
	v_max_f32_e32 v12, 0x2b8cbccc, v8
	v_div_scale_f32 v24, s[0:1], v12, v12, 1.0
	v_rcp_f32_e32 v25, v24
	v_and_or_b32 v8, v18, s54, v13
	global_store_dwordx4 v[50:51], v[8:11], off
	s_nop 1
	v_fma_f32 v8, -v24, v25, 1.0
	v_fmac_f32_e32 v25, v8, v25
	v_div_scale_f32 v8, vcc, 1.0, v12, 1.0
	v_mul_f32_e32 v9, v8, v25
	v_fma_f32 v10, -v24, v9, v8
	v_fmac_f32_e32 v9, v10, v25
	v_fma_f32 v8, -v24, v9, v8
	v_div_fmas_f32 v8, v8, v25, v9
	v_div_fixup_f32 v8, v8, v12, 1.0
	v_pk_mul_f32 v[10:11], v[16:17], v[8:9] op_sel_hi:[1,0]
	v_pk_mul_f32 v[12:13], v[22:23], v[8:9] op_sel_hi:[1,0]
	v_bfe_u32 v9, v10, 16, 1
	v_bfe_u32 v16, v11, 16, 1
	v_bfe_u32 v17, v12, 16, 1
	v_bfe_u32 v18, v13, 16, 1
	v_add3_u32 v13, v13, v18, s58
	v_add3_u32 v12, v12, v17, s58
	v_add3_u32 v11, v11, v16, s58
	v_add3_u32 v9, v10, v9, s58
	v_lshrrev_b32_e32 v16, 16, v9
	v_lshrrev_b32_e32 v17, 16, v11
	v_lshrrev_b32_e32 v10, 16, v12
	v_lshrrev_b32_e32 v11, 16, v13
	v_pk_mul_f32 v[12:13], v[20:21], v[8:9] op_sel_hi:[1,0]
	v_pk_mul_f32 v[8:9], v[14:15], v[8:9] op_sel_hi:[1,0]
	v_lshlrev_b64 v[24:25], 11, v[90:91]
	v_and_or_b32 v11, v9, s54, v11
	v_and_or_b32 v10, v8, s54, v10
	v_and_or_b32 v9, v13, s54, v17
	v_and_or_b32 v8, v12, s54, v16
	global_store_dwordx4 v[52:53], v[8:11], off
	s_waitcnt lgkmcnt(0)
	s_barrier
	v_mov_b32_e32 v8, v65
	v_lshl_add_u64 v[24:25], s[52:53], 0, v[24:25]
	v_mbcnt_lo_u32_b32 v8, -1, v8
	v_mbcnt_hi_u32_b32 v10, -1, v8
	v_and_b32_e32 v20, 31, v10
	v_or_b32_e32 v8, v20, v136
	v_ashrrev_i32_e32 v9, 31, v8
	v_ashrrev_i32_e32 v10, 2, v10
	v_lshlrev_b64 v[8:9], 8, v[8:9]
	v_and_b32_e32 v12, -8, v10
	v_lshl_add_u64 v[8:9], s[52:53], 0, v[8:9]
	v_ashrrev_i32_e32 v13, 31, v12
	v_lshl_add_u64 v[14:15], v[12:13], 1, v[8:9]
	v_add_co_u32_e32 v8, vcc, s70, v14
	v_lshl_add_u64 v[166:167], v[14:15], 0, s[46:47]
	s_nop 0
	v_addc_co_u32_e32 v9, vcc, 0, v15, vcc
	v_add_co_u32_e32 v164, vcc, s71, v14
	global_load_dwordx4 v[8:11], v[8:9], off
	s_nop 0
	v_addc_co_u32_e32 v165, vcc, 0, v15, vcc
	global_load_dwordx4 v[16:19], v[164:165], off
	global_load_dwordx4 v[140:143], v[166:167], off offset:32
	global_load_dwordx4 v[144:147], v[164:165], off offset:32
	global_load_dwordx4 v[148:151], v[166:167], off offset:64
	global_load_dwordx4 v[98:101], v[166:167], off offset:96
	global_load_dwordx4 v[152:155], v[164:165], off offset:64
	global_load_dwordx4 v[102:105], v[164:165], off offset:96
	v_lshlrev_b32_e32 v0, 1, v12
	v_mad_u32_u24 v191, v20, s63, v0
	ds_read_b128 v[20:23], v191
	ds_read_b128 v[106:109], v191 offset:32
	v_lshrrev_b32_e32 v0, 3, v135
	v_and_b32_e32 v0, 4, v0
	v_mul_u32_u24_e32 v0, 0x410, v0
	v_lshl_add_u64 v[114:115], v[24:25], 0, v[34:35]
	v_lshlrev_b64 v[24:25], 11, v[92:93]
	v_lshl_add_u32 v192, v1, 2, v0
	v_mul_lo_u32 v0, v138, s68
	v_lshl_add_u64 v[24:25], s[52:53], 0, v[24:25]
	v_add_u32_e32 v118, v64, v0
	s_waitcnt vmcnt(0) lgkmcnt(0)
	v_mfma_f32_32x32x16_bf16 v[0:15], v[20:23], v[8:11], 0
	v_lshl_add_u64 v[116:117], v[24:25], 0, v[34:35]
	ds_read_b128 v[34:37], v191 offset:64
	v_mul_f32_e32 v138, v170, v61
	v_mfma_f32_32x32x16_bf16 v[16:31], v[20:23], v[16:19], 0
	v_mfma_f32_32x32x16_bf16 v[0:15], v[106:109], v[140:143], v[0:15]
	v_mul_f32_e32 v140, v112, v66
	v_mul_f32_e32 v141, v111, v63
	v_mul_f32_e32 v142, v113, v67
	v_mul_f32_e32 v143, v179, v68
	v_mfma_f32_32x32x16_bf16 v[16:31], v[106:109], v[144:147], v[16:31]
	ds_read_b128 v[106:109], v191 offset:96
	v_mul_f32_e32 v144, v184, v70
	v_mul_f32_e32 v145, v185, v69
	v_mul_f32_e32 v146, v186, v71
	v_mul_f32_e32 v147, v159, v72
	v_mul_f32_e32 v159, v187, v84
	s_waitcnt lgkmcnt(1)
	v_mfma_f32_32x32x16_bf16 v[0:15], v[34:37], v[148:151], v[0:15]
	v_mul_f32_e32 v148, v160, v74
	v_mul_f32_e32 v149, v161, v73
	v_mul_f32_e32 v150, v162, v75
	v_mul_f32_e32 v151, v171, v76
	v_mul_f32_e32 v160, v188, v86
	v_mul_f32_e32 v161, v189, v85
	v_mul_f32_e32 v162, v190, v87
	v_mfma_f32_32x32x16_bf16 v[16:31], v[34:37], v[152:155], v[16:31]
	v_mul_f32_e32 v152, v172, v78
	v_mul_f32_e32 v153, v173, v77
	v_mul_f32_e32 v154, v174, v79
	v_mul_f32_e32 v155, v175, v80
	s_waitcnt lgkmcnt(0)
	v_mfma_f32_32x32x16_bf16 v[0:15], v[106:109], v[98:101], v[0:15]
	v_mfma_f32_32x32x16_bf16 v[16:31], v[106:109], v[102:105], v[16:31]
	global_load_dwordx4 v[34:37], v[166:167], off offset:128
	global_load_dwordx4 v[98:101], v[164:165], off offset:128
	ds_read_b128 v[102:105], v191 offset:128
	ds_read_b128 v[110:113], v191 offset:160
	global_load_dwordx4 v[106:109], v[166:167], off offset:160
	s_waitcnt vmcnt(0) lgkmcnt(0)
	v_mfma_f32_32x32x16_bf16 v[0:15], v[102:105], v[34:37], v[0:15]
	global_load_dwordx4 v[34:37], v[164:165], off offset:160
	v_mfma_f32_32x32x16_bf16 v[16:31], v[102:105], v[98:101], v[16:31]
	global_load_dwordx4 v[98:101], v[166:167], off offset:192
	global_load_dwordx4 v[102:105], v[164:165], off offset:192
	v_mfma_f32_32x32x16_bf16 v[0:15], v[110:113], v[106:109], v[0:15]
	ds_read_b128 v[106:109], v191 offset:192
	s_waitcnt vmcnt(0) lgkmcnt(0)
	v_mfma_f32_32x32x16_bf16 v[16:31], v[110:113], v[34:37], v[16:31]
	global_load_dwordx4 v[34:37], v[166:167], off offset:224
	ds_read_b128 v[110:113], v191 offset:224
	v_mfma_f32_32x32x16_bf16 v[0:15], v[106:109], v[98:101], v[0:15]
	global_load_dwordx4 v[98:101], v[164:165], off offset:224
	v_mfma_f32_32x32x16_bf16 v[16:31], v[106:109], v[102:105], v[16:31]
	s_waitcnt vmcnt(0) lgkmcnt(0)
	v_mfma_f32_32x32x16_bf16 v[0:15], v[110:113], v[34:37], v[0:15]
	v_mfma_f32_32x32x16_bf16 v[16:31], v[110:113], v[98:101], v[16:31]
	v_add_u32_e32 v163, 0x6000, v192
	v_add_u32_e32 v164, 0x6400, v192
	v_add_u32_e32 v165, 0x6800, v192
	v_add_u32_e32 v166, 0x6c00, v192
	v_add_u32_e32 v167, 0x8000, v192
	v_add_u32_e32 v168, 0x8400, v192
	v_add_u32_e32 v169, 0x8800, v192
	v_add_u32_e32 v170, 0x8c00, v192
	v_add_u32_e32 v171, 0xa000, v192
	v_add_u32_e32 v172, 0xa400, v192
	v_add_u32_e32 v173, 0xa800, v192
	v_add_u32_e32 v174, 0xac00, v192
	v_add_u32_e32 v175, 0xc200, v192
	v_add_u32_e32 v176, 0xc600, v192
	v_add_u32_e32 v177, 0xca00, v192
	v_add_u32_e32 v178, 0xce00, v192
	ds_write2_b32 v163, v0, v16 offset0:128 offset1:160
	ds_write2_b32 v164, v1, v17 offset0:132 offset1:164
	ds_write2_b32 v165, v2, v18 offset0:136 offset1:168
	ds_write2_b32 v166, v3, v19 offset0:140 offset1:172
	ds_write2_b32 v167, v4, v20 offset0:160 offset1:192
	ds_write2_b32 v168, v5, v21 offset0:164 offset1:196
	ds_write2_b32 v169, v6, v22 offset0:168 offset1:200
	ds_write2_b32 v170, v7, v23 offset0:172 offset1:204
	ds_write2_b32 v171, v8, v24 offset0:192 offset1:224
	ds_write2_b32 v172, v9, v25 offset0:196 offset1:228
	ds_write2_b32 v173, v10, v26 offset0:200 offset1:232
	ds_write2_b32 v174, v11, v27 offset0:204 offset1:236
	ds_write2_b32 v175, v12, v28 offset0:96 offset1:128
	ds_write2_b32 v176, v13, v29 offset0:100 offset1:132
	ds_write2_b32 v177, v14, v30 offset0:104 offset1:136
	ds_write2_b32 v178, v15, v31 offset0:108 offset1:140
	s_waitcnt lgkmcnt(0)
	s_barrier
	ds_read_b128 v[0:3], v118 offset:25088
	ds_read_b128 v[4:7], v118 offset:25104
	s_add_u32 s77, s52, 0x1b0d7900
	s_addc_u32 s78, s53, 0
	s_add_u32 s79, s52, 0x1d4d7900
	s_waitcnt lgkmcnt(1)
	v_and_b32_sdwa v8, v2, v134 dst_sel:DWORD dst_unused:UNUSED_PAD src0_sel:WORD_1 src1_sel:DWORD
	v_and_b32_sdwa v9, v0, v134 dst_sel:DWORD dst_unused:UNUSED_PAD src0_sel:WORD_1 src1_sel:DWORD
	v_add3_u32 v2, v2, v8, s58
	v_and_b32_sdwa v8, v3, v134 dst_sel:DWORD dst_unused:UNUSED_PAD src0_sel:WORD_1 src1_sel:DWORD
	v_add3_u32 v0, v0, v9, s58
	v_and_b32_sdwa v9, v1, v134 dst_sel:DWORD dst_unused:UNUSED_PAD src0_sel:WORD_1 src1_sel:DWORD
	v_add3_u32 v3, v3, v8, s58
	v_add3_u32 v1, v1, v9, s58
	v_and_b32_e32 v3, 0xffff0000, v3
	v_and_b32_e32 v8, 0xffff0000, v1
	v_or_b32_sdwa v1, v3, v2 dst_sel:DWORD dst_unused:UNUSED_PAD src0_sel:DWORD src1_sel:WORD_1
	s_waitcnt lgkmcnt(0)
	v_and_b32_sdwa v2, v6, v134 dst_sel:DWORD dst_unused:UNUSED_PAD src0_sel:WORD_1 src1_sel:DWORD
	v_and_b32_sdwa v3, v4, v134 dst_sel:DWORD dst_unused:UNUSED_PAD src0_sel:WORD_1 src1_sel:DWORD
	v_add3_u32 v4, v4, v3, s58
	v_add3_u32 v2, v6, v2, s58
	v_and_b32_sdwa v3, v7, v134 dst_sel:DWORD dst_unused:UNUSED_PAD src0_sel:WORD_1 src1_sel:DWORD
	v_and_b32_sdwa v6, v5, v134 dst_sel:DWORD dst_unused:UNUSED_PAD src0_sel:WORD_1 src1_sel:DWORD
	v_add3_u32 v3, v7, v3, s58
	v_add3_u32 v5, v5, v6, s58
	v_and_b32_e32 v3, 0xffff0000, v3
	v_and_b32_e32 v5, 0xffff0000, v5
	v_or_b32_sdwa v3, v3, v2 dst_sel:DWORD dst_unused:UNUSED_PAD src0_sel:DWORD src1_sel:WORD_1
	v_or_b32_sdwa v2, v5, v4 dst_sel:DWORD dst_unused:UNUSED_PAD src0_sel:DWORD src1_sel:WORD_1
	v_add_co_u32_e32 v4, vcc, s72, v114
	v_or_b32_sdwa v0, v8, v0 dst_sel:DWORD dst_unused:UNUSED_PAD src0_sel:DWORD src1_sel:WORD_1
	s_nop 0
	v_addc_co_u32_e32 v5, vcc, 0, v115, vcc
	global_store_dwordx4 v[4:5], v[0:3], off offset:2816
	ds_read_b128 v[0:3], v118 offset:26128
	ds_read_b128 v[4:7], v118 offset:26144
	s_addc_u32 s80, s53, 0
	s_add_u32 s81, s52, 0x1738000
	s_addc_u32 s82, s53, 0
	s_waitcnt lgkmcnt(0)
	v_and_b32_sdwa v8, v2, v134 dst_sel:DWORD dst_unused:UNUSED_PAD src0_sel:WORD_1 src1_sel:DWORD
	v_and_b32_sdwa v9, v0, v134 dst_sel:DWORD dst_unused:UNUSED_PAD src0_sel:WORD_1 src1_sel:DWORD
	v_add3_u32 v2, v2, v8, s58
	v_and_b32_sdwa v8, v3, v134 dst_sel:DWORD dst_unused:UNUSED_PAD src0_sel:WORD_1 src1_sel:DWORD
	v_add3_u32 v0, v0, v9, s58
	v_and_b32_sdwa v9, v1, v134 dst_sel:DWORD dst_unused:UNUSED_PAD src0_sel:WORD_1 src1_sel:DWORD
	v_add3_u32 v3, v3, v8, s58
	v_add3_u32 v1, v1, v9, s58
	v_and_b32_e32 v3, 0xffff0000, v3
	v_and_b32_e32 v8, 0xffff0000, v1
	v_or_b32_sdwa v1, v3, v2 dst_sel:DWORD dst_unused:UNUSED_PAD src0_sel:DWORD src1_sel:WORD_1
	v_and_b32_sdwa v2, v6, v134 dst_sel:DWORD dst_unused:UNUSED_PAD src0_sel:WORD_1 src1_sel:DWORD
	v_and_b32_sdwa v3, v4, v134 dst_sel:DWORD dst_unused:UNUSED_PAD src0_sel:WORD_1 src1_sel:DWORD
	v_add3_u32 v4, v4, v3, s58
	v_add3_u32 v2, v6, v2, s58
	v_and_b32_sdwa v3, v7, v134 dst_sel:DWORD dst_unused:UNUSED_PAD src0_sel:WORD_1 src1_sel:DWORD
	v_and_b32_sdwa v6, v5, v134 dst_sel:DWORD dst_unused:UNUSED_PAD src0_sel:WORD_1 src1_sel:DWORD
	v_add3_u32 v3, v7, v3, s58
	v_add3_u32 v5, v5, v6, s58
	v_and_b32_e32 v3, 0xffff0000, v3
	v_and_b32_e32 v5, 0xffff0000, v5
	v_or_b32_sdwa v3, v3, v2 dst_sel:DWORD dst_unused:UNUSED_PAD src0_sel:DWORD src1_sel:WORD_1
	v_or_b32_sdwa v2, v5, v4 dst_sel:DWORD dst_unused:UNUSED_PAD src0_sel:DWORD src1_sel:WORD_1
	v_add_co_u32_e32 v4, vcc, s72, v116
	v_or_b32_sdwa v0, v8, v0 dst_sel:DWORD dst_unused:UNUSED_PAD src0_sel:DWORD src1_sel:WORD_1
	s_nop 0
	v_addc_co_u32_e32 v5, vcc, 0, v117, vcc
	global_store_dwordx4 v[4:5], v[0:3], off offset:2816
	ds_read_b128 v[0:3], v118 offset:27168
	ds_read_b128 v[4:7], v118 offset:27184
	v_lshl_add_u64 v[88:89], v[88:89], 0, s[48:49]
	s_mov_b64 s[8:9], -1
	s_waitcnt lgkmcnt(0)
	v_and_b32_sdwa v8, v2, v134 dst_sel:DWORD dst_unused:UNUSED_PAD src0_sel:WORD_1 src1_sel:DWORD
	v_and_b32_sdwa v9, v0, v134 dst_sel:DWORD dst_unused:UNUSED_PAD src0_sel:WORD_1 src1_sel:DWORD
	v_add3_u32 v2, v2, v8, s58
	v_and_b32_sdwa v8, v3, v134 dst_sel:DWORD dst_unused:UNUSED_PAD src0_sel:WORD_1 src1_sel:DWORD
	v_add3_u32 v0, v0, v9, s58
	v_and_b32_sdwa v9, v1, v134 dst_sel:DWORD dst_unused:UNUSED_PAD src0_sel:WORD_1 src1_sel:DWORD
	v_add3_u32 v3, v3, v8, s58
	v_add3_u32 v1, v1, v9, s58
	v_and_b32_e32 v3, 0xffff0000, v3
	v_and_b32_e32 v8, 0xffff0000, v1
	v_or_b32_sdwa v1, v3, v2 dst_sel:DWORD dst_unused:UNUSED_PAD src0_sel:DWORD src1_sel:WORD_1
	v_and_b32_sdwa v2, v6, v134 dst_sel:DWORD dst_unused:UNUSED_PAD src0_sel:WORD_1 src1_sel:DWORD
	v_and_b32_sdwa v3, v4, v134 dst_sel:DWORD dst_unused:UNUSED_PAD src0_sel:WORD_1 src1_sel:DWORD
	v_add3_u32 v4, v4, v3, s58
	v_add3_u32 v2, v6, v2, s58
	v_and_b32_sdwa v3, v7, v134 dst_sel:DWORD dst_unused:UNUSED_PAD src0_sel:WORD_1 src1_sel:DWORD
	v_and_b32_sdwa v6, v5, v134 dst_sel:DWORD dst_unused:UNUSED_PAD src0_sel:WORD_1 src1_sel:DWORD
	v_add3_u32 v3, v7, v3, s58
	v_add3_u32 v5, v5, v6, s58
	v_and_b32_e32 v3, 0xffff0000, v3
	v_and_b32_e32 v5, 0xffff0000, v5
	v_or_b32_sdwa v3, v3, v2 dst_sel:DWORD dst_unused:UNUSED_PAD src0_sel:DWORD src1_sel:WORD_1
	v_or_b32_sdwa v2, v5, v4 dst_sel:DWORD dst_unused:UNUSED_PAD src0_sel:DWORD src1_sel:WORD_1
	v_add_co_u32_e32 v4, vcc, s72, v180
	v_or_b32_sdwa v0, v8, v0 dst_sel:DWORD dst_unused:UNUSED_PAD src0_sel:DWORD src1_sel:WORD_1
	s_nop 0
	v_addc_co_u32_e32 v5, vcc, 0, v181, vcc
	global_store_dwordx4 v[4:5], v[0:3], off offset:2816
	ds_read_b128 v[0:3], v119 offset:25088
	ds_read_b128 v[4:7], v119 offset:25104
	s_waitcnt lgkmcnt(0)
	v_and_b32_sdwa v8, v2, v134 dst_sel:DWORD dst_unused:UNUSED_PAD src0_sel:WORD_1 src1_sel:DWORD
	v_and_b32_sdwa v9, v0, v134 dst_sel:DWORD dst_unused:UNUSED_PAD src0_sel:WORD_1 src1_sel:DWORD
	v_add3_u32 v2, v2, v8, s58
	v_and_b32_sdwa v8, v3, v134 dst_sel:DWORD dst_unused:UNUSED_PAD src0_sel:WORD_1 src1_sel:DWORD
	v_add3_u32 v0, v0, v9, s58
	v_and_b32_sdwa v9, v1, v134 dst_sel:DWORD dst_unused:UNUSED_PAD src0_sel:WORD_1 src1_sel:DWORD
	v_add3_u32 v3, v3, v8, s58
	v_add3_u32 v1, v1, v9, s58
	v_and_b32_e32 v3, 0xffff0000, v3
	v_and_b32_e32 v8, 0xffff0000, v1
	v_or_b32_sdwa v1, v3, v2 dst_sel:DWORD dst_unused:UNUSED_PAD src0_sel:DWORD src1_sel:WORD_1
	v_and_b32_sdwa v2, v6, v134 dst_sel:DWORD dst_unused:UNUSED_PAD src0_sel:WORD_1 src1_sel:DWORD
	v_and_b32_sdwa v3, v4, v134 dst_sel:DWORD dst_unused:UNUSED_PAD src0_sel:WORD_1 src1_sel:DWORD
	v_add3_u32 v4, v4, v3, s58
	v_add3_u32 v2, v6, v2, s58
	v_and_b32_sdwa v3, v7, v134 dst_sel:DWORD dst_unused:UNUSED_PAD src0_sel:WORD_1 src1_sel:DWORD
	v_and_b32_sdwa v6, v5, v134 dst_sel:DWORD dst_unused:UNUSED_PAD src0_sel:WORD_1 src1_sel:DWORD
	v_add3_u32 v3, v7, v3, s58
	v_add3_u32 v5, v5, v6, s58
	v_and_b32_e32 v3, 0xffff0000, v3
	v_and_b32_e32 v5, 0xffff0000, v5
	v_or_b32_sdwa v3, v3, v2 dst_sel:DWORD dst_unused:UNUSED_PAD src0_sel:DWORD src1_sel:WORD_1
	v_or_b32_sdwa v2, v5, v4 dst_sel:DWORD dst_unused:UNUSED_PAD src0_sel:DWORD src1_sel:WORD_1
	v_add_co_u32_e32 v4, vcc, s72, v182
	v_or_b32_sdwa v0, v8, v0 dst_sel:DWORD dst_unused:UNUSED_PAD src0_sel:DWORD src1_sel:WORD_1
	s_nop 0
	v_addc_co_u32_e32 v5, vcc, 0, v183, vcc
	global_store_dwordx4 v[4:5], v[0:3], off offset:2816
	s_waitcnt lgkmcnt(0)
	s_barrier
	global_load_dwordx2 v[0:1], v[32:33], off offset:456
	v_and_b32_e32 v8, 7, v135
	v_lshlrev_b64 v[2:3], 8, v[92:93]
	v_lshlrev_b64 v[4:5], 8, v[94:95]
	v_lshlrev_b64 v[6:7], 8, v[96:97]
	v_cmp_eq_u32_e64 s[4:5], 0, v8
	v_or_b32_e32 v2, v2, v126
	v_or_b32_e32 v4, v4, v126
	v_or_b32_e32 v6, v6, v126
	v_lshlrev_b64 v[92:93], 4, v[92:93]
	v_lshlrev_b64 v[94:95], 4, v[94:95]
	v_lshlrev_b64 v[96:97], 4, v[96:97]
	v_lshlrev_b64 v[104:105], 1, v[2:3]
	v_lshlrev_b64 v[106:107], 1, v[4:5]
	v_lshlrev_b64 v[108:109], 1, v[6:7]
	s_waitcnt vmcnt(0) lgkmcnt(0)
	v_readfirstlane_b32 s1, v1
	v_readfirstlane_b32 s0, v0
	s_nop 1
	v_lshl_add_u64 v[0:1], s[0:1], 0, v[64:65]
	global_load_dwordx4 v[30:33], v[0:1], off
	global_load_dwordx4 v[34:37], v[0:1], off offset:16
	s_add_u32 s0, s52, 0x2954198
	s_addc_u32 s1, s53, 0
	s_add_u32 s83, s52, 0x1748000
	v_lshlrev_b64 v[0:1], 8, v[90:91]
	s_addc_u32 s84, s53, 0
	v_bfe_u32 v64, v135, 1, 4
	v_or_b32_e32 v0, v0, v126
	s_add_u32 s6, s52, 0x29541a8
	v_lshl_add_u64 v[8:9], s[52:53], 0, v[64:65]
	v_lshlrev_b64 v[90:91], 4, v[90:91]
	s_addc_u32 s7, s53, 0
	v_lshl_add_u64 v[98:99], v[8:9], 0, s[50:51]
	v_lshlrev_b32_e32 v64, 2, v126
	s_waitcnt vmcnt(0) lgkmcnt(0)
	v_mov_b32_e32 v100, v30
	v_mov_b32_e32 v101, v32
	v_mov_b32_e32 v32, v31
	v_mov_b32_e32 v102, v34
	v_mov_b32_e32 v103, v36
	v_mov_b32_e32 v36, v35
	v_lshlrev_b64 v[34:35], 1, v[0:1]
	s_branch .LBB0_426

.LBB0_1406:
	v_add_u32_e32 v4, s82, v135
	v_mul_hi_i32 v2, v4, s66
	v_lshrrev_b32_e32 v3, 31, v2
	v_ashrrev_i32_e32 v2, 3, v2
	v_add_u32_e32 v5, v2, v3
	v_mad_u64_u32 v[20:21], s[0:1], v5, s68, v[0:1]
	v_add_u32_e32 v6, s26, v5
	v_mov_b64_e32 v[2:3], s[54:55]
	v_add_u32_e32 v8, s81, v5
	v_mad_i64_i32 v[6:7], s[0:1], v6, s34, v[2:3]
	v_ashrrev_i32_e32 v21, 31, v20
	v_mad_u64_u32 v[18:19], s[0:1], v5, s67, v[4:5]
	v_lshl_add_u64 v[6:7], v[20:21], 1, v[6:7]
	v_cmp_lt_i32_e32 vcc, s27, v8
	v_lshl_add_u64 v[14:15], v[6:7], 0, s[22:23]
	v_add_co_u32_e64 v6, s[0:1], s69, v6
	v_cndmask_b32_e64 v11, 0, -1, vcc
	v_cndmask_b32_e32 v10, 0, v132, vcc
	v_cmp_gt_i32_e64 s[6:7], s80, v8
	v_addc_co_u32_e64 v7, s[0:1], 0, v7, s[0:1]
	v_lshl_add_u64 v[10:11], v[14:15], 0, v[10:11]
	global_load_dwordx4 v[6:9], v[6:7], off offset:1792
	v_cndmask_b32_e64 v64, 0, v133, s[6:7]
	global_load_dwordx4 v[10:13], v[10:11], off
	v_lshl_add_u64 v[14:15], v[14:15], 0, v[64:65]
	global_load_dwordx4 v[14:17], v[14:15], off
	v_lshlrev_b64 v[208:209], 2, v[20:21]
	v_lshl_add_u64 v[210:211], s[12:13], 0, v[208:209]
	v_lshl_add_u64 v[212:213], s[24:25], 0, v[208:209]
	global_load_dwordx4 v[216:219], v[210:211], off offset:0
	global_load_dwordx4 v[220:223], v[212:213], off offset:0
	global_load_dwordx4 v[224:227], v[210:211], off offset:16
	global_load_dwordx4 v[228:231], v[212:213], off offset:16
	v_cmp_gt_i32_e64 s[4:5], 32, v18
	v_cmp_gt_i32_e64 s[0:1], 16, v18
	v_lshl_add_u32 v5, v5, 4, v1
	v_add_u32_e32 v4, 0x100, v4
	s_addk_i32 s82, 0x200
	s_cmpk_eq_i32 s82, 0x600
	s_waitcnt vmcnt(0) lgkmcnt(0)
	v_lshlrev_b32_e32 v31, 16, v7
	v_and_b32_e32 v7, 0xffff0000, v7
	v_lshlrev_b32_e32 v26, 16, v12
	v_and_b32_e32 v27, 0xffff0000, v12
	v_lshlrev_b32_e32 v29, 16, v13
	v_and_b32_e32 v30, 0xffff0000, v13
	v_lshlrev_b64 v[12:13], 2, v[20:21]
	v_and_b32_e32 v19, 0xffff0000, v10
	v_lshlrev_b32_e32 v25, 16, v11
	v_and_b32_e32 v11, 0xffff0000, v11
	v_lshl_add_u64 v[20:21], s[12:13], 0, v[12:13]
	v_lshlrev_b32_e32 v10, 16, v10
	v_lshlrev_b32_e32 v32, 16, v14
	v_lshlrev_b32_e32 v33, 16, v15
	v_and_b32_e32 v36, 0xffff0000, v15
	v_and_b32_e32 v37, 0xffff0000, v14
	v_lshlrev_b32_e32 v38, 16, v16
	v_lshlrev_b32_e32 v39, 16, v17
	v_and_b32_e32 v40, 0xffff0000, v17
	v_and_b32_e32 v41, 0xffff0000, v16
	v_lshl_add_u64 v[22:23], s[24:25], 0, v[12:13]
	v_cndmask_b32_e32 v18, 0, v10, vcc
	v_cndmask_b32_e32 v24, 0, v19, vcc
	v_cndmask_b32_e32 v19, 0, v25, vcc
	v_cndmask_b32_e32 v25, 0, v11, vcc
	v_cndmask_b32_e32 v28, 0, v27, vcc
	v_cndmask_b32_e32 v27, 0, v29, vcc
	v_cndmask_b32_e32 v29, 0, v30, vcc
	v_lshlrev_b32_e32 v30, 16, v6
	v_cndmask_b32_e64 v33, 0, v33, s[6:7]
	v_cndmask_b32_e64 v32, 0, v32, s[6:7]
	v_pk_add_f32 v[18:19], v[18:19], v[30:31] neg_lo:[0,1] neg_hi:[0,1]
	v_and_b32_e32 v6, 0xffff0000, v6
	v_pk_add_f32 v[24:25], v[24:25], v[6:7] neg_lo:[0,1] neg_hi:[0,1]
	v_cndmask_b32_e32 v26, 0, v26, vcc
	s_waitcnt vmcnt(0) lgkmcnt(0)
	v_mov_b64_e32 v[10:11], v[216:217]
	v_mov_b64_e32 v[12:13], v[218:219]
	v_mov_b64_e32 v[14:15], v[220:221]
	v_mov_b64_e32 v[16:17], v[222:223]
	v_mov_b32_e32 v34, v10
	v_mov_b32_e32 v35, v12
	v_pk_fma_f32 v[18:19], v[34:35], v[18:19], v[30:31]
	v_pk_add_f32 v[30:31], v[32:33], v[30:31] neg_lo:[0,1] neg_hi:[0,1]
	v_mov_b32_e32 v32, v14
	v_mov_b32_e32 v33, v16
	v_pk_fma_f32 v[18:19], v[30:31], v[32:33], v[18:19]
	v_cndmask_b32_e64 v31, 0, v36, s[6:7]
	v_cndmask_b32_e64 v30, 0, v37, s[6:7]
	v_mov_b32_e32 v12, v11
	v_pk_fma_f32 v[12:13], v[12:13], v[24:25], v[6:7]
	v_pk_add_f32 v[6:7], v[30:31], v[6:7] neg_lo:[0,1] neg_hi:[0,1]
	v_mov_b32_e32 v16, v15
	v_pk_fma_f32 v[6:7], v[6:7], v[16:17], v[12:13]
	v_add_f32_e32 v10, v18, v18
	v_add_f32_e32 v11, v6, v6
	v_cndmask_b32_e64 v11, v11, v6, s[0:1]
	v_mul_f32_e32 v11, 0xbfb8aa3b, v11
	v_exp_f32_e32 v12, v11
	v_add_f32_e32 v11, v19, v19
	v_cndmask_b32_e64 v10, v10, v18, s[0:1]
	v_cndmask_b32_e64 v11, v11, v19, s[0:1]
	v_mul_f32_e32 v10, 0xbfb8aa3b, v10
	v_mul_f32_e32 v11, 0xbfb8aa3b, v11
	v_exp_f32_e32 v10, v10
	v_exp_f32_e32 v11, v11
	s_nop 0
	v_pk_add_f32 v[10:11], v[10:11], 1.0 op_sel_hi:[1,0]
	s_nop 0
	v_div_scale_f32 v13, s[84:85], v11, v11, 1.0
	v_rcp_f32_e32 v14, v13
	s_nop 0
	v_fma_f32 v15, -v13, v14, 1.0
	v_fmac_f32_e32 v14, v15, v14
	v_div_scale_f32 v15, vcc, 1.0, v11, 1.0
	v_mul_f32_e32 v16, v15, v14
	v_fma_f32 v17, -v13, v16, v15
	v_fmac_f32_e32 v16, v17, v14
	v_fma_f32 v13, -v13, v16, v15
	v_div_fmas_f32 v13, v13, v14, v16
	v_div_fixup_f32 v11, v13, v11, 1.0
	v_div_scale_f32 v13, s[84:85], v10, v10, 1.0
	v_rcp_f32_e32 v14, v13
	s_nop 0
	v_fma_f32 v15, -v13, v14, 1.0
	v_fmac_f32_e32 v14, v15, v14
	v_div_scale_f32 v15, vcc, 1.0, v10, 1.0
	v_mul_f32_e32 v16, v15, v14
	v_fma_f32 v17, -v13, v16, v15
	v_fmac_f32_e32 v16, v17, v14
	v_fma_f32 v13, -v13, v16, v15
	v_div_fmas_f32 v13, v13, v14, v16
	v_div_fixup_f32 v10, v13, v10, 1.0
	v_pk_fma_f32 v[14:15], v[10:11], 2.0, -1.0 op_sel_hi:[1,0,0]
	v_and_b32_e32 v17, 0xffff0000, v9
	v_cndmask_b32_e64 v13, v18, v14, s[4:5]
	v_cndmask_b32_e64 v25, v13, v10, s[0:1]
	v_add_f32_e32 v10, v7, v7
	v_cndmask_b32_e64 v10, v10, v7, s[0:1]
	v_mul_f32_e32 v10, 0xbfb8aa3b, v10
	v_exp_f32_e32 v13, v10
	v_cndmask_b32_e64 v14, v19, v15, s[4:5]
	v_cndmask_b32_e64 v24, v14, v11, s[0:1]
	v_cndmask_b32_e64 v19, 0, v39, s[6:7]
	v_pk_add_f32 v[10:11], v[12:13], 1.0 op_sel_hi:[1,0]
	v_cndmask_b32_e64 v18, 0, v38, s[6:7]
	v_div_scale_f32 v12, s[84:85], v11, v11, 1.0
	v_rcp_f32_e32 v13, v12
	s_nop 0
	v_fma_f32 v14, -v12, v13, 1.0
	v_fmac_f32_e32 v13, v14, v13
	v_div_scale_f32 v14, vcc, 1.0, v11, 1.0
	v_mul_f32_e32 v15, v14, v13
	v_fma_f32 v16, -v12, v15, v14
	v_fmac_f32_e32 v15, v16, v13
	v_fma_f32 v12, -v12, v15, v14
	v_div_fmas_f32 v12, v12, v13, v15
	v_div_fixup_f32 v11, v12, v11, 1.0
	v_div_scale_f32 v12, s[84:85], v10, v10, 1.0
	v_rcp_f32_e32 v13, v12
	s_nop 0
	v_fma_f32 v14, -v12, v13, 1.0
	v_fmac_f32_e32 v13, v14, v13
	v_div_scale_f32 v14, vcc, 1.0, v10, 1.0
	v_mul_f32_e32 v15, v14, v13
	v_fma_f32 v16, -v12, v15, v14
	v_fmac_f32_e32 v15, v16, v13
	v_fma_f32 v12, -v12, v15, v14
	v_div_fmas_f32 v12, v12, v13, v15
	v_div_fixup_f32 v10, v12, v10, 1.0
	v_pk_fma_f32 v[12:13], v[10:11], 2.0, -1.0 op_sel_hi:[1,0,0]
	v_lshlrev_b32_e32 v15, 16, v9
	v_cndmask_b32_e64 v7, v7, v13, s[4:5]
	v_cndmask_b32_e64 v6, v6, v12, s[4:5]
	v_cndmask_b32_e64 v30, v6, v10, s[0:1]
	v_cndmask_b32_e64 v31, v7, v11, s[0:1]
	v_lshlrev_b32_e32 v14, 16, v8
	v_and_b32_e32 v16, 0xffff0000, v8
	v_pk_add_f32 v[20:21], v[26:27], v[14:15] neg_lo:[0,1] neg_hi:[0,1]
	s_waitcnt vmcnt(0) lgkmcnt(0)
	v_mov_b64_e32 v[6:7], v[224:225]
	v_mov_b64_e32 v[8:9], v[226:227]
	v_mov_b64_e32 v[10:11], v[228:229]
	v_mov_b64_e32 v[12:13], v[230:231]
	v_mov_b32_e32 v22, v6
	v_mov_b32_e32 v23, v8
	v_pk_fma_f32 v[20:21], v[20:21], v[22:23], v[14:15]
	v_pk_add_f32 v[14:15], v[18:19], v[14:15] neg_lo:[0,1] neg_hi:[0,1]
	v_mov_b32_e32 v18, v10
	v_mov_b32_e32 v19, v12
	v_pk_fma_f32 v[14:15], v[14:15], v[18:19], v[20:21]
	v_cndmask_b32_e64 v19, 0, v40, s[6:7]
	v_cndmask_b32_e64 v18, 0, v41, s[6:7]
	v_pk_add_f32 v[20:21], v[28:29], v[16:17] neg_lo:[0,1] neg_hi:[0,1]
	v_mov_b32_e32 v8, v7
	v_pk_fma_f32 v[8:9], v[20:21], v[8:9], v[16:17]
	v_pk_add_f32 v[16:17], v[18:19], v[16:17] neg_lo:[0,1] neg_hi:[0,1]
	v_mov_b32_e32 v12, v11
	v_pk_fma_f32 v[8:9], v[16:17], v[12:13], v[8:9]
	v_add_f32_e32 v6, v14, v14
	v_add_f32_e32 v7, v8, v8
	v_cndmask_b32_e64 v7, v7, v8, s[0:1]
	v_mul_f32_e32 v7, 0xbfb8aa3b, v7
	v_exp_f32_e32 v10, v7
	v_add_f32_e32 v7, v15, v15
	v_cndmask_b32_e64 v6, v6, v14, s[0:1]
	v_cndmask_b32_e64 v7, v7, v15, s[0:1]
	v_mul_f32_e32 v6, 0xbfb8aa3b, v6
	v_mul_f32_e32 v7, 0xbfb8aa3b, v7
	v_exp_f32_e32 v6, v6
	v_exp_f32_e32 v7, v7
	s_nop 0
	v_pk_add_f32 v[6:7], v[6:7], 1.0 op_sel_hi:[1,0]
	s_nop 0
	v_div_scale_f32 v11, s[6:7], v7, v7, 1.0
	v_rcp_f32_e32 v12, v11
	s_nop 0
	v_fma_f32 v13, -v11, v12, 1.0
	v_fmac_f32_e32 v12, v13, v12
	v_div_scale_f32 v13, vcc, 1.0, v7, 1.0
	v_mul_f32_e32 v16, v13, v12
	v_fma_f32 v17, -v11, v16, v13
	v_fmac_f32_e32 v16, v17, v12
	v_fma_f32 v11, -v11, v16, v13
	v_div_fmas_f32 v11, v11, v12, v16
	v_div_fixup_f32 v7, v11, v7, 1.0
	v_div_scale_f32 v11, s[6:7], v6, v6, 1.0
	v_rcp_f32_e32 v12, v11
	s_nop 0
	v_fma_f32 v13, -v11, v12, 1.0
	v_fmac_f32_e32 v12, v13, v12
	v_div_scale_f32 v13, vcc, 1.0, v6, 1.0
	v_mul_f32_e32 v16, v13, v12
	v_fma_f32 v17, -v11, v16, v13
	v_fmac_f32_e32 v16, v17, v12
	v_fma_f32 v11, -v11, v16, v13
	v_div_fmas_f32 v11, v11, v12, v16
	v_div_fixup_f32 v6, v11, v6, 1.0
	v_pk_fma_f32 v[12:13], v[6:7], 2.0, -1.0 op_sel_hi:[1,0,0]
	s_nop 0
	v_cndmask_b32_e64 v11, v14, v12, s[4:5]
	v_cndmask_b32_e64 v12, v15, v13, s[4:5]
	v_cndmask_b32_e64 v13, v11, v6, s[0:1]
	v_add_f32_e32 v6, v9, v9
	v_cndmask_b32_e64 v6, v6, v9, s[0:1]
	v_mul_f32_e32 v6, 0xbfb8aa3b, v6
	v_exp_f32_e32 v11, v6
	v_cndmask_b32_e64 v12, v12, v7, s[0:1]
	v_pk_add_f32 v[6:7], v[10:11], 1.0 op_sel_hi:[1,0]
	s_nop 0
	v_div_scale_f32 v10, s[6:7], v7, v7, 1.0
	v_rcp_f32_e32 v11, v10
	s_nop 0
	v_fma_f32 v14, -v10, v11, 1.0
	v_fmac_f32_e32 v11, v14, v11
	v_div_scale_f32 v14, vcc, 1.0, v7, 1.0
	v_mul_f32_e32 v15, v14, v11
	v_fma_f32 v16, -v10, v15, v14
	v_fmac_f32_e32 v15, v16, v11
	v_fma_f32 v10, -v10, v15, v14
	v_div_fmas_f32 v10, v10, v11, v15
	v_div_fixup_f32 v7, v10, v7, 1.0
	v_div_scale_f32 v10, s[6:7], v6, v6, 1.0
	v_rcp_f32_e32 v11, v10
	s_nop 0
	v_fma_f32 v14, -v10, v11, 1.0
	v_fmac_f32_e32 v11, v14, v11
	v_div_scale_f32 v14, vcc, 1.0, v6, 1.0
	v_mul_f32_e32 v15, v14, v11
	v_fma_f32 v16, -v10, v15, v14
	v_fmac_f32_e32 v15, v16, v11
	v_fma_f32 v10, -v10, v15, v14
	v_div_fmas_f32 v10, v10, v11, v15
	v_div_fixup_f32 v6, v10, v6, 1.0
	v_pk_fma_f32 v[10:11], v[6:7], 2.0, -1.0 op_sel_hi:[1,0,0]
	v_bfe_u32 v14, v13, 16, 1
	v_cndmask_b32_e64 v9, v9, v11, s[4:5]
	v_cndmask_b32_e64 v8, v8, v10, s[4:5]
	v_cndmask_b32_e64 v6, v8, v6, s[0:1]
	v_cndmask_b32_e64 v7, v9, v7, s[0:1]
	v_bfe_u32 v8, v7, 16, 1
	v_bfe_u32 v9, v6, 16, 1
	v_add3_u32 v6, v6, v9, s60
	v_add3_u32 v7, v7, v8, s60
	v_bfe_u32 v8, v25, 16, 1
	v_bfe_u32 v9, v24, 16, 1
	v_bfe_u32 v15, v12, 16, 1
	v_bfe_u32 v10, v31, 16, 1
	v_bfe_u32 v11, v30, 16, 1
	v_add3_u32 v12, v12, v15, s60
	v_add3_u32 v13, v13, v14, s60
	v_add3_u32 v9, v24, v9, s60
	v_add3_u32 v8, v25, v8, s60
	v_add3_u32 v11, v30, v11, s60
	v_add3_u32 v10, v31, v10, s60
	v_lshrrev_b32_e32 v14, 16, v8
	v_lshrrev_b32_e32 v15, 16, v9
	v_lshrrev_b32_e32 v8, 16, v13
	v_lshrrev_b32_e32 v9, 16, v12
	v_and_or_b32 v9, v7, s56, v9
	v_and_or_b32 v8, v6, s56, v8
	v_and_or_b32 v7, v10, s56, v15
	v_and_or_b32 v6, v11, s56, v14
	ds_write_b128 v5, v[6:9]
	v_mul_hi_i32 v5, v4, s66
	v_lshrrev_b32_e32 v6, 31, v5
	v_ashrrev_i32_e32 v5, 3, v5
	v_add_u32_e32 v6, v5, v6
	v_mad_u64_u32 v[4:5], s[0:1], v6, s67, v[4:5]
	v_mul_lo_u32 v5, v6, s68
	s_movk_i32 s0, 0x800
	v_add3_u32 v20, v0, v5, s0
	v_add_u32_e32 v7, s26, v6
	v_mad_i64_i32 v[2:3], s[0:1], v7, s34, v[2:3]
	v_ashrrev_i32_e32 v21, 31, v20
	v_lshl_add_u64 v[2:3], v[20:21], 1, v[2:3]
	v_add_u32_e32 v5, s81, v6
	v_lshl_add_u64 v[16:17], v[2:3], 0, s[22:23]
	v_add_co_u32_e64 v2, s[0:1], s69, v2
	v_cmp_lt_i32_e32 vcc, s27, v5
	s_nop 0
	v_addc_co_u32_e64 v3, s[0:1], 0, v3, s[0:1]
	v_cmp_gt_i32_e64 s[6:7], s80, v5
	global_load_dwordx4 v[8:11], v[2:3], off offset:1792
	v_cndmask_b32_e64 v3, 0, -1, vcc
	v_cndmask_b32_e32 v2, 0, v132, vcc
	v_lshl_add_u64 v[2:3], v[16:17], 0, v[2:3]
	v_cndmask_b32_e64 v64, 0, v133, s[6:7]
	global_load_dwordx4 v[12:15], v[2:3], off
	v_lshl_add_u64 v[2:3], v[16:17], 0, v[64:65]
	global_load_dwordx4 v[16:19], v[2:3], off
	v_lshlrev_b64 v[208:209], 2, v[20:21]
	v_lshl_add_u64 v[210:211], s[12:13], 0, v[208:209]
	v_lshl_add_u64 v[212:213], s[24:25], 0, v[208:209]
	global_load_dwordx4 v[216:219], v[210:211], off offset:0
	global_load_dwordx4 v[220:223], v[212:213], off offset:0
	global_load_dwordx4 v[224:227], v[210:211], off offset:16
	global_load_dwordx4 v[228:231], v[212:213], off offset:16
	v_lshlrev_b64 v[2:3], 2, v[20:21]
	v_cmp_gt_i32_e64 s[4:5], 32, v4
	v_cmp_gt_i32_e64 s[0:1], 16, v4
	v_lshl_add_u32 v6, v6, 4, v1
	v_add_u32_e32 v1, 0x2000, v1
	v_add_u32_e32 v0, 0x1000, v0
	s_waitcnt vmcnt(0) lgkmcnt(0)
	v_lshlrev_b32_e32 v29, 16, v9
	v_lshlrev_b32_e32 v28, 16, v8
	v_and_b32_e32 v9, 0xffff0000, v9
	v_and_b32_e32 v8, 0xffff0000, v8
	v_and_b32_e32 v5, 0xffff0000, v12
	v_lshlrev_b32_e32 v7, 16, v13
	v_and_b32_e32 v13, 0xffff0000, v13
	v_lshlrev_b32_e32 v24, 16, v14
	v_and_b32_e32 v14, 0xffff0000, v14
	v_lshlrev_b32_e32 v25, 16, v15
	v_and_b32_e32 v15, 0xffff0000, v15
	v_lshlrev_b32_e32 v30, 16, v16
	v_lshlrev_b32_e32 v31, 16, v17
	v_and_b32_e32 v34, 0xffff0000, v17
	v_and_b32_e32 v35, 0xffff0000, v16
	v_lshlrev_b32_e32 v36, 16, v18
	v_lshlrev_b32_e32 v37, 16, v19
	v_and_b32_e32 v38, 0xffff0000, v19
	v_and_b32_e32 v39, 0xffff0000, v18
	v_lshl_add_u64 v[16:17], s[12:13], 0, v[2:3]
	v_lshl_add_u64 v[18:19], s[24:25], 0, v[2:3]
	v_lshlrev_b32_e32 v2, 16, v12
	v_cndmask_b32_e32 v20, 0, v2, vcc
	v_cndmask_b32_e32 v22, 0, v5, vcc
	v_cndmask_b32_e32 v23, 0, v13, vcc
	v_cndmask_b32_e32 v26, 0, v14, vcc
	v_cndmask_b32_e32 v27, 0, v15, vcc
	v_cndmask_b32_e32 v21, 0, v7, vcc
	v_cndmask_b32_e64 v31, 0, v31, s[6:7]
	v_cndmask_b32_e64 v30, 0, v30, s[6:7]
	v_pk_add_f32 v[20:21], v[20:21], v[28:29] neg_lo:[0,1] neg_hi:[0,1]
	v_pk_add_f32 v[22:23], v[22:23], v[8:9] neg_lo:[0,1] neg_hi:[0,1]
	v_cndmask_b32_e32 v24, 0, v24, vcc
	v_cndmask_b32_e32 v25, 0, v25, vcc
	s_waitcnt vmcnt(0) lgkmcnt(0)
	v_mov_b64_e32 v[2:3], v[216:217]
	v_mov_b64_e32 v[4:5], v[218:219]
	v_mov_b64_e32 v[12:13], v[220:221]
	v_mov_b64_e32 v[14:15], v[222:223]
	v_mov_b32_e32 v32, v2
	v_mov_b32_e32 v33, v4
	v_pk_fma_f32 v[20:21], v[32:33], v[20:21], v[28:29]
	v_pk_add_f32 v[28:29], v[30:31], v[28:29] neg_lo:[0,1] neg_hi:[0,1]
	v_mov_b32_e32 v30, v12
	v_mov_b32_e32 v31, v14
	v_pk_fma_f32 v[20:21], v[28:29], v[30:31], v[20:21]
	v_cndmask_b32_e64 v29, 0, v34, s[6:7]
	v_cndmask_b32_e64 v28, 0, v35, s[6:7]
	v_mov_b32_e32 v4, v3
	v_pk_fma_f32 v[4:5], v[4:5], v[22:23], v[8:9]
	v_pk_add_f32 v[8:9], v[28:29], v[8:9] neg_lo:[0,1] neg_hi:[0,1]
	v_mov_b32_e32 v14, v13
	v_pk_fma_f32 v[4:5], v[8:9], v[14:15], v[4:5]
	v_add_f32_e32 v2, v20, v20
	v_add_f32_e32 v3, v4, v4
	v_cndmask_b32_e64 v3, v3, v4, s[0:1]
	v_mul_f32_e32 v3, 0xbfb8aa3b, v3
	v_exp_f32_e32 v8, v3
	v_add_f32_e32 v3, v21, v21
	v_cndmask_b32_e64 v2, v2, v20, s[0:1]
	v_cndmask_b32_e64 v3, v3, v21, s[0:1]
	v_mul_f32_e32 v2, 0xbfb8aa3b, v2
	v_mul_f32_e32 v3, 0xbfb8aa3b, v3
	v_exp_f32_e32 v2, v2
	v_exp_f32_e32 v3, v3
	v_and_b32_e32 v15, 0xffff0000, v11
	v_pk_add_f32 v[2:3], v[2:3], 1.0 op_sel_hi:[1,0]
	s_nop 0
	v_div_scale_f32 v7, s[84:85], v3, v3, 1.0
	v_rcp_f32_e32 v9, v7
	s_nop 0
	v_fma_f32 v12, -v7, v9, 1.0
	v_fmac_f32_e32 v9, v12, v9
	v_div_scale_f32 v12, vcc, 1.0, v3, 1.0
	v_mul_f32_e32 v13, v12, v9
	v_fma_f32 v14, -v7, v13, v12
	v_fmac_f32_e32 v13, v14, v9
	v_fma_f32 v7, -v7, v13, v12
	v_div_fmas_f32 v7, v7, v9, v13
	v_div_fixup_f32 v3, v7, v3, 1.0
	v_div_scale_f32 v7, s[84:85], v2, v2, 1.0
	v_rcp_f32_e32 v9, v7
	s_nop 0
	v_fma_f32 v12, -v7, v9, 1.0
	v_fmac_f32_e32 v9, v12, v9
	v_div_scale_f32 v12, vcc, 1.0, v2, 1.0
	v_mul_f32_e32 v13, v12, v9
	v_fma_f32 v14, -v7, v13, v12
	v_fmac_f32_e32 v13, v14, v9
	v_fma_f32 v7, -v7, v13, v12
	v_div_fmas_f32 v7, v7, v9, v13
	v_div_fixup_f32 v2, v7, v2, 1.0
	v_pk_fma_f32 v[12:13], v[2:3], 2.0, -1.0 op_sel_hi:[1,0,0]
	s_nop 0
	v_cndmask_b32_e64 v7, v20, v12, s[4:5]
	v_cndmask_b32_e64 v7, v7, v2, s[0:1]
	v_add_f32_e32 v2, v5, v5
	v_cndmask_b32_e64 v2, v2, v5, s[0:1]
	v_cndmask_b32_e64 v9, v21, v13, s[4:5]
	v_mul_f32_e32 v2, 0xbfb8aa3b, v2
	v_cndmask_b32_e64 v22, v9, v3, s[0:1]
	v_exp_f32_e32 v9, v2
	s_nop 0
	v_pk_add_f32 v[2:3], v[8:9], 1.0 op_sel_hi:[1,0]
	s_nop 0
	v_div_scale_f32 v8, s[84:85], v3, v3, 1.0
	v_rcp_f32_e32 v9, v8
	s_nop 0
	v_fma_f32 v12, -v8, v9, 1.0
	v_fmac_f32_e32 v9, v12, v9
	v_div_scale_f32 v12, vcc, 1.0, v3, 1.0
	v_mul_f32_e32 v13, v12, v9
	v_fma_f32 v14, -v8, v13, v12
	v_fmac_f32_e32 v13, v14, v9
	v_fma_f32 v8, -v8, v13, v12
	v_div_fmas_f32 v8, v8, v9, v13
	v_div_fixup_f32 v3, v8, v3, 1.0
	v_div_scale_f32 v8, s[84:85], v2, v2, 1.0
	v_rcp_f32_e32 v9, v8
	s_nop 0
	v_fma_f32 v12, -v8, v9, 1.0
	v_fmac_f32_e32 v9, v12, v9
	v_div_scale_f32 v12, vcc, 1.0, v2, 1.0
	v_mul_f32_e32 v13, v12, v9
	v_fma_f32 v14, -v8, v13, v12
	v_fmac_f32_e32 v13, v14, v9
	v_fma_f32 v8, -v8, v13, v12
	v_div_fmas_f32 v8, v8, v9, v13
	v_div_fixup_f32 v2, v8, v2, 1.0
	v_pk_fma_f32 v[8:9], v[2:3], 2.0, -1.0 op_sel_hi:[1,0,0]
	v_lshlrev_b32_e32 v13, 16, v11
	v_cndmask_b32_e64 v5, v5, v9, s[4:5]
	v_cndmask_b32_e64 v4, v4, v8, s[4:5]
	v_cndmask_b32_e64 v23, v4, v2, s[0:1]
	v_cndmask_b32_e64 v28, v5, v3, s[0:1]
	v_lshlrev_b32_e32 v12, 16, v10
	v_and_b32_e32 v14, 0xffff0000, v10
	v_cndmask_b32_e64 v17, 0, v37, s[6:7]
	v_cndmask_b32_e64 v16, 0, v36, s[6:7]
	v_pk_add_f32 v[18:19], v[24:25], v[12:13] neg_lo:[0,1] neg_hi:[0,1]
	s_waitcnt vmcnt(0) lgkmcnt(0)
	v_mov_b64_e32 v[2:3], v[224:225]
	v_mov_b64_e32 v[4:5], v[226:227]
	v_mov_b64_e32 v[8:9], v[228:229]
	v_mov_b64_e32 v[10:11], v[230:231]
	v_mov_b32_e32 v20, v2
	v_mov_b32_e32 v21, v4
	v_pk_fma_f32 v[18:19], v[18:19], v[20:21], v[12:13]
	v_pk_add_f32 v[12:13], v[16:17], v[12:13] neg_lo:[0,1] neg_hi:[0,1]
	v_mov_b32_e32 v16, v8
	v_mov_b32_e32 v17, v10
	v_pk_fma_f32 v[12:13], v[12:13], v[16:17], v[18:19]
	v_cndmask_b32_e64 v17, 0, v38, s[6:7]
	v_cndmask_b32_e64 v16, 0, v39, s[6:7]
	v_pk_add_f32 v[18:19], v[26:27], v[14:15] neg_lo:[0,1] neg_hi:[0,1]
	v_mov_b32_e32 v4, v3
	v_pk_fma_f32 v[4:5], v[18:19], v[4:5], v[14:15]
	v_pk_add_f32 v[14:15], v[16:17], v[14:15] neg_lo:[0,1] neg_hi:[0,1]
	v_mov_b32_e32 v10, v9
	v_pk_fma_f32 v[4:5], v[14:15], v[10:11], v[4:5]
	v_add_f32_e32 v2, v12, v12
	v_add_f32_e32 v3, v4, v4
	v_cndmask_b32_e64 v3, v3, v4, s[0:1]
	v_mul_f32_e32 v3, 0xbfb8aa3b, v3
	v_exp_f32_e32 v8, v3
	v_add_f32_e32 v3, v13, v13
	v_cndmask_b32_e64 v2, v2, v12, s[0:1]
	v_cndmask_b32_e64 v3, v3, v13, s[0:1]
	v_mul_f32_e32 v2, 0xbfb8aa3b, v2
	v_mul_f32_e32 v3, 0xbfb8aa3b, v3
	v_exp_f32_e32 v2, v2
	v_exp_f32_e32 v3, v3
	s_nop 0
	v_pk_add_f32 v[2:3], v[2:3], 1.0 op_sel_hi:[1,0]
	s_nop 0
	v_div_scale_f32 v9, s[6:7], v3, v3, 1.0
	v_rcp_f32_e32 v10, v9
	s_nop 0
	v_fma_f32 v11, -v9, v10, 1.0
	v_fmac_f32_e32 v10, v11, v10
	v_div_scale_f32 v11, vcc, 1.0, v3, 1.0
	v_mul_f32_e32 v14, v11, v10
	v_fma_f32 v15, -v9, v14, v11
	v_fmac_f32_e32 v14, v15, v10
	v_fma_f32 v9, -v9, v14, v11
	v_div_fmas_f32 v9, v9, v10, v14
	v_div_fixup_f32 v3, v9, v3, 1.0
	v_div_scale_f32 v9, s[6:7], v2, v2, 1.0
	v_rcp_f32_e32 v10, v9
	s_nop 0
	v_fma_f32 v11, -v9, v10, 1.0
	v_fmac_f32_e32 v10, v11, v10
	v_div_scale_f32 v11, vcc, 1.0, v2, 1.0
	v_mul_f32_e32 v14, v11, v10
	v_fma_f32 v15, -v9, v14, v11
	v_fmac_f32_e32 v14, v15, v10
	v_fma_f32 v9, -v9, v14, v11
	v_div_fmas_f32 v9, v9, v10, v14
	v_div_fixup_f32 v2, v9, v2, 1.0
	v_pk_fma_f32 v[10:11], v[2:3], 2.0, -1.0 op_sel_hi:[1,0,0]
	s_nop 0
	v_cndmask_b32_e64 v9, v12, v10, s[4:5]
	v_cndmask_b32_e64 v10, v13, v11, s[4:5]
	v_cndmask_b32_e64 v11, v9, v2, s[0:1]
	v_add_f32_e32 v2, v5, v5
	v_cndmask_b32_e64 v2, v2, v5, s[0:1]
	v_mul_f32_e32 v2, 0xbfb8aa3b, v2
	v_exp_f32_e32 v9, v2
	v_cndmask_b32_e64 v10, v10, v3, s[0:1]
	v_pk_add_f32 v[2:3], v[8:9], 1.0 op_sel_hi:[1,0]
	s_nop 0
	v_div_scale_f32 v8, s[6:7], v3, v3, 1.0
	v_rcp_f32_e32 v9, v8
	s_nop 0
	v_fma_f32 v12, -v8, v9, 1.0
	v_fmac_f32_e32 v9, v12, v9
	v_div_scale_f32 v12, vcc, 1.0, v3, 1.0
	v_mul_f32_e32 v13, v12, v9
	v_fma_f32 v14, -v8, v13, v12
	v_fmac_f32_e32 v13, v14, v9
	v_fma_f32 v8, -v8, v13, v12
	v_div_fmas_f32 v8, v8, v9, v13
	v_div_fixup_f32 v3, v8, v3, 1.0
	v_div_scale_f32 v8, s[6:7], v2, v2, 1.0
	v_rcp_f32_e32 v9, v8
	s_nop 0
	v_fma_f32 v12, -v8, v9, 1.0
	v_fmac_f32_e32 v9, v12, v9
	v_div_scale_f32 v12, vcc, 1.0, v2, 1.0
	v_mul_f32_e32 v13, v12, v9
	v_fma_f32 v14, -v8, v13, v12
	v_fmac_f32_e32 v13, v14, v9
	v_fma_f32 v8, -v8, v13, v12
	v_div_fmas_f32 v8, v8, v9, v13
	v_div_fixup_f32 v2, v8, v2, 1.0
	v_pk_fma_f32 v[8:9], v[2:3], 2.0, -1.0 op_sel_hi:[1,0,0]
	v_bfe_u32 v12, v11, 16, 1
	v_cndmask_b32_e64 v5, v5, v9, s[4:5]
	v_cndmask_b32_e64 v4, v4, v8, s[4:5]
	v_cndmask_b32_e64 v2, v4, v2, s[0:1]
	v_cndmask_b32_e64 v3, v5, v3, s[0:1]
	v_bfe_u32 v4, v3, 16, 1
	v_bfe_u32 v5, v2, 16, 1
	v_add3_u32 v2, v2, v5, s60
	v_add3_u32 v3, v3, v4, s60
	v_bfe_u32 v4, v7, 16, 1
	v_bfe_u32 v5, v22, 16, 1
	v_bfe_u32 v13, v10, 16, 1
	v_bfe_u32 v8, v28, 16, 1
	v_bfe_u32 v9, v23, 16, 1
	v_add3_u32 v10, v10, v13, s60
	v_add3_u32 v11, v11, v12, s60
	v_add3_u32 v5, v22, v5, s60
	v_add3_u32 v4, v7, v4, s60
	v_add3_u32 v9, v23, v9, s60
	v_add3_u32 v8, v28, v8, s60
	v_lshrrev_b32_e32 v7, 16, v4
	v_lshrrev_b32_e32 v12, 16, v5
	v_lshrrev_b32_e32 v4, 16, v11
	v_lshrrev_b32_e32 v5, 16, v10
	v_and_or_b32 v5, v3, s56, v5
	v_and_or_b32 v4, v2, s56, v4
	v_and_or_b32 v3, v8, s56, v12
	v_and_or_b32 v2, v9, s56, v7
	ds_write_b128 v6, v[2:5] offset:4096
	s_cbranch_scc0 .LBB0_1406
	v_ashrrev_i32_e32 v137, 3, v135
	v_and_b32_e32 v138, -4, v137
	v_add_u32_e32 v18, s81, v138
	v_add_u32_e32 v0, -1, v18
	v_or_b32_e32 v44, 1, v18
	v_and_b32_e32 v126, 31, v135
	v_max_i32_e32 v0, s27, v0
	v_max_i32_e32 v2, s27, v18
	v_max_i32_e32 v10, s27, v44
	v_lshlrev_b32_e32 v34, 4, v126
	v_mov_b32_e32 v35, v65
	s_mulk_i32 s18, 0x900
	v_min_i32_e32 v0, s80, v0
	v_min_i32_e32 v2, s80, v2
	v_min_i32_e32 v10, s80, v10
	v_lshl_add_u64 v[88:89], s[54:55], 0, v[34:35]
	s_mov_b64 s[0:1], 0x7158100
	v_add_u32_e32 v0, s18, v0
	v_add_u32_e32 v2, s18, v2
	v_add_u32_e32 v10, s18, v10
	v_lshl_add_u64 v[8:9], v[88:89], 0, s[0:1]
	v_mul_hi_i32_i24_e32 v25, 0x1240, v0
	v_mul_i32_i24_e32 v24, 0x1240, v0
	v_mul_hi_i32_i24_e32 v27, 0x1240, v2
	v_mul_i32_i24_e32 v26, 0x1240, v2
	v_mul_hi_i32_i24_e32 v49, 0x1240, v10
	v_mul_i32_i24_e32 v48, 0x1240, v10
	v_lshl_add_u64 v[0:1], v[8:9], 0, v[24:25]
	v_lshl_add_u64 v[4:5], v[8:9], 0, v[26:27]
	v_lshl_add_u64 v[10:11], v[8:9], 0, v[48:49]
	v_or_b32_e32 v45, 2, v18
	global_load_dwordx4 v[0:3], v[0:1], off
	s_nop 0
	global_load_dwordx4 v[4:7], v[4:5], off
	v_or_b32_e32 v70, 3, v18
	global_load_dwordx4 v[36:39], v[10:11], off
	v_max_i32_e32 v10, s27, v45
	v_min_i32_e32 v10, s80, v10
	v_add_u32_e32 v10, s18, v10
	v_mul_hi_i32_i24_e32 v55, 0x1240, v10
	v_mul_i32_i24_e32 v54, 0x1240, v10
	v_lshl_add_u64 v[10:11], v[8:9], 0, v[54:55]
	global_load_dwordx4 v[40:43], v[10:11], off
	v_max_i32_e32 v10, s27, v70
	v_min_i32_e32 v10, s80, v10
	v_add_u32_e32 v10, s18, v10
	v_mul_hi_i32_i24_e32 v57, 0x1240, v10
	v_mul_i32_i24_e32 v56, 0x1240, v10
	v_lshl_add_u64 v[10:11], v[8:9], 0, v[56:57]
	v_add_u32_e32 v71, 4, v18
	global_load_dwordx4 v[60:63], v[10:11], off
	v_max_i32_e32 v10, s27, v71
	v_min_i32_e32 v10, s80, v10
	v_add_u32_e32 v10, s18, v10
	v_mul_hi_i32_i24_e32 v59, 0x1240, v10
	v_mul_i32_i24_e32 v58, 0x1240, v10
	v_lshl_add_u64 v[8:9], v[8:9], 0, v[58:59]
	global_load_dwordx4 v[66:69], v[8:9], off
	v_mov_b32_e32 v8, s54
	v_mov_b32_e32 v9, s55
	v_add_co_u32_e32 v32, vcc, s57, v8
	v_lshlrev_b32_e32 v64, 5, v126
	s_nop 0
	v_addc_co_u32_e32 v33, vcc, 0, v9, vcc
	v_lshl_add_u64 v[28:29], s[8:9], 0, v[64:65]
	v_add_co_u32_e32 v50, vcc, s35, v28
	v_lshl_add_u64 v[46:47], s[10:11], 0, v[64:65]
	s_nop 0
	v_addc_co_u32_e32 v51, vcc, 0, v29, vcc
	v_add_co_u32_e32 v52, vcc, s35, v46
	global_load_dwordx4 v[8:11], v[50:51], off offset:512
	s_nop 0
	v_addc_co_u32_e32 v53, vcc, 0, v47, vcc
	global_load_dwordx2 v[30:31], v[32:33], off offset:464
	global_load_dwordx4 v[12:15], v[52:53], off offset:512
	v_lshl_add_u64 v[16:17], v[28:29], 0, s[20:21]
	v_lshl_add_u64 v[20:21], v[46:47], 0, s[20:21]
	v_cmp_lt_i32_e32 vcc, s27, v18
	v_cmp_ge_i32_e64 s[0:1], s79, v18
	v_cmp_le_i32_e64 s[4:5], s27, v18
	v_cmp_gt_i32_e64 s[6:7], s79, v18
	global_load_dwordx4 v[16:19], v[16:17], off offset:16
	s_and_b64 vcc, vcc, s[0:1]
	global_load_dwordx4 v[20:23], v[20:21], off offset:16
	s_and_b64 s[4:5], s[4:5], s[6:7]
	v_cmp_le_i32_e64 s[0:1], s27, v44
	v_cmp_gt_i32_e64 s[6:7], s79, v44
	s_and_b64 s[6:7], s[0:1], s[6:7]
	v_cmp_le_i32_e64 s[0:1], s27, v45
	v_cmp_gt_i32_e64 s[8:9], s79, v45
	s_and_b64 s[8:9], s[0:1], s[8:9]
	v_cmp_le_i32_e64 s[0:1], s27, v70
	v_cmp_gt_i32_e64 s[10:11], s79, v70
	s_and_b64 s[10:11], s[0:1], s[10:11]
	v_cmp_le_i32_e64 s[0:1], s27, v71
	v_cmp_gt_i32_e64 s[12:13], s79, v71
	s_and_b64 s[12:13], s[0:1], s[12:13]
	v_add_u32_e32 v90, s26, v138
	v_ashrrev_i32_e32 v91, 31, v90
	s_mov_b32 s24, 0
	v_lshlrev_b32_e32 v126, 3, v126
	s_waitcnt vmcnt(0) lgkmcnt(0)
	v_cndmask_b32_e32 v72, 0, v1, vcc
	v_cndmask_b32_e32 v73, 0, v0, vcc
	v_cndmask_b32_e64 v77, 0, v5, s[4:5]
	v_cndmask_b32_e64 v79, 0, v4, s[4:5]
	v_cndmask_b32_e64 v80, 0, v39, s[6:7]
	v_cndmask_b32_e64 v82, 0, v38, s[6:7]
	v_cndmask_b32_e64 v38, 0, v37, s[6:7]
	v_cndmask_b32_e64 v39, 0, v36, s[6:7]
	v_and_b32_e32 v37, 0xffff0000, v72
	v_and_b32_e32 v36, 0xffff0000, v73
	v_cndmask_b32_e32 v74, 0, v3, vcc
	v_cndmask_b32_e32 v75, 0, v2, vcc
	v_cndmask_b32_e64 v76, 0, v7, s[4:5]
	v_cndmask_b32_e64 v78, 0, v6, s[4:5]
	v_lshlrev_b32_e32 v45, 16, v77
	v_lshlrev_b32_e32 v44, 16, v79
	v_and_b32_e32 v81, 0xffff0000, v80
	v_cndmask_b32_e64 v86, 0, v43, s[8:9]
	v_cndmask_b32_e64 v94, 0, v63, s[10:11]
	v_cndmask_b32_e64 v95, 0, v62, s[10:11]
	v_and_b32_e32 v63, 0xffff0000, v77
	v_and_b32_e32 v62, 0xffff0000, v79
	v_pk_add_f32 v[36:37], v[36:37], v[62:63] neg_lo:[0,1] neg_hi:[0,1]
	v_and_b32_e32 v77, 0xffff0000, v76
	v_lshlrev_b32_e32 v79, 16, v80
	v_cndmask_b32_e64 v122, 0, v69, s[12:13]
	v_cndmask_b32_e64 v123, 0, v68, s[12:13]
	v_and_b32_e32 v69, 0xffff0000, v38
	v_and_b32_e32 v68, 0xffff0000, v39
	v_cndmask_b32_e64 v118, 0, v67, s[12:13]
	v_cndmask_b32_e64 v119, 0, v66, s[12:13]
	v_lshlrev_b32_e32 v67, 16, v38
	v_lshlrev_b32_e32 v66, 16, v39
	v_pk_add_f32 v[38:39], v[66:67], v[44:45] neg_lo:[0,1] neg_hi:[0,1]
	v_and_b32_e32 v80, 0xffff0000, v82
	v_cndmask_b32_e64 v96, 0, v61, s[10:11]
	v_cndmask_b32_e64 v97, 0, v60, s[10:11]
	v_cndmask_b32_e64 v87, 0, v42, s[8:9]
	v_cndmask_b32_e64 v92, 0, v41, s[8:9]
	v_cndmask_b32_e64 v93, 0, v40, s[8:9]
	v_mov_b32_e32 v71, v10
	v_mov_b32_e32 v10, v9
	v_mov_b32_e32 v70, v8
	v_readfirstlane_b32 s1, v31
	v_readfirstlane_b32 s0, v30
	v_lshlrev_b32_e32 v31, 16, v72
	v_lshlrev_b32_e32 v30, 16, v73
	v_mov_b32_e32 v73, v14
	v_pk_fma_f32 v[8:9], v[10:11], v[36:37], v[62:63]
	v_pk_add_f32 v[36:37], v[68:69], v[62:63] neg_lo:[0,1] neg_hi:[0,1]
	v_mov_b32_e32 v14, v13
	v_pk_add_f32 v[30:31], v[30:31], v[44:45] neg_lo:[0,1] neg_hi:[0,1]
	v_mov_b32_e32 v72, v12
	v_pk_fma_f32 v[36:37], v[14:15], v[36:37], v[8:9]
	v_lshlrev_b32_e32 v9, 16, v74
	v_lshlrev_b32_e32 v8, 16, v75
	v_and_b32_e32 v13, 0xffff0000, v74
	v_and_b32_e32 v12, 0xffff0000, v75
	v_lshlrev_b32_e32 v75, 16, v76
	v_lshlrev_b32_e32 v74, 16, v78
	v_pk_fma_f32 v[30:31], v[70:71], v[30:31], v[44:45]
	v_and_b32_e32 v76, 0xffff0000, v78
	v_lshlrev_b32_e32 v78, 16, v82
	v_pk_add_f32 v[8:9], v[8:9], v[74:75] neg_lo:[0,1] neg_hi:[0,1]
	v_mov_b32_e32 v82, v16
	v_mov_b32_e32 v83, v18
	v_pk_fma_f32 v[30:31], v[72:73], v[38:39], v[30:31]
	v_pk_fma_f32 v[8:9], v[82:83], v[8:9], v[74:75]
	v_pk_add_f32 v[38:39], v[78:79], v[74:75] neg_lo:[0,1] neg_hi:[0,1]
	v_mov_b32_e32 v84, v20
	v_mov_b32_e32 v85, v22
	v_pk_fma_f32 v[98:99], v[84:85], v[38:39], v[8:9]
	v_pk_add_f32 v[8:9], v[12:13], v[76:77] neg_lo:[0,1] neg_hi:[0,1]
	v_mov_b32_e32 v18, v17
	v_pk_fma_f32 v[8:9], v[18:19], v[8:9], v[76:77]
	v_pk_add_f32 v[12:13], v[80:81], v[76:77] neg_lo:[0,1] neg_hi:[0,1]
	v_mov_b32_e32 v22, v21
	v_pk_fma_f32 v[100:101], v[22:23], v[12:13], v[8:9]
	v_bfe_u32 v8, v30, 16, 1
	v_bfe_u32 v9, v31, 16, 1
	v_bfe_u32 v12, v98, 16, 1
	v_bfe_u32 v13, v99, 16, 1
	v_lshl_add_u64 v[0:1], s[0:1], 0, v[64:65]
	s_mov_b64 s[0:1], 0x156d7900
	v_add3_u32 v13, v99, v13, s60
	v_add3_u32 v12, v98, v12, s60
	v_add3_u32 v9, v31, v9, s60
	v_add3_u32 v8, v30, v8, s60
	v_lshl_add_u64 v[60:61], v[88:89], 0, s[0:1]
	v_lshrrev_b32_e32 v8, 16, v8
	v_lshrrev_b32_e32 v9, 16, v9
	v_lshrrev_b32_e32 v12, 16, v12
	v_lshrrev_b32_e32 v13, 16, v13
	v_lshlrev_b64 v[38:39], 9, v[90:91]
	v_and_or_b32 v43, v101, s56, v13
	v_and_or_b32 v42, v100, s56, v12
	v_and_or_b32 v41, v37, s56, v9
	v_and_or_b32 v40, v36, s56, v8
	v_lshl_add_u64 v[8:9], v[60:61], 0, v[38:39]
	global_load_dwordx4 v[4:7], v[0:1], off offset:1024
	s_nop 0
	global_load_dwordx4 v[0:3], v[0:1], off offset:1040
	v_pk_add_f32 v[16:17], v[44:45], v[66:67] neg_lo:[0,1] neg_hi:[0,1]
	global_store_dwordx4 v[8:9], v[40:43], off
	v_lshlrev_b32_e32 v9, 16, v92
	v_lshlrev_b32_e32 v8, 16, v93
	v_pk_fma_f32 v[16:17], v[70:71], v[16:17], v[66:67]
	v_pk_add_f32 v[20:21], v[8:9], v[66:67] neg_lo:[0,1] neg_hi:[0,1]
	v_and_b32_e32 v13, 0xffff0000, v92
	v_and_b32_e32 v12, 0xffff0000, v93
	v_pk_fma_f32 v[102:103], v[72:73], v[20:21], v[16:17]
	v_pk_add_f32 v[16:17], v[62:63], v[68:69] neg_lo:[0,1] neg_hi:[0,1]
	v_pk_add_f32 v[20:21], v[12:13], v[68:69] neg_lo:[0,1] neg_hi:[0,1]
	v_pk_fma_f32 v[16:17], v[10:11], v[16:17], v[68:69]
	v_pk_add_f32 v[40:41], v[74:75], v[78:79] neg_lo:[0,1] neg_hi:[0,1]
	v_pk_fma_f32 v[104:105], v[14:15], v[20:21], v[16:17]
	v_lshlrev_b32_e32 v17, 16, v86
	v_lshlrev_b32_e32 v16, 16, v87
	v_pk_fma_f32 v[40:41], v[82:83], v[40:41], v[78:79]
	v_pk_add_f32 v[42:43], v[16:17], v[78:79] neg_lo:[0,1] neg_hi:[0,1]
	v_and_b32_e32 v21, 0xffff0000, v86
	v_and_b32_e32 v20, 0xffff0000, v87
	v_pk_fma_f32 v[106:107], v[84:85], v[42:43], v[40:41]
	v_pk_add_f32 v[40:41], v[76:77], v[80:81] neg_lo:[0,1] neg_hi:[0,1]
	v_pk_add_f32 v[42:43], v[20:21], v[80:81] neg_lo:[0,1] neg_hi:[0,1]
	v_pk_fma_f32 v[40:41], v[18:19], v[40:41], v[80:81]
	v_or_b32_e32 v92, 1, v90
	v_pk_fma_f32 v[108:109], v[22:23], v[42:43], v[40:41]
	v_bfe_u32 v40, v102, 16, 1
	v_bfe_u32 v41, v103, 16, 1
	v_bfe_u32 v42, v106, 16, 1
	v_bfe_u32 v43, v107, 16, 1
	v_add3_u32 v43, v107, v43, s60
	v_add3_u32 v42, v106, v42, s60
	v_add3_u32 v41, v103, v41, s60
	v_add3_u32 v40, v102, v40, s60
	v_lshrrev_b32_e32 v40, 16, v40
	v_lshrrev_b32_e32 v41, 16, v41
	v_lshrrev_b32_e32 v42, 16, v42
	v_lshrrev_b32_e32 v43, 16, v43
	v_ashrrev_i32_e32 v93, 31, v92
	v_and_or_b32 v45, v109, s56, v43
	v_and_or_b32 v44, v108, s56, v42
	v_and_or_b32 v43, v105, s56, v41
	v_and_or_b32 v42, v104, s56, v40
	v_lshlrev_b64 v[40:41], 9, v[92:93]
	v_lshl_add_u64 v[62:63], v[60:61], 0, v[40:41]
	global_store_dwordx4 v[62:63], v[42:45], off
	v_pk_add_f32 v[66:67], v[66:67], v[8:9] neg_lo:[0,1] neg_hi:[0,1]
	v_and_b32_e32 v63, 0xffff0000, v96
	v_lshlrev_b32_e32 v45, 16, v96
	v_lshlrev_b32_e32 v44, 16, v97
	v_pk_add_f32 v[42:43], v[44:45], v[8:9] neg_lo:[0,1] neg_hi:[0,1]
	v_pk_fma_f32 v[66:67], v[70:71], v[66:67], v[8:9]
	v_and_b32_e32 v62, 0xffff0000, v97
	v_pk_fma_f32 v[110:111], v[72:73], v[42:43], v[66:67]
	v_pk_add_f32 v[42:43], v[68:69], v[12:13] neg_lo:[0,1] neg_hi:[0,1]
	v_pk_add_f32 v[74:75], v[62:63], v[12:13] neg_lo:[0,1] neg_hi:[0,1]
	v_pk_fma_f32 v[42:43], v[10:11], v[42:43], v[12:13]
	v_pk_add_f32 v[68:69], v[78:79], v[16:17] neg_lo:[0,1] neg_hi:[0,1]
	v_pk_fma_f32 v[112:113], v[14:15], v[74:75], v[42:43]
	v_lshlrev_b32_e32 v75, 16, v94
	v_lshlrev_b32_e32 v74, 16, v95
	v_pk_add_f32 v[42:43], v[74:75], v[16:17] neg_lo:[0,1] neg_hi:[0,1]
	v_pk_fma_f32 v[68:69], v[82:83], v[68:69], v[16:17]
	v_and_b32_e32 v77, 0xffff0000, v94
	v_and_b32_e32 v76, 0xffff0000, v95
	v_pk_fma_f32 v[114:115], v[84:85], v[42:43], v[68:69]
	v_pk_add_f32 v[42:43], v[80:81], v[20:21] neg_lo:[0,1] neg_hi:[0,1]
	v_pk_add_f32 v[66:67], v[76:77], v[20:21] neg_lo:[0,1] neg_hi:[0,1]
	v_pk_fma_f32 v[42:43], v[18:19], v[42:43], v[20:21]
	v_or_b32_e32 v94, 2, v90
	v_pk_fma_f32 v[116:117], v[22:23], v[66:67], v[42:43]
	v_bfe_u32 v42, v110, 16, 1
	v_bfe_u32 v43, v111, 16, 1
	v_bfe_u32 v66, v114, 16, 1
	v_bfe_u32 v67, v115, 16, 1
	v_add3_u32 v67, v115, v67, s60
	v_add3_u32 v66, v114, v66, s60
	v_add3_u32 v43, v111, v43, s60
	v_add3_u32 v42, v110, v42, s60
	v_lshrrev_b32_e32 v42, 16, v42
	v_lshrrev_b32_e32 v43, 16, v43
	v_lshrrev_b32_e32 v66, 16, v66
	v_lshrrev_b32_e32 v67, 16, v67
	v_ashrrev_i32_e32 v95, 31, v94
	v_and_or_b32 v69, v117, s56, v67
	v_and_or_b32 v68, v116, s56, v66
	v_and_or_b32 v67, v113, s56, v43
	v_and_or_b32 v66, v112, s56, v42
	v_lshlrev_b64 v[42:43], 9, v[94:95]
	v_lshl_add_u64 v[78:79], v[60:61], 0, v[42:43]
	global_store_dwordx4 v[78:79], v[66:69], off
	v_pk_add_f32 v[8:9], v[8:9], v[44:45] neg_lo:[0,1] neg_hi:[0,1]
	v_pk_add_f32 v[12:13], v[12:13], v[62:63] neg_lo:[0,1] neg_hi:[0,1]
	v_lshlrev_b32_e32 v67, 16, v118
	v_lshlrev_b32_e32 v66, 16, v119
	v_and_b32_e32 v69, 0xffff0000, v118
	v_and_b32_e32 v68, 0xffff0000, v119
	v_pk_add_f32 v[66:67], v[66:67], v[44:45] neg_lo:[0,1] neg_hi:[0,1]
	v_pk_fma_f32 v[8:9], v[70:71], v[8:9], v[44:45]
	v_pk_add_f32 v[68:69], v[68:69], v[62:63] neg_lo:[0,1] neg_hi:[0,1]
	v_pk_fma_f32 v[118:119], v[72:73], v[66:67], v[8:9]
	v_pk_fma_f32 v[8:9], v[10:11], v[12:13], v[62:63]
	v_pk_add_f32 v[12:13], v[16:17], v[74:75] neg_lo:[0,1] neg_hi:[0,1]
	v_pk_fma_f32 v[120:121], v[14:15], v[68:69], v[8:9]
	v_lshlrev_b32_e32 v9, 16, v122
	v_lshlrev_b32_e32 v8, 16, v123
	v_and_b32_e32 v11, 0xffff0000, v122
	v_and_b32_e32 v10, 0xffff0000, v123
	v_pk_add_f32 v[8:9], v[8:9], v[74:75] neg_lo:[0,1] neg_hi:[0,1]
	v_pk_add_f32 v[14:15], v[20:21], v[76:77] neg_lo:[0,1] neg_hi:[0,1]
	v_pk_fma_f32 v[12:13], v[82:83], v[12:13], v[74:75]
	v_pk_add_f32 v[10:11], v[10:11], v[76:77] neg_lo:[0,1] neg_hi:[0,1]
	v_pk_fma_f32 v[122:123], v[84:85], v[8:9], v[12:13]
	v_pk_fma_f32 v[8:9], v[18:19], v[14:15], v[76:77]
	v_or_b32_e32 v96, 3, v90
	v_pk_fma_f32 v[124:125], v[22:23], v[10:11], v[8:9]
	v_bfe_u32 v8, v118, 16, 1
	v_bfe_u32 v9, v119, 16, 1
	v_bfe_u32 v10, v122, 16, 1
	v_bfe_u32 v11, v123, 16, 1
	v_add3_u32 v11, v123, v11, s60
	v_add3_u32 v10, v122, v10, s60
	v_add3_u32 v9, v119, v9, s60
	v_add3_u32 v8, v118, v8, s60
	v_ashrrev_i32_e32 v97, 31, v96
	v_lshrrev_b32_e32 v8, 16, v8
	v_lshrrev_b32_e32 v9, 16, v9
	v_lshrrev_b32_e32 v10, 16, v10
	v_lshrrev_b32_e32 v11, 16, v11
	v_lshlrev_b64 v[44:45], 9, v[96:97]
	v_and_or_b32 v11, v125, s56, v11
	v_and_or_b32 v10, v124, s56, v10
	v_and_or_b32 v9, v121, s56, v9
	v_and_or_b32 v8, v120, s56, v8
	v_lshl_add_u64 v[12:13], v[60:61], 0, v[44:45]
	global_store_dwordx4 v[12:13], v[8:11], off
	v_lshl_add_u64 v[16:17], v[28:29], 0, s[36:37]
	v_lshl_add_u64 v[20:21], v[46:47], 0, s[36:37]
	v_lshl_add_u64 v[8:9], v[88:89], 0, s[38:39]
	v_lshl_add_u64 v[10:11], v[8:9], 0, v[24:25]
	global_load_dwordx4 v[60:63], v[10:11], off
	v_lshl_add_u64 v[10:11], v[8:9], 0, v[26:27]
	global_load_dwordx4 v[66:69], v[10:11], off
	v_lshl_add_u64 v[10:11], v[8:9], 0, v[48:49]
	global_load_dwordx4 v[70:73], v[10:11], off
	v_lshl_add_u64 v[10:11], v[8:9], 0, v[54:55]
	global_load_dwordx4 v[74:77], v[10:11], off
	v_lshl_add_u64 v[10:11], v[8:9], 0, v[56:57]
	global_load_dwordx4 v[78:81], v[10:11], off
	v_lshl_add_u64 v[8:9], v[8:9], 0, v[58:59]
	global_load_dwordx4 v[82:85], v[8:9], off
	s_nop 0
	global_load_dwordx4 v[8:11], v[50:51], off offset:2560
	global_load_dwordx4 v[12:15], v[52:53], off offset:2560
	s_waitcnt vmcnt(0) lgkmcnt(0)
	v_mul_f32_e32 v159, v98, v0
	global_load_dwordx4 v[16:19], v[16:17], off offset:16
	v_mul_f32_e32 v160, v100, v1
	global_load_dwordx4 v[20:23], v[20:21], off offset:16
	v_mul_f32_e32 v161, v99, v2
	v_mul_f32_e32 v162, v101, v3
	v_mul_f32_e32 v163, v4, v102
	v_mul_f32_e32 v168, v5, v104
	v_mul_f32_e32 v169, v103, v6
	v_mul_f32_e32 v170, v105, v7
	v_mul_f32_e32 v171, v106, v0
	v_mul_f32_e32 v114, v114, v0
	v_mul_f32_e32 v187, v122, v0
	v_mul_f32_e32 v172, v108, v1
	v_mul_f32_e32 v116, v116, v1
	v_mul_f32_e32 v188, v124, v1
	v_bitop3_b32 v1, v135, 31, v130 bitop3:0xe0
	v_mul_f32_e32 v173, v107, v2
	v_mul_f32_e32 v174, v109, v3
	v_mul_f32_e32 v175, v4, v110
	v_mul_f32_e32 v176, v5, v112
	v_mul_f32_e32 v177, v6, v111
	v_mul_f32_e32 v178, v113, v7
	v_mul_f32_e32 v115, v115, v2
	v_mul_f32_e32 v117, v117, v3
	v_mul_f32_e32 v179, v4, v118
	v_mul_f32_e32 v184, v5, v120
	v_mul_f32_e32 v185, v6, v119
	v_mul_f32_e32 v186, v7, v121
	v_mul_f32_e32 v189, v123, v2
	v_mul_f32_e32 v190, v125, v3
	v_or_b32_e32 v110, 3, v137
	v_mul_lo_u32 v110, v110, s70
	v_add_u32_e32 v119, v64, v110
	v_lshlrev_b64 v[110:111], 11, v[96:97]
	v_lshl_add_u64 v[110:111], s[54:55], 0, v[110:111]
	v_cndmask_b32_e32 v136, 0, v61, vcc
	v_cndmask_b32_e32 v139, 0, v60, vcc
	v_cndmask_b32_e64 v140, 0, v69, s[4:5]
	v_cndmask_b32_e64 v141, 0, v68, s[4:5]
	v_cndmask_b32_e64 v68, 0, v67, s[4:5]
	v_cndmask_b32_e64 v69, 0, v66, s[4:5]
	v_cndmask_b32_e64 v142, 0, v73, s[6:7]
	v_cndmask_b32_e64 v143, 0, v72, s[6:7]
	v_cndmask_b32_e64 v144, 0, v71, s[6:7]
	v_cndmask_b32_e64 v145, 0, v70, s[6:7]
	v_and_b32_e32 v67, 0xffff0000, v136
	v_and_b32_e32 v66, 0xffff0000, v139
	v_and_b32_e32 v73, 0xffff0000, v68
	v_and_b32_e32 v72, 0xffff0000, v69
	v_cndmask_b32_e64 v146, 0, v77, s[8:9]
	v_cndmask_b32_e64 v147, 0, v76, s[8:9]
	v_cndmask_b32_e64 v152, 0, v79, s[10:11]
	v_and_b32_e32 v77, 0xffff0000, v144
	v_and_b32_e32 v76, 0xffff0000, v145
	v_mov_b32_e32 v79, v10
	v_pk_add_f32 v[66:67], v[66:67], v[72:73] neg_lo:[0,1] neg_hi:[0,1]
	v_mov_b32_e32 v10, v9
	v_cndmask_b32_e32 v86, 0, v63, vcc
	v_cndmask_b32_e32 v87, 0, v62, vcc
	v_cndmask_b32_e64 v150, 0, v81, s[10:11]
	v_cndmask_b32_e64 v153, 0, v78, s[10:11]
	v_mov_b32_e32 v78, v8
	v_mov_b32_e32 v81, v14
	v_pk_fma_f32 v[8:9], v[10:11], v[66:67], v[72:73]
	v_pk_add_f32 v[66:67], v[76:77], v[72:73] neg_lo:[0,1] neg_hi:[0,1]
	v_mov_b32_e32 v14, v13
	v_cndmask_b32_e64 v154, 0, v85, s[12:13]
	v_cndmask_b32_e64 v155, 0, v84, s[12:13]
	v_lshlrev_b32_e32 v63, 16, v136
	v_lshlrev_b32_e32 v62, 16, v139
	v_lshlrev_b32_e32 v71, 16, v68
	v_lshlrev_b32_e32 v70, 16, v69
	v_pk_fma_f32 v[8:9], v[14:15], v[66:67], v[8:9]
	v_and_b32_e32 v67, 0xffff0000, v86
	v_and_b32_e32 v66, 0xffff0000, v87
	v_and_b32_e32 v85, 0xffff0000, v140
	v_and_b32_e32 v84, 0xffff0000, v141
	v_cndmask_b32_e64 v148, 0, v75, s[8:9]
	v_cndmask_b32_e64 v149, 0, v74, s[8:9]
	v_cndmask_b32_e64 v151, 0, v80, s[10:11]
	v_cndmask_b32_e64 v156, 0, v83, s[12:13]
	v_cndmask_b32_e64 v157, 0, v82, s[12:13]
	v_lshlrev_b32_e32 v75, 16, v144
	v_lshlrev_b32_e32 v74, 16, v145
	v_pk_add_f32 v[62:63], v[62:63], v[70:71] neg_lo:[0,1] neg_hi:[0,1]
	v_mov_b32_e32 v80, v12
	v_lshlrev_b32_e32 v13, 16, v86
	v_lshlrev_b32_e32 v12, 16, v87
	v_lshlrev_b32_e32 v83, 16, v140
	v_lshlrev_b32_e32 v82, 16, v141
	v_lshlrev_b32_e32 v86, 16, v143
	v_and_b32_e32 v141, 0xffff0000, v142
	v_and_b32_e32 v140, 0xffff0000, v143
	s_waitcnt vmcnt(0) lgkmcnt(0)
	v_mov_b32_e32 v143, v18
	v_pk_add_f32 v[66:67], v[66:67], v[84:85] neg_lo:[0,1] neg_hi:[0,1]
	v_mov_b32_e32 v18, v17
	v_pk_fma_f32 v[62:63], v[78:79], v[62:63], v[70:71]
	v_pk_add_f32 v[68:69], v[74:75], v[70:71] neg_lo:[0,1] neg_hi:[0,1]
	v_lshlrev_b32_e32 v87, 16, v142
	v_pk_add_f32 v[12:13], v[12:13], v[82:83] neg_lo:[0,1] neg_hi:[0,1]
	v_mov_b32_e32 v142, v16
	v_mov_b32_e32 v145, v22
	v_pk_fma_f32 v[16:17], v[18:19], v[66:67], v[84:85]
	v_pk_add_f32 v[66:67], v[140:141], v[84:85] neg_lo:[0,1] neg_hi:[0,1]
	v_mov_b32_e32 v22, v21
	v_pk_fma_f32 v[62:63], v[80:81], v[68:69], v[62:63]
	v_pk_fma_f32 v[12:13], v[142:143], v[12:13], v[82:83]
	v_pk_add_f32 v[68:69], v[86:87], v[82:83] neg_lo:[0,1] neg_hi:[0,1]
	v_mov_b32_e32 v144, v20
	v_pk_fma_f32 v[16:17], v[22:23], v[66:67], v[16:17]
	v_pk_fma_f32 v[12:13], v[144:145], v[68:69], v[12:13]
	v_bfe_u32 v20, v17, 16, 1
	v_bfe_u32 v21, v16, 16, 1
	v_bfe_u32 v66, v9, 16, 1
	v_bfe_u32 v67, v8, 16, 1
	v_add3_u32 v8, v8, v67, s60
	v_add3_u32 v9, v9, v66, s60
	v_add3_u32 v16, v16, v21, s60
	v_add3_u32 v17, v17, v20, s60
	v_bfe_u32 v20, v62, 16, 1
	v_bfe_u32 v21, v63, 16, 1
	v_bfe_u32 v66, v12, 16, 1
	v_bfe_u32 v67, v13, 16, 1
	v_add3_u32 v13, v13, v67, s60
	v_add3_u32 v12, v12, v66, s60
	v_add3_u32 v21, v63, v21, s60
	v_add3_u32 v20, v62, v20, s60
	v_lshl_add_u64 v[60:61], v[88:89], 0, s[40:41]
	v_lshrrev_b32_e32 v20, 16, v20
	v_lshrrev_b32_e32 v21, 16, v21
	v_lshrrev_b32_e32 v12, 16, v12
	v_lshrrev_b32_e32 v13, 16, v13
	v_and_or_b32 v69, v17, s56, v13
	v_and_or_b32 v68, v16, s56, v12
	v_and_or_b32 v67, v9, s56, v21
	v_and_or_b32 v66, v8, s56, v20
	v_lshl_add_u64 v[8:9], v[60:61], 0, v[38:39]
	global_store_dwordx4 v[8:9], v[66:69], off
	v_lshlrev_b32_e32 v9, 16, v148
	v_lshlrev_b32_e32 v8, 16, v149
	v_pk_add_f32 v[16:17], v[70:71], v[74:75] neg_lo:[0,1] neg_hi:[0,1]
	v_pk_add_f32 v[20:21], v[8:9], v[74:75] neg_lo:[0,1] neg_hi:[0,1]
	v_pk_fma_f32 v[16:17], v[78:79], v[16:17], v[74:75]
	v_and_b32_e32 v13, 0xffff0000, v148
	v_and_b32_e32 v12, 0xffff0000, v149
	v_pk_fma_f32 v[16:17], v[80:81], v[20:21], v[16:17]
	v_pk_add_f32 v[20:21], v[72:73], v[76:77] neg_lo:[0,1] neg_hi:[0,1]
	v_pk_add_f32 v[62:63], v[12:13], v[76:77] neg_lo:[0,1] neg_hi:[0,1]
	v_pk_fma_f32 v[20:21], v[10:11], v[20:21], v[76:77]
	v_pk_add_f32 v[66:67], v[82:83], v[86:87] neg_lo:[0,1] neg_hi:[0,1]
	v_pk_fma_f32 v[20:21], v[14:15], v[62:63], v[20:21]
	v_lshlrev_b32_e32 v63, 16, v146
	v_lshlrev_b32_e32 v62, 16, v147
	v_pk_fma_f32 v[66:67], v[142:143], v[66:67], v[86:87]
	v_pk_add_f32 v[68:69], v[62:63], v[86:87] neg_lo:[0,1] neg_hi:[0,1]
	v_and_b32_e32 v71, 0xffff0000, v146
	v_and_b32_e32 v70, 0xffff0000, v147
	v_pk_fma_f32 v[66:67], v[144:145], v[68:69], v[66:67]
	v_pk_add_f32 v[68:69], v[84:85], v[140:141] neg_lo:[0,1] neg_hi:[0,1]
	v_pk_add_f32 v[72:73], v[70:71], v[140:141] neg_lo:[0,1] neg_hi:[0,1]
	v_pk_fma_f32 v[68:69], v[18:19], v[68:69], v[140:141]
	v_bfe_u32 v82, v21, 16, 1
	v_pk_fma_f32 v[68:69], v[22:23], v[72:73], v[68:69]
	v_bfe_u32 v83, v20, 16, 1
	v_bfe_u32 v72, v69, 16, 1
	v_bfe_u32 v73, v68, 16, 1
	v_add3_u32 v20, v20, v83, s60
	v_add3_u32 v21, v21, v82, s60
	v_add3_u32 v68, v68, v73, s60
	v_add3_u32 v69, v69, v72, s60
	v_bfe_u32 v72, v16, 16, 1
	v_bfe_u32 v73, v17, 16, 1
	v_bfe_u32 v82, v66, 16, 1
	v_bfe_u32 v83, v67, 16, 1
	v_add3_u32 v67, v67, v83, s60
	v_add3_u32 v66, v66, v82, s60
	v_add3_u32 v17, v17, v73, s60
	v_add3_u32 v16, v16, v72, s60
	v_lshrrev_b32_e32 v16, 16, v16
	v_lshrrev_b32_e32 v17, 16, v17
	v_lshrrev_b32_e32 v66, 16, v66
	v_lshrrev_b32_e32 v67, 16, v67
	v_and_or_b32 v69, v69, s56, v67
	v_and_or_b32 v68, v68, s56, v66
	v_and_or_b32 v67, v21, s56, v17
	v_and_or_b32 v66, v20, s56, v16
	v_lshl_add_u64 v[16:17], v[60:61], 0, v[40:41]
	global_store_dwordx4 v[16:17], v[66:69], off
	v_lshlrev_b32_e32 v17, 16, v152
	v_lshlrev_b32_e32 v16, 16, v153
	v_pk_add_f32 v[72:73], v[74:75], v[8:9] neg_lo:[0,1] neg_hi:[0,1]
	v_pk_add_f32 v[66:67], v[16:17], v[8:9] neg_lo:[0,1] neg_hi:[0,1]
	v_pk_fma_f32 v[72:73], v[78:79], v[72:73], v[8:9]
	v_and_b32_e32 v21, 0xffff0000, v152
	v_and_b32_e32 v20, 0xffff0000, v153
	v_pk_fma_f32 v[66:67], v[80:81], v[66:67], v[72:73]
	v_pk_add_f32 v[72:73], v[76:77], v[12:13] neg_lo:[0,1] neg_hi:[0,1]
	v_pk_add_f32 v[68:69], v[20:21], v[12:13] neg_lo:[0,1] neg_hi:[0,1]
	v_pk_fma_f32 v[72:73], v[10:11], v[72:73], v[12:13]
	v_pk_add_f32 v[84:85], v[86:87], v[62:63] neg_lo:[0,1] neg_hi:[0,1]
	v_pk_fma_f32 v[68:69], v[14:15], v[68:69], v[72:73]
	v_lshlrev_b32_e32 v73, 16, v150
	v_lshlrev_b32_e32 v72, 16, v151
	v_pk_add_f32 v[76:77], v[72:73], v[62:63] neg_lo:[0,1] neg_hi:[0,1]
	v_pk_fma_f32 v[84:85], v[142:143], v[84:85], v[62:63]
	v_and_b32_e32 v75, 0xffff0000, v150
	v_and_b32_e32 v74, 0xffff0000, v151
	v_pk_fma_f32 v[76:77], v[144:145], v[76:77], v[84:85]
	v_pk_add_f32 v[84:85], v[140:141], v[70:71] neg_lo:[0,1] neg_hi:[0,1]
	v_pk_add_f32 v[82:83], v[74:75], v[70:71] neg_lo:[0,1] neg_hi:[0,1]
	v_pk_fma_f32 v[84:85], v[18:19], v[84:85], v[70:71]
	v_bfe_u32 v86, v69, 16, 1
	v_pk_fma_f32 v[82:83], v[22:23], v[82:83], v[84:85]
	v_bfe_u32 v87, v68, 16, 1
	v_bfe_u32 v84, v83, 16, 1
	v_bfe_u32 v85, v82, 16, 1
	v_add3_u32 v87, v68, v87, s60
	v_add3_u32 v86, v69, v86, s60
	v_add3_u32 v68, v82, v85, s60
	v_add3_u32 v69, v83, v84, s60
	v_bfe_u32 v82, v66, 16, 1
	v_bfe_u32 v83, v67, 16, 1
	v_bfe_u32 v84, v76, 16, 1
	v_bfe_u32 v85, v77, 16, 1
	v_add3_u32 v77, v77, v85, s60
	v_add3_u32 v76, v76, v84, s60
	v_add3_u32 v67, v67, v83, s60
	v_add3_u32 v66, v66, v82, s60
	v_lshrrev_b32_e32 v66, 16, v66
	v_lshrrev_b32_e32 v67, 16, v67
	v_lshrrev_b32_e32 v76, 16, v76
	v_lshrrev_b32_e32 v77, 16, v77
	v_and_or_b32 v69, v69, s56, v77
	v_and_or_b32 v68, v68, s56, v76
	v_and_or_b32 v67, v86, s56, v67
	v_and_or_b32 v66, v87, s56, v66
	v_lshl_add_u64 v[76:77], v[60:61], 0, v[42:43]
	global_store_dwordx4 v[76:77], v[66:69], off
	v_pk_add_f32 v[8:9], v[8:9], v[16:17] neg_lo:[0,1] neg_hi:[0,1]
	v_pk_add_f32 v[12:13], v[12:13], v[20:21] neg_lo:[0,1] neg_hi:[0,1]
	v_lshlrev_b32_e32 v67, 16, v156
	v_lshlrev_b32_e32 v66, 16, v157
	v_and_b32_e32 v69, 0xffff0000, v156
	v_and_b32_e32 v68, 0xffff0000, v157
	v_pk_add_f32 v[66:67], v[66:67], v[16:17] neg_lo:[0,1] neg_hi:[0,1]
	v_pk_add_f32 v[68:69], v[68:69], v[20:21] neg_lo:[0,1] neg_hi:[0,1]
	v_pk_fma_f32 v[8:9], v[78:79], v[8:9], v[16:17]
	v_pk_fma_f32 v[10:11], v[10:11], v[12:13], v[20:21]
	v_lshlrev_b32_e32 v13, 16, v154
	v_lshlrev_b32_e32 v12, 16, v155
	v_pk_add_f32 v[16:17], v[62:63], v[72:73] neg_lo:[0,1] neg_hi:[0,1]
	v_pk_fma_f32 v[10:11], v[14:15], v[68:69], v[10:11]
	v_and_b32_e32 v15, 0xffff0000, v154
	v_and_b32_e32 v14, 0xffff0000, v155
	v_pk_add_f32 v[12:13], v[12:13], v[72:73] neg_lo:[0,1] neg_hi:[0,1]
	v_pk_add_f32 v[20:21], v[70:71], v[74:75] neg_lo:[0,1] neg_hi:[0,1]
	v_pk_fma_f32 v[16:17], v[142:143], v[16:17], v[72:73]
	v_pk_add_f32 v[14:15], v[14:15], v[74:75] neg_lo:[0,1] neg_hi:[0,1]
	v_pk_fma_f32 v[12:13], v[144:145], v[12:13], v[16:17]
	v_pk_fma_f32 v[16:17], v[18:19], v[20:21], v[74:75]
	v_pk_fma_f32 v[8:9], v[80:81], v[66:67], v[8:9]
	v_pk_fma_f32 v[14:15], v[22:23], v[14:15], v[16:17]
	v_bfe_u32 v18, v11, 16, 1
	v_bfe_u32 v16, v15, 16, 1
	v_bfe_u32 v17, v14, 16, 1
	v_bfe_u32 v19, v10, 16, 1
	v_add3_u32 v19, v10, v19, s60
	v_add3_u32 v18, v11, v18, s60
	v_add3_u32 v10, v14, v17, s60
	v_add3_u32 v11, v15, v16, s60
	v_bfe_u32 v14, v8, 16, 1
	v_bfe_u32 v15, v9, 16, 1
	v_bfe_u32 v16, v12, 16, 1
	v_bfe_u32 v17, v13, 16, 1
	v_add3_u32 v13, v13, v17, s60
	v_add3_u32 v12, v12, v16, s60
	v_add3_u32 v9, v9, v15, s60
	v_add3_u32 v8, v8, v14, s60
	v_lshrrev_b32_e32 v8, 16, v8
	v_lshrrev_b32_e32 v9, 16, v9
	v_lshrrev_b32_e32 v12, 16, v12
	v_lshrrev_b32_e32 v13, 16, v13
	v_and_or_b32 v11, v11, s56, v13
	v_and_or_b32 v10, v10, s56, v12
	v_and_or_b32 v9, v18, s56, v9
	v_and_or_b32 v8, v19, s56, v8
	v_lshl_add_u64 v[12:13], v[60:61], 0, v[44:45]
	global_store_dwordx4 v[12:13], v[8:11], off
	v_lshl_add_u64 v[12:13], v[88:89], 0, s[44:45]
	v_lshl_add_u64 v[14:15], v[12:13], 0, v[26:27]
	v_lshl_add_u64 v[8:9], v[12:13], 0, v[24:25]
	global_load_dwordx4 v[8:11], v[8:9], off
	v_lshl_add_u64 v[26:27], v[28:29], 0, s[42:43]
	global_load_dwordx4 v[22:25], v[14:15], off
	v_lshl_add_u64 v[14:15], v[12:13], 0, v[48:49]
	global_load_dwordx4 v[60:63], v[14:15], off
	v_lshl_add_u64 v[14:15], v[12:13], 0, v[54:55]
	global_load_dwordx4 v[66:69], v[14:15], off
	v_lshl_add_u64 v[14:15], v[12:13], 0, v[56:57]
	global_load_dwordx4 v[54:57], v[14:15], off
	v_lshl_add_u64 v[12:13], v[12:13], 0, v[58:59]
	global_load_dwordx4 v[70:73], v[12:13], off
	s_nop 0
	global_load_dwordx2 v[12:13], v[32:33], off offset:448
	global_load_dwordx4 v[18:21], v[50:51], off offset:1536
	global_load_dwordx4 v[14:17], v[52:53], off offset:1536
	v_lshl_add_u64 v[28:29], v[46:47], 0, s[42:43]
	v_lshl_add_u64 v[52:53], v[88:89], 0, s[46:47]
	v_lshl_add_u64 v[46:47], v[52:53], 0, v[38:39]
	v_lshl_add_u64 v[48:49], v[52:53], 0, v[40:41]
	v_lshl_add_u64 v[50:51], v[52:53], 0, v[42:43]
	v_lshl_add_u64 v[52:53], v[52:53], 0, v[44:45]
	v_and_b32_e32 v136, 0xffffffc0, v135
	s_waitcnt vmcnt(0) lgkmcnt(0)
	v_cndmask_b32_e32 v82, 0, v9, vcc
	v_cndmask_b32_e32 v83, 0, v8, vcc
	v_cndmask_b32_e64 v147, 0, v25, s[4:5]
	v_cndmask_b32_e64 v148, 0, v24, s[4:5]
	v_cndmask_b32_e64 v58, 0, v23, s[4:5]
	v_cndmask_b32_e64 v59, 0, v22, s[4:5]
	global_load_dwordx4 v[22:25], v[26:27], off offset:16
	v_cndmask_b32_e32 v139, 0, v11, vcc
	global_load_dwordx4 v[26:29], v[28:29], off offset:16
	v_cndmask_b32_e64 v55, 0, v55, s[10:11]
	v_cndmask_b32_e64 v54, 0, v54, s[10:11]
	v_cndmask_b32_e32 v146, 0, v10, vcc
	v_cndmask_b32_e64 v61, 0, v61, s[6:7]
	v_cndmask_b32_e64 v60, 0, v60, s[6:7]
	v_cndmask_b32_e64 v153, 0, v57, s[10:11]
	v_cndmask_b32_e64 v154, 0, v56, s[10:11]
	v_cndmask_b32_e64 v157, 0, v71, s[12:13]
	v_cndmask_b32_e64 v158, 0, v70, s[12:13]
	v_lshlrev_b32_e32 v8, 16, v83
	v_lshlrev_b32_e32 v9, 16, v82
	v_lshlrev_b32_e32 v10, 16, v59
	v_lshlrev_b32_e32 v11, 16, v58
	v_lshlrev_b32_e32 v70, 16, v54
	v_lshlrev_b32_e32 v71, 16, v55
	v_readfirstlane_b32 s1, v13
	v_readfirstlane_b32 s0, v12
	v_and_b32_e32 v79, 0xffff0000, v55
	v_and_b32_e32 v78, 0xffff0000, v54
	v_and_b32_e32 v55, 0xffff0000, v58
	v_and_b32_e32 v54, 0xffff0000, v59
	v_and_b32_e32 v57, 0xffff0000, v82
	v_and_b32_e32 v56, 0xffff0000, v83
	v_cndmask_b32_e64 v149, 0, v63, s[6:7]
	v_cndmask_b32_e64 v150, 0, v62, s[6:7]
	v_lshlrev_b32_e32 v62, 16, v60
	v_lshlrev_b32_e32 v63, 16, v61
	v_lshl_add_u64 v[12:13], s[0:1], 0, v[64:65]
	v_pk_add_f32 v[8:9], v[8:9], v[10:11] neg_lo:[0,1] neg_hi:[0,1]
	v_pk_add_f32 v[56:57], v[56:57], v[54:55] neg_lo:[0,1] neg_hi:[0,1]
	v_mov_b32_e32 v82, v18
	v_mov_b32_e32 v83, v20
	v_mov_b32_e32 v20, v19
	v_pk_add_f32 v[58:59], v[10:11], v[62:63] neg_lo:[0,1] neg_hi:[0,1]
	v_pk_fma_f32 v[140:141], v[82:83], v[8:9], v[10:11]
	v_pk_fma_f32 v[18:19], v[20:21], v[56:57], v[54:55]
	v_pk_add_f32 v[56:57], v[62:63], v[10:11] neg_lo:[0,1] neg_hi:[0,1]
	global_load_dwordx4 v[8:11], v[12:13], off offset:1024
	v_mov_b32_e32 v144, v14
	v_mov_b32_e32 v145, v16
	v_mov_b32_e32 v16, v15
	global_load_dwordx4 v[12:15], v[12:13], off offset:1040
	v_cndmask_b32_e64 v67, 0, v67, s[8:9]
	v_cndmask_b32_e64 v66, 0, v66, s[8:9]
	v_cndmask_b32_e64 v151, 0, v69, s[8:9]
	v_cndmask_b32_e64 v152, 0, v68, s[8:9]
	v_lshlrev_b32_e32 v68, 16, v66
	v_lshlrev_b32_e32 v69, 16, v67
	v_and_b32_e32 v77, 0xffff0000, v67
	v_and_b32_e32 v76, 0xffff0000, v66
	v_and_b32_e32 v67, 0xffff0000, v61
	v_and_b32_e32 v66, 0xffff0000, v60
	v_pk_add_f32 v[142:143], v[66:67], v[54:55] neg_lo:[0,1] neg_hi:[0,1]
	v_pk_add_f32 v[60:61], v[54:55], v[66:67] neg_lo:[0,1] neg_hi:[0,1]
	v_pk_fma_f32 v[54:55], v[144:145], v[56:57], v[140:141]
	v_pk_fma_f32 v[56:57], v[16:17], v[142:143], v[18:19]
	v_pk_fma_f32 v[18:19], v[82:83], v[58:59], v[62:63]
	v_pk_add_f32 v[58:59], v[68:69], v[62:63] neg_lo:[0,1] neg_hi:[0,1]
	v_and_b32_e32 v141, 0xffff0000, v157
	v_pk_fma_f32 v[58:59], v[144:145], v[58:59], v[18:19]
	v_pk_fma_f32 v[18:19], v[20:21], v[60:61], v[66:67]
	v_pk_add_f32 v[60:61], v[76:77], v[66:67] neg_lo:[0,1] neg_hi:[0,1]
	v_and_b32_e32 v140, 0xffff0000, v158
	v_pk_fma_f32 v[60:61], v[16:17], v[60:61], v[18:19]
	v_pk_add_f32 v[18:19], v[62:63], v[68:69] neg_lo:[0,1] neg_hi:[0,1]
	v_pk_add_f32 v[62:63], v[70:71], v[68:69] neg_lo:[0,1] neg_hi:[0,1]
	v_pk_fma_f32 v[18:19], v[82:83], v[18:19], v[68:69]
	v_pk_add_f32 v[68:69], v[68:69], v[70:71] neg_lo:[0,1] neg_hi:[0,1]
	v_pk_fma_f32 v[62:63], v[144:145], v[62:63], v[18:19]
	v_pk_add_f32 v[18:19], v[66:67], v[76:77] neg_lo:[0,1] neg_hi:[0,1]
	v_pk_add_f32 v[66:67], v[78:79], v[76:77] neg_lo:[0,1] neg_hi:[0,1]
	v_pk_fma_f32 v[18:19], v[20:21], v[18:19], v[76:77]
	v_pk_fma_f32 v[68:69], v[82:83], v[68:69], v[70:71]
	v_pk_fma_f32 v[66:67], v[16:17], v[66:67], v[18:19]
	v_lshlrev_b32_e32 v19, 16, v157
	v_lshlrev_b32_e32 v18, 16, v158
	v_pk_add_f32 v[18:19], v[18:19], v[70:71] neg_lo:[0,1] neg_hi:[0,1]
	v_cndmask_b32_e64 v155, 0, v73, s[12:13]
	v_pk_fma_f32 v[68:69], v[144:145], v[18:19], v[68:69]
	v_pk_add_f32 v[18:19], v[76:77], v[78:79] neg_lo:[0,1] neg_hi:[0,1]
	v_cndmask_b32_e64 v156, 0, v72, s[12:13]
	v_lshlrev_b32_e32 v74, 16, v146
	v_lshlrev_b32_e32 v75, 16, v139
	v_lshlrev_b32_e32 v72, 16, v148
	v_lshlrev_b32_e32 v73, 16, v147
	v_pk_fma_f32 v[18:19], v[20:21], v[18:19], v[78:79]
	v_pk_add_f32 v[20:21], v[140:141], v[78:79] neg_lo:[0,1] neg_hi:[0,1]
	v_and_b32_e32 v77, 0xffff0000, v147
	v_and_b32_e32 v76, 0xffff0000, v148
	v_and_b32_e32 v141, 0xffff0000, v139
	v_and_b32_e32 v140, 0xffff0000, v146
	v_lshlrev_b32_e32 v80, 16, v150
	v_lshlrev_b32_e32 v81, 16, v149
	v_pk_fma_f32 v[70:71], v[16:17], v[20:21], v[18:19]
	v_and_b32_e32 v17, 0xffff0000, v149
	v_and_b32_e32 v16, 0xffff0000, v150
	v_pk_add_f32 v[74:75], v[74:75], v[72:73] neg_lo:[0,1] neg_hi:[0,1]
	v_pk_add_f32 v[140:141], v[140:141], v[76:77] neg_lo:[0,1] neg_hi:[0,1]
	s_waitcnt vmcnt(0) lgkmcnt(0)
	v_mov_b32_e32 v142, v22
	v_mov_b32_e32 v143, v24
	v_mov_b32_e32 v24, v23
	v_lshlrev_b32_e32 v86, 16, v152
	v_lshlrev_b32_e32 v87, 16, v151
	v_pk_add_f32 v[78:79], v[72:73], v[80:81] neg_lo:[0,1] neg_hi:[0,1]
	v_pk_add_f32 v[82:83], v[76:77], v[16:17] neg_lo:[0,1] neg_hi:[0,1]
	v_pk_fma_f32 v[74:75], v[142:143], v[74:75], v[72:73]
	v_pk_fma_f32 v[22:23], v[24:25], v[140:141], v[76:77]
	v_pk_add_f32 v[72:73], v[80:81], v[72:73] neg_lo:[0,1] neg_hi:[0,1]
	v_pk_add_f32 v[76:77], v[16:17], v[76:77] neg_lo:[0,1] neg_hi:[0,1]
	v_mov_b32_e32 v140, v26
	v_mov_b32_e32 v141, v28
	v_mov_b32_e32 v28, v27
	v_and_b32_e32 v19, 0xffff0000, v151
	v_and_b32_e32 v18, 0xffff0000, v152
	v_pk_fma_f32 v[72:73], v[140:141], v[72:73], v[74:75]
	v_pk_fma_f32 v[74:75], v[28:29], v[76:77], v[22:23]
	v_pk_fma_f32 v[22:23], v[142:143], v[78:79], v[80:81]
	v_pk_add_f32 v[26:27], v[86:87], v[80:81] neg_lo:[0,1] neg_hi:[0,1]
	v_lshlrev_b32_e32 v84, 16, v154
	v_pk_fma_f32 v[76:77], v[140:141], v[26:27], v[22:23]
	v_pk_fma_f32 v[22:23], v[24:25], v[82:83], v[16:17]
	v_pk_add_f32 v[26:27], v[18:19], v[16:17] neg_lo:[0,1] neg_hi:[0,1]
	v_lshlrev_b32_e32 v85, 16, v153
	v_pk_fma_f32 v[78:79], v[28:29], v[26:27], v[22:23]
	v_pk_add_f32 v[22:23], v[80:81], v[86:87] neg_lo:[0,1] neg_hi:[0,1]
	v_and_b32_e32 v21, 0xffff0000, v153
	v_and_b32_e32 v20, 0xffff0000, v154
	v_pk_fma_f32 v[22:23], v[142:143], v[22:23], v[86:87]
	v_pk_add_f32 v[26:27], v[84:85], v[86:87] neg_lo:[0,1] neg_hi:[0,1]
	v_pk_add_f32 v[16:17], v[16:17], v[18:19] neg_lo:[0,1] neg_hi:[0,1]
	v_pk_fma_f32 v[80:81], v[140:141], v[26:27], v[22:23]
	v_pk_fma_f32 v[16:17], v[24:25], v[16:17], v[18:19]
	v_pk_add_f32 v[22:23], v[20:21], v[18:19] neg_lo:[0,1] neg_hi:[0,1]
	v_and_b32_e32 v27, 0xffff0000, v155
	v_pk_fma_f32 v[82:83], v[28:29], v[22:23], v[16:17]
	v_pk_add_f32 v[16:17], v[86:87], v[84:85] neg_lo:[0,1] neg_hi:[0,1]
	v_lshlrev_b32_e32 v23, 16, v155
	v_pk_fma_f32 v[86:87], v[142:143], v[16:17], v[84:85]
	v_mov_b32_e32 v16, v8
	v_mov_b32_e32 v17, v10
	v_mov_b32_e32 v10, v9
	v_pk_mul_f32 v[142:143], v[16:17], v[54:55]
	v_pk_mul_f32 v[144:145], v[56:57], v[10:11]
	v_mov_b32_e32 v8, v143
	v_mov_b32_e32 v9, v145
	v_pk_mul_f32 v[146:147], v[8:9], v[8:9]
	v_mov_b32_e32 v8, v12
	v_mov_b32_e32 v9, v14
	v_mov_b32_e32 v14, v13
	v_mul_f32_e32 v139, v142, v142
	v_pk_mul_f32 v[148:149], v[72:73], v[8:9]
	v_pk_mul_f32 v[12:13], v[74:75], v[14:15]
	v_fmac_f32_e32 v139, v144, v144
	v_mov_b32_e32 v150, v148
	v_mov_b32_e32 v151, v12
	v_add_f32_e32 v139, v139, v146
	v_pk_mul_f32 v[150:151], v[150:151], v[150:151]
	v_add_f32_e32 v139, v139, v147
	v_mov_b32_e32 v152, v149
	v_mov_b32_e32 v153, v13
	v_add_f32_e32 v139, v139, v150
	v_pk_mul_f32 v[152:153], v[152:153], v[152:153]
	v_add_f32_e32 v139, v139, v151
	v_add_f32_e32 v139, v139, v152
	v_add_f32_e32 v139, v139, v153
	v_lshlrev_b32_e32 v22, 16, v156
	v_pk_add_f32 v[22:23], v[22:23], v[84:85] neg_lo:[0,1] neg_hi:[0,1]
	v_add_f32_dpp v139, v139, v139 quad_perm:[1,0,3,2] row_mask:0xf bank_mask:0xf bound_ctrl:1
	v_pk_fma_f32 v[84:85], v[140:141], v[22:23], v[86:87]
	v_and_b32_e32 v26, 0xffff0000, v156
	v_add_f32_dpp v139, v139, v139 quad_perm:[2,3,0,1] row_mask:0xf bank_mask:0xf bound_ctrl:1
	v_pk_add_f32 v[18:19], v[18:19], v[20:21] neg_lo:[0,1] neg_hi:[0,1]
	v_pk_mul_f32 v[140:141], v[78:79], v[14:15]
	v_add_f32_dpp v139, v139, v139 row_half_mirror row_mask:0xf bank_mask:0xf bound_ctrl:1
	v_mul_f32_e32 v146, 0x4f800000, v139
	v_cmp_gt_f32_e32 vcc, s71, v139
	v_pk_fma_f32 v[18:19], v[24:25], v[18:19], v[20:21]
	v_pk_add_f32 v[20:21], v[26:27], v[20:21] neg_lo:[0,1] neg_hi:[0,1]
	v_cndmask_b32_e32 v139, v139, v146, vcc
	v_sqrt_f32_e32 v146, v139
	v_mul_f32_e32 v156, v36, v5
	v_mul_f32_e32 v157, v31, v6
	v_mul_f32_e32 v158, v37, v7
	v_add_u32_e32 v22, -1, v146
	v_fma_f32 v23, -v22, v146, v139
	v_cmp_ge_f32_e64 s[0:1], 0, v23
	v_add_u32_e32 v23, 1, v146
	v_fma_f32 v86, -v23, v146, v139
	v_cndmask_b32_e64 v22, v146, v22, s[0:1]
	v_cmp_lt_f32_e64 s[0:1], 0, v86
	v_pk_fma_f32 v[86:87], v[28:29], v[20:21], v[18:19]
	v_pk_mul_f32 v[28:29], v[76:77], v[8:9]
	v_cndmask_b32_e64 v22, v22, v23, s[0:1]
	v_mul_f32_e32 v23, 0x37800000, v22
	v_cndmask_b32_e32 v22, v22, v23, vcc
	v_cmp_class_f32_e32 vcc, v139, v128
	v_lshlrev_b64 v[36:37], 11, v[94:95]
	v_lshl_add_u64 v[36:37], s[54:55], 0, v[36:37]
	v_cndmask_b32_e32 v22, v22, v139, vcc
	v_max_f32_e32 v22, 0x2b8cbccc, v22
	v_div_scale_f32 v23, s[0:1], v22, v22, 1.0
	v_rcp_f32_e32 v139, v23
	v_lshl_add_u64 v[36:37], v[36:37], 0, v[34:35]
	v_mul_f32_e32 v121, v156, v56
	v_mul_f32_e32 v122, v157, v55
	v_fma_f32 v18, -v23, v139, 1.0
	v_fmac_f32_e32 v139, v18, v139
	v_div_scale_f32 v18, vcc, 1.0, v22, 1.0
	v_mul_f32_e32 v19, v18, v139
	v_fma_f32 v20, -v23, v19, v18
	v_fmac_f32_e32 v19, v20, v139
	v_fma_f32 v18, -v23, v19, v18
	v_div_fmas_f32 v18, v18, v139, v19
	v_div_fixup_f32 v18, v18, v22, 1.0
	v_pk_mul_f32 v[20:21], v[142:143], v[18:19] op_sel_hi:[1,0]
	v_pk_mul_f32 v[22:23], v[148:149], v[18:19] op_sel_hi:[1,0]
	v_bfe_u32 v19, v20, 16, 1
	v_bfe_u32 v24, v21, 16, 1
	v_bfe_u32 v25, v22, 16, 1
	v_bfe_u32 v26, v23, 16, 1
	v_add3_u32 v23, v23, v26, s60
	v_add3_u32 v22, v22, v25, s60
	v_add3_u32 v21, v21, v24, s60
	v_add3_u32 v19, v20, v19, s60
	v_pk_mul_f32 v[24:25], v[58:59], v[16:17]
	v_pk_mul_f32 v[26:27], v[60:61], v[10:11]
	v_lshrrev_b32_e32 v139, 16, v19
	v_lshrrev_b32_e32 v19, 16, v21
	v_mov_b32_e32 v20, v27
	v_mov_b32_e32 v21, v25
	v_mul_f32_e32 v148, v24, v24
	v_pk_mul_f32 v[20:21], v[20:21], v[20:21]
	v_fmac_f32_e32 v148, v26, v26
	v_mov_b32_e32 v142, v140
	v_mov_b32_e32 v143, v28
	v_add_f32_e32 v21, v21, v148
	v_pk_mul_f32 v[142:143], v[142:143], v[142:143]
	v_add_f32_e32 v20, v20, v21
	v_lshrrev_b32_e32 v146, 16, v22
	v_lshrrev_b32_e32 v147, 16, v23
	v_pk_mul_f32 v[22:23], v[144:145], v[18:19] op_sel_hi:[1,0]
	v_mov_b32_e32 v144, v141
	v_mov_b32_e32 v145, v29
	v_add_f32_e32 v20, v143, v20
	v_pk_mul_f32 v[144:145], v[144:145], v[144:145]
	v_add_f32_e32 v20, v142, v20
	v_add_f32_e32 v20, v145, v20
	v_add_f32_e32 v20, v144, v20
	v_pk_mul_f32 v[12:13], v[12:13], v[18:19] op_sel_hi:[1,0]
	v_and_or_b32 v19, v23, s56, v19
	v_add_f32_dpp v20, v20, v20 quad_perm:[1,0,3,2] row_mask:0xf bank_mask:0xf bound_ctrl:1
	v_mul_f32_e32 v123, v158, v57
	v_mul_f32_e32 v124, v163, v58
	v_add_f32_dpp v20, v20, v20 quad_perm:[2,3,0,1] row_mask:0xf bank_mask:0xf bound_ctrl:1
	v_mul_f32_e32 v125, v168, v60
	v_mul_f32_e32 v137, v169, v59
	v_add_f32_dpp v20, v20, v20 row_half_mirror row_mask:0xf bank_mask:0xf bound_ctrl:1
	v_mul_f32_e32 v21, 0x4f800000, v20
	v_cmp_gt_f32_e32 vcc, s71, v20
	v_mul_f32_e32 v156, v116, v82
	v_mul_f32_e32 v157, v115, v81
	v_cndmask_b32_e32 v142, v20, v21, vcc
	v_sqrt_f32_e32 v143, v142
	v_and_or_b32 v20, v12, s56, v146
	v_and_or_b32 v21, v13, s56, v147
	v_mul_f32_e32 v158, v117, v83
	v_add_u32_e32 v12, -1, v143
	v_fma_f32 v13, -v12, v143, v142
	v_cmp_ge_f32_e64 s[0:1], 0, v13
	v_add_u32_e32 v13, 1, v143
	v_fma_f32 v18, -v13, v143, v142
	v_cndmask_b32_e64 v12, v143, v12, s[0:1]
	v_cmp_lt_f32_e64 s[0:1], 0, v18
	v_and_or_b32 v18, v22, s56, v139
	global_store_dwordx4 v[46:47], v[18:21], off
	v_cndmask_b32_e64 v12, v12, v13, s[0:1]
	v_mul_f32_e32 v13, 0x37800000, v12
	v_cndmask_b32_e32 v12, v12, v13, vcc
	v_cmp_class_f32_e32 vcc, v142, v128
	s_nop 1
	v_cndmask_b32_e32 v12, v12, v142, vcc
	v_max_f32_e32 v12, 0x2b8cbccc, v12
	v_div_scale_f32 v13, s[0:1], v12, v12, 1.0
	v_rcp_f32_e32 v142, v13
	s_nop 0
	v_fma_f32 v18, -v13, v142, 1.0
	v_fmac_f32_e32 v142, v18, v142
	v_div_scale_f32 v18, vcc, 1.0, v12, 1.0
	v_mul_f32_e32 v19, v18, v142
	v_fma_f32 v20, -v13, v19, v18
	v_fmac_f32_e32 v19, v20, v142
	v_fma_f32 v13, -v13, v19, v18
	v_div_fmas_f32 v13, v13, v142, v19
	v_div_fixup_f32 v12, v13, v12, 1.0
	v_pk_mul_f32 v[18:19], v[24:25], v[12:13] op_sel_hi:[1,0]
	v_pk_mul_f32 v[20:21], v[28:29], v[12:13] op_sel_hi:[1,0]
	v_bfe_u32 v13, v18, 16, 1
	v_bfe_u32 v22, v19, 16, 1
	v_bfe_u32 v23, v20, 16, 1
	v_bfe_u32 v24, v21, 16, 1
	v_add3_u32 v21, v21, v24, s60
	v_add3_u32 v20, v20, v23, s60
	v_add3_u32 v19, v19, v22, s60
	v_add3_u32 v13, v18, v13, s60
	v_pk_mul_f32 v[22:23], v[16:17], v[62:63]
	v_pk_mul_f32 v[24:25], v[66:67], v[10:11]
	v_lshrrev_b32_e32 v139, 16, v13
	v_lshrrev_b32_e32 v146, 16, v19
	v_lshrrev_b32_e32 v147, 16, v20
	v_lshrrev_b32_e32 v148, 16, v21
	v_pk_mul_f32 v[18:19], v[26:27], v[12:13] op_sel_hi:[1,0]
	v_mov_b32_e32 v20, v25
	v_mov_b32_e32 v21, v23
	v_mul_f32_e32 v13, v22, v22
	v_pk_mul_f32 v[20:21], v[20:21], v[20:21]
	v_pk_mul_f32 v[26:27], v[80:81], v[8:9]
	v_pk_mul_f32 v[28:29], v[82:83], v[14:15]
	v_fmac_f32_e32 v13, v24, v24
	v_mov_b32_e32 v142, v28
	v_mov_b32_e32 v143, v26
	v_add_f32_e32 v13, v21, v13
	v_pk_mul_f32 v[142:143], v[142:143], v[142:143]
	v_add_f32_e32 v13, v20, v13
	v_mov_b32_e32 v144, v29
	v_mov_b32_e32 v145, v27
	v_add_f32_e32 v13, v143, v13
	v_pk_mul_f32 v[144:145], v[144:145], v[144:145]
	v_add_f32_e32 v13, v142, v13
	v_add_f32_e32 v13, v145, v13
	v_add_f32_e32 v13, v144, v13
	v_and_or_b32 v19, v19, s56, v146
	v_and_or_b32 v18, v18, s56, v139
	v_add_f32_dpp v13, v13, v13 quad_perm:[1,0,3,2] row_mask:0xf bank_mask:0xf bound_ctrl:1
	v_pk_mul_f32 v[16:17], v[16:17], v[68:69]
	v_pk_mul_f32 v[14:15], v[86:87], v[14:15]
	v_add_f32_dpp v13, v13, v13 quad_perm:[2,3,0,1] row_mask:0xf bank_mask:0xf bound_ctrl:1
	s_nop 1
	v_add_f32_dpp v13, v13, v13 row_half_mirror row_mask:0xf bank_mask:0xf bound_ctrl:1
	v_mul_f32_e32 v20, 0x4f800000, v13
	v_cmp_gt_f32_e32 vcc, s71, v13
	s_nop 1
	v_cndmask_b32_e32 v142, v13, v20, vcc
	v_sqrt_f32_e32 v143, v142
	v_pk_mul_f32 v[12:13], v[140:141], v[12:13] op_sel_hi:[1,0]
	s_nop 0
	v_and_or_b32 v20, v12, s56, v147
	v_add_u32_e32 v12, -1, v143
	v_and_or_b32 v21, v13, s56, v148
	v_fma_f32 v13, -v12, v143, v142
	v_cmp_ge_f32_e64 s[0:1], 0, v13
	v_add_u32_e32 v13, 1, v143
	v_fma_f32 v140, -v13, v143, v142
	v_cndmask_b32_e64 v12, v143, v12, s[0:1]
	v_cmp_lt_f32_e64 s[0:1], 0, v140
	global_store_dwordx4 v[48:49], v[18:21], off
	s_nop 0
	v_cndmask_b32_e64 v12, v12, v13, s[0:1]
	v_mul_f32_e32 v13, 0x37800000, v12
	v_cndmask_b32_e32 v12, v12, v13, vcc
	v_cmp_class_f32_e32 vcc, v142, v128
	s_nop 1
	v_cndmask_b32_e32 v12, v12, v142, vcc
	v_max_f32_e32 v12, 0x2b8cbccc, v12
	v_div_scale_f32 v13, s[0:1], v12, v12, 1.0
	v_rcp_f32_e32 v140, v13
	s_nop 0
	v_fma_f32 v18, -v13, v140, 1.0
	v_fmac_f32_e32 v140, v18, v140
	v_div_scale_f32 v18, vcc, 1.0, v12, 1.0
	v_mul_f32_e32 v19, v18, v140
	v_fma_f32 v20, -v13, v19, v18
	v_fmac_f32_e32 v19, v20, v140
	v_fma_f32 v13, -v13, v19, v18
	v_div_fmas_f32 v13, v13, v140, v19
	v_div_fixup_f32 v12, v13, v12, 1.0
	v_pk_mul_f32 v[20:21], v[26:27], v[12:13] op_sel_hi:[1,0]
	v_pk_mul_f32 v[18:19], v[22:23], v[12:13] op_sel_hi:[1,0]
	v_bfe_u32 v23, v20, 16, 1
	v_bfe_u32 v26, v21, 16, 1
	v_add3_u32 v21, v21, v26, s60
	v_add3_u32 v20, v20, v23, s60
	v_lshrrev_b32_e32 v27, 16, v20
	v_lshrrev_b32_e32 v139, 16, v21
	v_pk_mul_f32 v[20:21], v[10:11], v[70:71]
	v_bfe_u32 v22, v19, 16, 1
	v_mov_b32_e32 v10, v21
	v_mov_b32_e32 v11, v17
	v_mul_f32_e32 v140, v16, v16
	v_bfe_u32 v13, v18, 16, 1
	v_add3_u32 v19, v19, v22, s60
	v_pk_mul_f32 v[10:11], v[10:11], v[10:11]
	v_pk_mul_f32 v[22:23], v[84:85], v[8:9]
	v_fmac_f32_e32 v140, v20, v20
	v_add3_u32 v13, v18, v13, s60
	v_mov_b32_e32 v8, v14
	v_mov_b32_e32 v9, v22
	v_add_f32_e32 v11, v11, v140
	v_lshrrev_b32_e32 v13, 16, v13
	v_pk_mul_f32 v[8:9], v[8:9], v[8:9]
	v_add_f32_e32 v10, v10, v11
	v_lshrrev_b32_e32 v26, 16, v19
	v_pk_mul_f32 v[18:19], v[24:25], v[12:13] op_sel_hi:[1,0]
	v_mov_b32_e32 v24, v15
	v_mov_b32_e32 v25, v23
	v_add_f32_e32 v9, v9, v10
	v_pk_mul_f32 v[24:25], v[24:25], v[24:25]
	v_add_f32_e32 v8, v8, v9
	v_add_f32_e32 v8, v25, v8
	v_add_f32_e32 v8, v24, v8
	s_nop 1
	v_add_f32_dpp v8, v8, v8 quad_perm:[1,0,3,2] row_mask:0xf bank_mask:0xf bound_ctrl:1
	s_nop 1
	v_add_f32_dpp v8, v8, v8 quad_perm:[2,3,0,1] row_mask:0xf bank_mask:0xf bound_ctrl:1
	s_nop 1
	v_add_f32_dpp v8, v8, v8 row_half_mirror row_mask:0xf bank_mask:0xf bound_ctrl:1
	v_mul_f32_e32 v9, 0x4f800000, v8
	v_cmp_gt_f32_e32 vcc, s71, v8
	s_nop 1
	v_cndmask_b32_e32 v24, v8, v9, vcc
	v_sqrt_f32_e32 v25, v24
	v_pk_mul_f32 v[8:9], v[28:29], v[12:13] op_sel_hi:[1,0]
	s_nop 0
	v_and_or_b32 v10, v8, s56, v27
	v_add_u32_e32 v8, -1, v25
	v_and_or_b32 v11, v9, s56, v139
	v_fma_f32 v9, -v8, v25, v24
	v_cmp_ge_f32_e64 s[0:1], 0, v9
	v_add_u32_e32 v9, 1, v25
	v_fma_f32 v12, -v9, v25, v24
	v_cndmask_b32_e64 v8, v25, v8, s[0:1]
	v_cmp_lt_f32_e64 s[0:1], 0, v12
	v_mul_f32_e32 v139, v4, v30
	v_mul_f32_e32 v120, v139, v54
	v_cndmask_b32_e64 v8, v8, v9, s[0:1]
	v_mul_f32_e32 v9, 0x37800000, v8
	v_cndmask_b32_e32 v8, v8, v9, vcc
	v_cmp_class_f32_e32 vcc, v24, v128
	v_and_or_b32 v9, v19, s56, v26
	v_mul_f32_e32 v139, v175, v62
	v_cndmask_b32_e32 v8, v8, v24, vcc
	v_max_f32_e32 v12, 0x2b8cbccc, v8
	v_div_scale_f32 v24, s[0:1], v12, v12, 1.0
	v_rcp_f32_e32 v25, v24
	v_and_or_b32 v8, v18, s56, v13
	global_store_dwordx4 v[50:51], v[8:11], off
	s_nop 1
	v_fma_f32 v8, -v24, v25, 1.0
	v_fmac_f32_e32 v25, v8, v25
	v_div_scale_f32 v8, vcc, 1.0, v12, 1.0
	v_mul_f32_e32 v9, v8, v25
	v_fma_f32 v10, -v24, v9, v8
	v_fmac_f32_e32 v9, v10, v25
	v_fma_f32 v8, -v24, v9, v8
	v_div_fmas_f32 v8, v8, v25, v9
	v_div_fixup_f32 v8, v8, v12, 1.0
	v_pk_mul_f32 v[10:11], v[16:17], v[8:9] op_sel_hi:[1,0]
	v_pk_mul_f32 v[12:13], v[22:23], v[8:9] op_sel_hi:[1,0]
	v_bfe_u32 v9, v10, 16, 1
	v_bfe_u32 v16, v11, 16, 1
	v_bfe_u32 v17, v12, 16, 1
	v_bfe_u32 v18, v13, 16, 1
	v_add3_u32 v13, v13, v18, s60
	v_add3_u32 v12, v12, v17, s60
	v_add3_u32 v11, v11, v16, s60
	v_add3_u32 v9, v10, v9, s60
	v_lshrrev_b32_e32 v16, 16, v9
	v_lshrrev_b32_e32 v17, 16, v11
	v_lshrrev_b32_e32 v10, 16, v12
	v_lshrrev_b32_e32 v11, 16, v13
	v_pk_mul_f32 v[12:13], v[20:21], v[8:9] op_sel_hi:[1,0]
	v_pk_mul_f32 v[8:9], v[14:15], v[8:9] op_sel_hi:[1,0]
	v_lshlrev_b64 v[24:25], 11, v[90:91]
	v_and_or_b32 v11, v9, s56, v11
	v_and_or_b32 v10, v8, s56, v10
	v_and_or_b32 v9, v13, s56, v17
	v_and_or_b32 v8, v12, s56, v16
	global_store_dwordx4 v[52:53], v[8:11], off
	s_waitcnt lgkmcnt(0)
	s_barrier
	v_mov_b32_e32 v8, v65
	v_lshl_add_u64 v[24:25], s[54:55], 0, v[24:25]
	v_mbcnt_lo_u32_b32 v8, -1, v8
	v_mbcnt_hi_u32_b32 v10, -1, v8
	v_and_b32_e32 v20, 31, v10
	v_or_b32_e32 v8, v20, v136
	v_ashrrev_i32_e32 v9, 31, v8
	v_ashrrev_i32_e32 v10, 2, v10
	v_lshlrev_b64 v[8:9], 8, v[8:9]
	v_and_b32_e32 v12, -8, v10
	v_lshl_add_u64 v[8:9], s[54:55], 0, v[8:9]
	v_ashrrev_i32_e32 v13, 31, v12
	v_lshl_add_u64 v[14:15], v[12:13], 1, v[8:9]
	v_add_co_u32_e32 v8, vcc, s72, v14
	v_lshl_add_u64 v[166:167], v[14:15], 0, s[48:49]
	s_nop 0
	v_addc_co_u32_e32 v9, vcc, 0, v15, vcc
	v_add_co_u32_e32 v164, vcc, s73, v14
	global_load_dwordx4 v[8:11], v[8:9], off
	s_nop 0
	v_addc_co_u32_e32 v165, vcc, 0, v15, vcc
	global_load_dwordx4 v[16:19], v[164:165], off
	global_load_dwordx4 v[140:143], v[166:167], off offset:32
	global_load_dwordx4 v[144:147], v[164:165], off offset:32
	global_load_dwordx4 v[148:151], v[166:167], off offset:64
	global_load_dwordx4 v[98:101], v[166:167], off offset:96
	global_load_dwordx4 v[152:155], v[164:165], off offset:64
	global_load_dwordx4 v[102:105], v[164:165], off offset:96
	v_lshlrev_b32_e32 v0, 1, v12
	v_mad_u32_u24 v191, v20, s65, v0
	ds_read_b128 v[20:23], v191
	ds_read_b128 v[106:109], v191 offset:32
	v_lshrrev_b32_e32 v0, 3, v135
	v_and_b32_e32 v0, 4, v0
	v_mul_u32_u24_e32 v0, 0x410, v0
	v_lshl_add_u64 v[180:181], v[24:25], 0, v[34:35]
	v_lshlrev_b64 v[24:25], 11, v[92:93]
	v_lshl_add_u32 v192, v1, 2, v0
	v_mul_lo_u32 v0, v138, s70
	v_lshl_add_u64 v[24:25], s[54:55], 0, v[24:25]
	v_add_u32_e32 v118, v64, v0
	s_waitcnt vmcnt(0) lgkmcnt(0)
	v_mfma_f32_32x32x16_bf16 v[0:15], v[20:23], v[8:11], 0
	v_lshl_add_u64 v[182:183], v[24:25], 0, v[34:35]
	v_lshl_add_u64 v[34:35], v[110:111], 0, v[34:35]
	ds_read_b128 v[110:113], v191 offset:64
	v_mul_f32_e32 v138, v170, v61
	v_mfma_f32_32x32x16_bf16 v[16:31], v[20:23], v[16:19], 0
	v_mfma_f32_32x32x16_bf16 v[0:15], v[106:109], v[140:143], v[0:15]
	v_mul_f32_e32 v140, v176, v66
	v_mul_f32_e32 v141, v177, v63
	v_mul_f32_e32 v142, v178, v67
	v_mul_f32_e32 v143, v179, v68
	v_mfma_f32_32x32x16_bf16 v[16:31], v[106:109], v[144:147], v[16:31]
	ds_read_b128 v[106:109], v191 offset:96
	v_mul_f32_e32 v144, v184, v70
	v_mul_f32_e32 v145, v185, v69
	v_mul_f32_e32 v146, v186, v71
	v_mul_f32_e32 v147, v159, v72
	v_mul_f32_e32 v159, v187, v84
	s_waitcnt lgkmcnt(1)
	v_mfma_f32_32x32x16_bf16 v[0:15], v[110:113], v[148:151], v[0:15]
	v_mul_f32_e32 v148, v160, v74
	v_mul_f32_e32 v149, v161, v73
	v_mul_f32_e32 v150, v162, v75
	v_mul_f32_e32 v151, v171, v76
	v_mul_f32_e32 v160, v188, v86
	v_mul_f32_e32 v161, v189, v85
	v_mul_f32_e32 v162, v190, v87
	v_mfma_f32_32x32x16_bf16 v[16:31], v[110:113], v[152:155], v[16:31]
	v_mul_f32_e32 v152, v172, v78
	v_mul_f32_e32 v153, v173, v77
	v_mul_f32_e32 v154, v174, v79
	v_mul_f32_e32 v155, v114, v80
	s_waitcnt lgkmcnt(0)
	v_mfma_f32_32x32x16_bf16 v[0:15], v[106:109], v[98:101], v[0:15]
	v_mfma_f32_32x32x16_bf16 v[16:31], v[106:109], v[102:105], v[16:31]
	global_load_dwordx4 v[98:101], v[166:167], off offset:128
	global_load_dwordx4 v[102:105], v[164:165], off offset:128
	ds_read_b128 v[106:109], v191 offset:128
	ds_read_b128 v[114:117], v191 offset:160
	global_load_dwordx4 v[110:113], v[166:167], off offset:160
	s_waitcnt vmcnt(0) lgkmcnt(0)
	v_mfma_f32_32x32x16_bf16 v[0:15], v[106:109], v[98:101], v[0:15]
	global_load_dwordx4 v[98:101], v[164:165], off offset:160
	v_mfma_f32_32x32x16_bf16 v[16:31], v[106:109], v[102:105], v[16:31]
	global_load_dwordx4 v[102:105], v[166:167], off offset:192
	global_load_dwordx4 v[106:109], v[164:165], off offset:192
	v_mfma_f32_32x32x16_bf16 v[0:15], v[114:117], v[110:113], v[0:15]
	ds_read_b128 v[110:113], v191 offset:192
	s_waitcnt vmcnt(0) lgkmcnt(0)
	v_mfma_f32_32x32x16_bf16 v[16:31], v[114:117], v[98:101], v[16:31]
	global_load_dwordx4 v[98:101], v[166:167], off offset:224
	ds_read_b128 v[114:117], v191 offset:224
	v_mfma_f32_32x32x16_bf16 v[0:15], v[110:113], v[102:105], v[0:15]
	global_load_dwordx4 v[102:105], v[164:165], off offset:224
	v_mfma_f32_32x32x16_bf16 v[16:31], v[110:113], v[106:109], v[16:31]
	s_waitcnt vmcnt(0) lgkmcnt(0)
	v_mfma_f32_32x32x16_bf16 v[0:15], v[114:117], v[98:101], v[0:15]
	v_mfma_f32_32x32x16_bf16 v[16:31], v[114:117], v[102:105], v[16:31]
	v_add_u32_e32 v163, 0x6000, v192
	v_add_u32_e32 v164, 0x6400, v192
	v_add_u32_e32 v165, 0x6800, v192
	v_add_u32_e32 v166, 0x6c00, v192
	v_add_u32_e32 v167, 0x8000, v192
	v_add_u32_e32 v168, 0x8400, v192
	v_add_u32_e32 v169, 0x8800, v192
	v_add_u32_e32 v170, 0x8c00, v192
	v_add_u32_e32 v171, 0xa000, v192
	v_add_u32_e32 v172, 0xa400, v192
	v_add_u32_e32 v173, 0xa800, v192
	v_add_u32_e32 v174, 0xac00, v192
	v_add_u32_e32 v175, 0xc200, v192
	v_add_u32_e32 v176, 0xc600, v192
	v_add_u32_e32 v177, 0xca00, v192
	v_add_u32_e32 v178, 0xce00, v192
	ds_write2_b32 v163, v0, v16 offset0:128 offset1:160
	ds_write2_b32 v164, v1, v17 offset0:132 offset1:164
	ds_write2_b32 v165, v2, v18 offset0:136 offset1:168
	ds_write2_b32 v166, v3, v19 offset0:140 offset1:172
	ds_write2_b32 v167, v4, v20 offset0:160 offset1:192
	ds_write2_b32 v168, v5, v21 offset0:164 offset1:196
	ds_write2_b32 v169, v6, v22 offset0:168 offset1:200
	ds_write2_b32 v170, v7, v23 offset0:172 offset1:204
	ds_write2_b32 v171, v8, v24 offset0:192 offset1:224
	ds_write2_b32 v172, v9, v25 offset0:196 offset1:228
	ds_write2_b32 v173, v10, v26 offset0:200 offset1:232
	ds_write2_b32 v174, v11, v27 offset0:204 offset1:236
	ds_write2_b32 v175, v12, v28 offset0:96 offset1:128
	ds_write2_b32 v176, v13, v29 offset0:100 offset1:132
	ds_write2_b32 v177, v14, v30 offset0:104 offset1:136
	ds_write2_b32 v178, v15, v31 offset0:108 offset1:140
	s_waitcnt lgkmcnt(0)
	s_barrier
	ds_read_b128 v[0:3], v118 offset:25088
	ds_read_b128 v[4:7], v118 offset:25104
	s_add_u32 s79, s54, 0x1b0d7900
	s_addc_u32 s80, s55, 0
	s_add_u32 s81, s54, 0x1d4d7900
	s_waitcnt lgkmcnt(1)
	v_and_b32_sdwa v8, v2, v134 dst_sel:DWORD dst_unused:UNUSED_PAD src0_sel:WORD_1 src1_sel:DWORD
	v_and_b32_sdwa v9, v0, v134 dst_sel:DWORD dst_unused:UNUSED_PAD src0_sel:WORD_1 src1_sel:DWORD
	v_add3_u32 v2, v2, v8, s60
	v_and_b32_sdwa v8, v3, v134 dst_sel:DWORD dst_unused:UNUSED_PAD src0_sel:WORD_1 src1_sel:DWORD
	v_add3_u32 v0, v0, v9, s60
	v_and_b32_sdwa v9, v1, v134 dst_sel:DWORD dst_unused:UNUSED_PAD src0_sel:WORD_1 src1_sel:DWORD
	v_add3_u32 v3, v3, v8, s60
	v_add3_u32 v1, v1, v9, s60
	v_and_b32_e32 v3, 0xffff0000, v3
	v_and_b32_e32 v8, 0xffff0000, v1
	v_or_b32_sdwa v1, v3, v2 dst_sel:DWORD dst_unused:UNUSED_PAD src0_sel:DWORD src1_sel:WORD_1
	s_waitcnt lgkmcnt(0)
	v_and_b32_sdwa v2, v6, v134 dst_sel:DWORD dst_unused:UNUSED_PAD src0_sel:WORD_1 src1_sel:DWORD
	v_and_b32_sdwa v3, v4, v134 dst_sel:DWORD dst_unused:UNUSED_PAD src0_sel:WORD_1 src1_sel:DWORD
	v_add3_u32 v4, v4, v3, s60
	v_add3_u32 v2, v6, v2, s60
	v_and_b32_sdwa v3, v7, v134 dst_sel:DWORD dst_unused:UNUSED_PAD src0_sel:WORD_1 src1_sel:DWORD
	v_and_b32_sdwa v6, v5, v134 dst_sel:DWORD dst_unused:UNUSED_PAD src0_sel:WORD_1 src1_sel:DWORD
	v_add3_u32 v3, v7, v3, s60
	v_add3_u32 v5, v5, v6, s60
	v_and_b32_e32 v3, 0xffff0000, v3
	v_and_b32_e32 v5, 0xffff0000, v5
	v_or_b32_sdwa v3, v3, v2 dst_sel:DWORD dst_unused:UNUSED_PAD src0_sel:DWORD src1_sel:WORD_1
	v_or_b32_sdwa v2, v5, v4 dst_sel:DWORD dst_unused:UNUSED_PAD src0_sel:DWORD src1_sel:WORD_1
	v_add_co_u32_e32 v4, vcc, s75, v180
	v_or_b32_sdwa v0, v8, v0 dst_sel:DWORD dst_unused:UNUSED_PAD src0_sel:DWORD src1_sel:WORD_1
	s_nop 0
	v_addc_co_u32_e32 v5, vcc, 0, v181, vcc
	global_store_dwordx4 v[4:5], v[0:3], off offset:2816
	ds_read_b128 v[0:3], v118 offset:26128
	ds_read_b128 v[4:7], v118 offset:26144
	s_addc_u32 s82, s55, 0
	s_add_u32 s83, s54, 0x1738000
	s_addc_u32 s84, s55, 0
	s_waitcnt lgkmcnt(0)
	v_and_b32_sdwa v8, v2, v134 dst_sel:DWORD dst_unused:UNUSED_PAD src0_sel:WORD_1 src1_sel:DWORD
	v_and_b32_sdwa v9, v0, v134 dst_sel:DWORD dst_unused:UNUSED_PAD src0_sel:WORD_1 src1_sel:DWORD
	v_add3_u32 v2, v2, v8, s60
	v_and_b32_sdwa v8, v3, v134 dst_sel:DWORD dst_unused:UNUSED_PAD src0_sel:WORD_1 src1_sel:DWORD
	v_add3_u32 v0, v0, v9, s60
	v_and_b32_sdwa v9, v1, v134 dst_sel:DWORD dst_unused:UNUSED_PAD src0_sel:WORD_1 src1_sel:DWORD
	v_add3_u32 v3, v3, v8, s60
	v_add3_u32 v1, v1, v9, s60
	v_and_b32_e32 v3, 0xffff0000, v3
	v_and_b32_e32 v8, 0xffff0000, v1
	v_or_b32_sdwa v1, v3, v2 dst_sel:DWORD dst_unused:UNUSED_PAD src0_sel:DWORD src1_sel:WORD_1
	v_and_b32_sdwa v2, v6, v134 dst_sel:DWORD dst_unused:UNUSED_PAD src0_sel:WORD_1 src1_sel:DWORD
	v_and_b32_sdwa v3, v4, v134 dst_sel:DWORD dst_unused:UNUSED_PAD src0_sel:WORD_1 src1_sel:DWORD
	v_add3_u32 v4, v4, v3, s60
	v_add3_u32 v2, v6, v2, s60
	v_and_b32_sdwa v3, v7, v134 dst_sel:DWORD dst_unused:UNUSED_PAD src0_sel:WORD_1 src1_sel:DWORD
	v_and_b32_sdwa v6, v5, v134 dst_sel:DWORD dst_unused:UNUSED_PAD src0_sel:WORD_1 src1_sel:DWORD
	v_add3_u32 v3, v7, v3, s60
	v_add3_u32 v5, v5, v6, s60
	v_and_b32_e32 v3, 0xffff0000, v3
	v_and_b32_e32 v5, 0xffff0000, v5
	v_or_b32_sdwa v3, v3, v2 dst_sel:DWORD dst_unused:UNUSED_PAD src0_sel:DWORD src1_sel:WORD_1
	v_or_b32_sdwa v2, v5, v4 dst_sel:DWORD dst_unused:UNUSED_PAD src0_sel:DWORD src1_sel:WORD_1
	v_add_co_u32_e32 v4, vcc, s75, v182
	v_or_b32_sdwa v0, v8, v0 dst_sel:DWORD dst_unused:UNUSED_PAD src0_sel:DWORD src1_sel:WORD_1
	s_nop 0
	v_addc_co_u32_e32 v5, vcc, 0, v183, vcc
	global_store_dwordx4 v[4:5], v[0:3], off offset:2816
	ds_read_b128 v[0:3], v118 offset:27168
	ds_read_b128 v[4:7], v118 offset:27184
	v_lshl_add_u64 v[88:89], v[88:89], 0, s[50:51]
	s_mov_b64 s[8:9], -1
	s_waitcnt lgkmcnt(0)
	v_and_b32_sdwa v8, v2, v134 dst_sel:DWORD dst_unused:UNUSED_PAD src0_sel:WORD_1 src1_sel:DWORD
	v_and_b32_sdwa v9, v0, v134 dst_sel:DWORD dst_unused:UNUSED_PAD src0_sel:WORD_1 src1_sel:DWORD
	v_add3_u32 v2, v2, v8, s60
	v_and_b32_sdwa v8, v3, v134 dst_sel:DWORD dst_unused:UNUSED_PAD src0_sel:WORD_1 src1_sel:DWORD
	v_add3_u32 v0, v0, v9, s60
	v_and_b32_sdwa v9, v1, v134 dst_sel:DWORD dst_unused:UNUSED_PAD src0_sel:WORD_1 src1_sel:DWORD
	v_add3_u32 v3, v3, v8, s60
	v_add3_u32 v1, v1, v9, s60
	v_and_b32_e32 v3, 0xffff0000, v3
	v_and_b32_e32 v8, 0xffff0000, v1
	v_or_b32_sdwa v1, v3, v2 dst_sel:DWORD dst_unused:UNUSED_PAD src0_sel:DWORD src1_sel:WORD_1
	v_and_b32_sdwa v2, v6, v134 dst_sel:DWORD dst_unused:UNUSED_PAD src0_sel:WORD_1 src1_sel:DWORD
	v_and_b32_sdwa v3, v4, v134 dst_sel:DWORD dst_unused:UNUSED_PAD src0_sel:WORD_1 src1_sel:DWORD
	v_add3_u32 v4, v4, v3, s60
	v_add3_u32 v2, v6, v2, s60
	v_and_b32_sdwa v3, v7, v134 dst_sel:DWORD dst_unused:UNUSED_PAD src0_sel:WORD_1 src1_sel:DWORD
	v_and_b32_sdwa v6, v5, v134 dst_sel:DWORD dst_unused:UNUSED_PAD src0_sel:WORD_1 src1_sel:DWORD
	v_add3_u32 v3, v7, v3, s60
	v_add3_u32 v5, v5, v6, s60
	v_and_b32_e32 v3, 0xffff0000, v3
	v_and_b32_e32 v5, 0xffff0000, v5
	v_or_b32_sdwa v3, v3, v2 dst_sel:DWORD dst_unused:UNUSED_PAD src0_sel:DWORD src1_sel:WORD_1
	v_or_b32_sdwa v2, v5, v4 dst_sel:DWORD dst_unused:UNUSED_PAD src0_sel:DWORD src1_sel:WORD_1
	v_add_co_u32_e32 v4, vcc, s75, v36
	v_or_b32_sdwa v0, v8, v0 dst_sel:DWORD dst_unused:UNUSED_PAD src0_sel:DWORD src1_sel:WORD_1
	s_nop 0
	v_addc_co_u32_e32 v5, vcc, 0, v37, vcc
	global_store_dwordx4 v[4:5], v[0:3], off offset:2816
	ds_read_b128 v[0:3], v119 offset:25088
	ds_read_b128 v[4:7], v119 offset:25104
	s_waitcnt lgkmcnt(0)
	v_and_b32_sdwa v8, v2, v134 dst_sel:DWORD dst_unused:UNUSED_PAD src0_sel:WORD_1 src1_sel:DWORD
	v_and_b32_sdwa v9, v0, v134 dst_sel:DWORD dst_unused:UNUSED_PAD src0_sel:WORD_1 src1_sel:DWORD
	v_add3_u32 v2, v2, v8, s60
	v_and_b32_sdwa v8, v3, v134 dst_sel:DWORD dst_unused:UNUSED_PAD src0_sel:WORD_1 src1_sel:DWORD
	v_add3_u32 v0, v0, v9, s60
	v_and_b32_sdwa v9, v1, v134 dst_sel:DWORD dst_unused:UNUSED_PAD src0_sel:WORD_1 src1_sel:DWORD
	v_add3_u32 v3, v3, v8, s60
	v_add3_u32 v1, v1, v9, s60
	v_and_b32_e32 v3, 0xffff0000, v3
	v_and_b32_e32 v8, 0xffff0000, v1
	v_or_b32_sdwa v1, v3, v2 dst_sel:DWORD dst_unused:UNUSED_PAD src0_sel:DWORD src1_sel:WORD_1
	v_and_b32_sdwa v2, v6, v134 dst_sel:DWORD dst_unused:UNUSED_PAD src0_sel:WORD_1 src1_sel:DWORD
	v_and_b32_sdwa v3, v4, v134 dst_sel:DWORD dst_unused:UNUSED_PAD src0_sel:WORD_1 src1_sel:DWORD
	v_add3_u32 v4, v4, v3, s60
	v_add3_u32 v2, v6, v2, s60
	v_and_b32_sdwa v3, v7, v134 dst_sel:DWORD dst_unused:UNUSED_PAD src0_sel:WORD_1 src1_sel:DWORD
	v_and_b32_sdwa v6, v5, v134 dst_sel:DWORD dst_unused:UNUSED_PAD src0_sel:WORD_1 src1_sel:DWORD
	v_add3_u32 v3, v7, v3, s60
	v_add3_u32 v5, v5, v6, s60
	v_and_b32_e32 v3, 0xffff0000, v3
	v_and_b32_e32 v5, 0xffff0000, v5
	v_or_b32_sdwa v3, v3, v2 dst_sel:DWORD dst_unused:UNUSED_PAD src0_sel:DWORD src1_sel:WORD_1
	v_or_b32_sdwa v2, v5, v4 dst_sel:DWORD dst_unused:UNUSED_PAD src0_sel:DWORD src1_sel:WORD_1
	v_add_co_u32_e32 v4, vcc, s75, v34
	v_or_b32_sdwa v0, v8, v0 dst_sel:DWORD dst_unused:UNUSED_PAD src0_sel:DWORD src1_sel:WORD_1
	s_nop 0
	v_addc_co_u32_e32 v5, vcc, 0, v35, vcc
	global_store_dwordx4 v[4:5], v[0:3], off offset:2816
	s_waitcnt lgkmcnt(0)
	s_barrier
	global_load_dwordx2 v[0:1], v[32:33], off offset:456
	v_and_b32_e32 v8, 7, v135
	v_lshlrev_b64 v[2:3], 8, v[92:93]
	v_lshlrev_b64 v[4:5], 8, v[94:95]
	v_lshlrev_b64 v[6:7], 8, v[96:97]
	v_cmp_eq_u32_e64 s[4:5], 0, v8
	v_or_b32_e32 v2, v2, v126
	v_or_b32_e32 v4, v4, v126
	v_or_b32_e32 v6, v6, v126
	v_lshlrev_b64 v[92:93], 4, v[92:93]
	v_lshlrev_b64 v[94:95], 4, v[94:95]
	v_lshlrev_b64 v[96:97], 4, v[96:97]
	v_lshlrev_b64 v[104:105], 1, v[2:3]
	v_lshlrev_b64 v[106:107], 1, v[4:5]
	v_lshlrev_b64 v[108:109], 1, v[6:7]
	s_waitcnt vmcnt(0) lgkmcnt(0)
	v_readfirstlane_b32 s1, v1
	v_readfirstlane_b32 s0, v0
	s_nop 1
	v_lshl_add_u64 v[0:1], s[0:1], 0, v[64:65]
	global_load_dwordx4 v[30:33], v[0:1], off offset:1024
	global_load_dwordx4 v[34:37], v[0:1], off offset:1040
	s_add_u32 s0, s54, 0x2954198
	s_addc_u32 s1, s55, 0
	s_add_u32 s85, s54, 0x1748000
	v_lshlrev_b64 v[0:1], 8, v[90:91]
	s_addc_u32 s86, s55, 0
	v_bfe_u32 v64, v135, 1, 4
	v_or_b32_e32 v0, v0, v126
	s_add_u32 s6, s54, 0x29541a8
	v_lshl_add_u64 v[8:9], s[54:55], 0, v[64:65]
	v_lshlrev_b64 v[90:91], 4, v[90:91]
	s_addc_u32 s7, s55, 0
	v_lshl_add_u64 v[98:99], v[8:9], 0, s[52:53]
	v_lshlrev_b32_e32 v64, 2, v126
	s_waitcnt vmcnt(0) lgkmcnt(0)
	v_mov_b32_e32 v100, v30
	v_mov_b32_e32 v101, v32
	v_mov_b32_e32 v32, v31
	v_mov_b32_e32 v102, v34
	v_mov_b32_e32 v103, v36
	v_mov_b32_e32 v36, v35
	v_lshlrev_b64 v[34:35], 1, v[0:1]
	s_branch .LBB0_1409
